# peel first K iteration with SrcC=0 on first-touch MFMAs; delete per-unit accumulator zeroing
# baseline (speedup 1.0000x reference)
; #define PG8_STAGE(bufoff, soff, voff) do { _Pragma("unroll") for (int _i = 0; _i < 2; ++_i) \
;         __builtin_amdgcn_raw_ptr_buffer_load_lds(PG8_RS_##voff, (PG8_LAS void*)(lds + (bufoff) + ldsw + _i * 8192), 16, (voff)[_i], (soff), 0, 0); } while (0)
; #define PG8_LDA(dst, b, h) do { _Pragma("unroll") for (int m = 0; m < 4; ++m) _Pragma("unroll") for (int k = 0; k < 2; ++k) dst[m][k] = *(const PG8_LAS bf16x8*)(lds + PG8_SA(b, h) + aoff + m * 2048 + k * 1024); } while (0)
; #define PG8_LDB(dst, b, h) do { _Pragma("unroll") for (int n = 0; n < 2; ++n) _Pragma("unroll") for (int k = 0; k < 2; ++k) dst[n][k] = *(const PG8_LAS bf16x8*)(lds + PG8_SB(b, h) + boff + n * 2048 + k * 1024); } while (0)
; #define PG8_MMA(ai, bj, At, Bt) do { __builtin_amdgcn_s_setprio(1); _Pragma("unroll") for (int m = 0; m < 4; ++m) _Pragma("unroll") for (int n = 0; n < 2; ++n) _Pragma("unroll") for (int k = 0; k < 2; ++k) \
;         acc[ai][bj][m][n] = __builtin_amdgcn_mfma_f32_16x16x32_bf16(Bt[n][k], At[m][k], acc[ai][bj][m][n], 0, 0, 0); __builtin_amdgcn_s_setprio(0); } while (0)
; #define PG8_WAIT_V(n) asm volatile("s_waitcnt vmcnt(" #n ")" ::: "memory")
; #define PG8_WAIT_L(n) asm volatile("s_waitcnt lgkmcnt(" #n ")" ::: "memory")
; #define PG8_BAR __builtin_amdgcn_s_barrier()
; #define PG8_SCHED __builtin_amdgcn_sched_barrier(0)
; template <class Epi, class Sched, bool ALIGN_EPI = false, bool SP2 = false>
; __device__ __forceinline__ void gemm_phase(PG8_LAS unsigned char* lds, const Gemm g, const Sched& S, const Epi& E) {
;     ...
;             PG8_LDB(B0, 0, 0); PG8_LDB(B1, 0, 1); PG8_SCHED; PG8_LDA(At, 0, 0); PG8_STAGE(PG8_SA(1, 1), a1 + hstep, voffA);
;             PG8_WAIT_V(8); PG8_WAIT_L(0); PG8_BAR; PG8_MMA(0, 0, At, B0); PG8_MMA(0, 1, At, B1); PG8_BAR; PG8_SCHED;
;             PG8_LDA(At, 0, 1); PG8_STAGE(PG8_SB(0, 0), b2, voffB); PG8_STAGE(PG8_SB(0, 1), b2 + hstep, voffB); PG8_STAGE(PG8_SA(0, 0), a2, voffA);
;             PG8_WAIT_V(8); PG8_WAIT_L(0); PG8_BAR; PG8_MMA(1, 0, At, B0); PG8_MMA(1, 1, At, B1); PG8_BAR; PG8_SCHED;
.LBB0_376:
	s_lshl_b32 s50, s49, 20
	s_and_b64 s[0:1], s[40:41], exec
	s_cselect_b32 s0, s50, s5
	s_lshl_b32 s51, s48, 20
	s_and_b64 s[10:11], s[40:41], exec
	s_cselect_b32 s1, s51, s4
	s_add_i32 s5, s5, 0x80080
	s_addk_i32 s4, 0x100
	s_mov_b32 s54, -2
	v_add_u32_e32 v2, 0x10000, v192
	ds_read_b128 v[132:135], v2
	ds_read_b128 v[136:139], v2 offset:1024
	ds_read_b128 v[140:143], v2 offset:2048
	ds_read_b128 v[144:147], v2 offset:3072
	v_add_u32_e32 v2, 0x14000, v192
	ds_read_b128 v[194:197], v2
	ds_read_b128 v[208:211], v2 offset:1024
	ds_read_b128 v[212:215], v2 offset:2048
	ds_read_b128 v[218:221], v2 offset:3072
	s_add_i32 s10, s5, 0xfff80080
	s_cmp_eq_u32 s54, 28
	s_cselect_b32 s57, s0, s10
	s_cselect_b32 s56, s1, s4
	s_or_b32 s55, s57, 0x80
	s_mov_b32 m0, s44
	ds_read_b128 v[222:225], v193
	ds_read_b128 v[226:229], v193 offset:1024
	ds_read_b128 v[230:233], v193 offset:2048
	ds_read_b128 v[234:237], v193 offset:3072
	ds_read_b128 v[238:241], v193 offset:4096
	ds_read_b128 v[242:245], v193 offset:5120
	ds_read_b128 v[246:249], v193 offset:6144
	ds_read_b128 v[168:171], v193 offset:7168
	buffer_load_dwordx4 v151, s[28:31], s5 offen lds
	s_mov_b32 m0, s45
	s_nop 0
	buffer_load_dwordx4 v155, s[28:31], s5 offen lds
	s_waitcnt vmcnt(8)
	s_waitcnt lgkmcnt(0)
	s_barrier
	s_setprio 1
	s_waitcnt lgkmcnt(7)
	v_mfma_f32_16x16x32_bf16 v[128:131], v[132:135], v[222:225], 0
	v_mfma_f32_16x16x32_bf16 v[124:127], v[140:143], v[222:225], 0
	s_waitcnt lgkmcnt(5)
	v_mfma_f32_16x16x32_bf16 v[112:115], v[132:135], v[230:233], 0
	v_mfma_f32_16x16x32_bf16 v[108:111], v[140:143], v[230:233], 0
	s_waitcnt lgkmcnt(3)
	v_mfma_f32_16x16x32_bf16 v[96:99], v[132:135], v[238:241], 0
	v_mfma_f32_16x16x32_bf16 v[92:95], v[140:143], v[238:241], 0
	s_waitcnt lgkmcnt(1)
	v_mfma_f32_16x16x32_bf16 v[80:83], v[132:135], v[246:249], 0
	v_mfma_f32_16x16x32_bf16 v[76:79], v[140:143], v[246:249], 0
	v_mfma_f32_16x16x32_bf16 v[128:131], v[136:139], v[226:229], v[128:131]
	v_mfma_f32_16x16x32_bf16 v[124:127], v[144:147], v[226:229], v[124:127]
	v_mfma_f32_16x16x32_bf16 v[112:115], v[136:139], v[234:237], v[112:115]
	v_mfma_f32_16x16x32_bf16 v[108:111], v[144:147], v[234:237], v[108:111]
	v_mfma_f32_16x16x32_bf16 v[96:99], v[136:139], v[242:245], v[96:99]
	v_mfma_f32_16x16x32_bf16 v[92:95], v[144:147], v[242:245], v[92:95]
	s_waitcnt lgkmcnt(0)
	v_mfma_f32_16x16x32_bf16 v[80:83], v[136:139], v[168:171], v[80:83]
	v_mfma_f32_16x16x32_bf16 v[76:79], v[144:147], v[168:171], v[76:79]
	s_setprio 0
	s_setprio 1
	v_mfma_f32_16x16x32_bf16 v[120:123], v[194:197], v[222:225], 0
	v_mfma_f32_16x16x32_bf16 v[116:119], v[212:215], v[222:225], 0
	v_mfma_f32_16x16x32_bf16 v[104:107], v[194:197], v[230:233], 0
	v_mfma_f32_16x16x32_bf16 v[100:103], v[212:215], v[230:233], 0
	v_mfma_f32_16x16x32_bf16 v[88:91], v[194:197], v[238:241], 0
	v_mfma_f32_16x16x32_bf16 v[84:87], v[212:215], v[238:241], 0
	v_mfma_f32_16x16x32_bf16 v[72:75], v[194:197], v[246:249], 0
	v_mfma_f32_16x16x32_bf16 v[68:71], v[212:215], v[246:249], 0
	v_mfma_f32_16x16x32_bf16 v[120:123], v[208:211], v[226:229], v[120:123]
	v_mfma_f32_16x16x32_bf16 v[116:119], v[218:221], v[226:229], v[116:119]
	v_mfma_f32_16x16x32_bf16 v[104:107], v[208:211], v[234:237], v[104:107]
	v_mfma_f32_16x16x32_bf16 v[100:103], v[218:221], v[234:237], v[100:103]
	v_mfma_f32_16x16x32_bf16 v[88:91], v[208:211], v[242:245], v[88:91]
	v_mfma_f32_16x16x32_bf16 v[84:87], v[218:221], v[242:245], v[84:87]
	v_mfma_f32_16x16x32_bf16 v[72:75], v[208:211], v[168:171], v[72:75]
	v_mfma_f32_16x16x32_bf16 v[68:71], v[218:221], v[168:171], v[68:71]
	s_setprio 0
	s_barrier
	s_mov_b32 m0, s21
	s_mov_b32 s10, s30
	s_mov_b32 s11, s31
	ds_read_b128 v[168:171], v193 offset:16384
	ds_read_b128 v[222:225], v193 offset:17408
	ds_read_b128 v[226:229], v193 offset:18432
	ds_read_b128 v[230:233], v193 offset:19456
	ds_read_b128 v[234:237], v193 offset:20480
	ds_read_b128 v[238:241], v193 offset:21504
	ds_read_b128 v[242:245], v193 offset:22528
	ds_read_b128 v[246:249], v193 offset:23552
	buffer_load_dwordx4 v153, s[8:11], s56 offen lds
	s_mov_b32 m0, s22
	s_add_i32 s58, s56, 0x80000
	buffer_load_dwordx4 v157, s[8:11], s56 offen lds
	s_mov_b32 m0, s23
	s_nop 0
	buffer_load_dwordx4 v153, s[8:11], s58 offen lds
	s_mov_b32 m0, s24
	s_nop 0
	buffer_load_dwordx4 v157, s[8:11], s58 offen lds
	s_mov_b32 m0, s20
	s_nop 0
	buffer_load_dwordx4 v151, s[28:31], s57 offen lds
	s_mov_b32 m0, s25
	s_nop 0
	buffer_load_dwordx4 v155, s[28:31], s57 offen lds
	s_waitcnt vmcnt(8)
	s_waitcnt lgkmcnt(0)
	s_barrier
; #define PG8_STAGE(bufoff, soff, voff) do { _Pragma("unroll") for (int _i = 0; _i < 2; ++_i) \
;         __builtin_amdgcn_raw_ptr_buffer_load_lds(PG8_RS_##voff, (PG8_LAS void*)(lds + (bufoff) + ldsw + _i * 8192), 16, (voff)[_i], (soff), 0, 0); } while (0)
; #define PG8_LDA(dst, b, h) do { _Pragma("unroll") for (int m = 0; m < 4; ++m) _Pragma("unroll") for (int k = 0; k < 2; ++k) dst[m][k] = *(const PG8_LAS bf16x8*)(lds + PG8_SA(b, h) + aoff + m * 2048 + k * 1024); } while (0)
; #define PG8_LDB(dst, b, h) do { _Pragma("unroll") for (int n = 0; n < 2; ++n) _Pragma("unroll") for (int k = 0; k < 2; ++k) dst[n][k] = *(const PG8_LAS bf16x8*)(lds + PG8_SB(b, h) + boff + n * 2048 + k * 1024); } while (0)
; #define PG8_MMA(ai, bj, At, Bt) do { __builtin_amdgcn_s_setprio(1); _Pragma("unroll") for (int m = 0; m < 4; ++m) _Pragma("unroll") for (int n = 0; n < 2; ++n) _Pragma("unroll") for (int k = 0; k < 2; ++k) \
;         acc[ai][bj][m][n] = __builtin_amdgcn_mfma_f32_16x16x32_bf16(Bt[n][k], At[m][k], acc[ai][bj][m][n], 0, 0, 0); __builtin_amdgcn_s_setprio(0); } while (0)
; #define PG8_WAIT_V(n) asm volatile("s_waitcnt vmcnt(" #n ")" ::: "memory")
; #define PG8_WAIT_L(n) asm volatile("s_waitcnt lgkmcnt(" #n ")" ::: "memory")
; #define PG8_BAR __builtin_amdgcn_s_barrier()
; #define PG8_SCHED __builtin_amdgcn_sched_barrier(0)
; template <class Epi, class Sched, bool ALIGN_EPI = false, bool SP2 = false>
; __device__ __forceinline__ void gemm_phase(PG8_LAS unsigned char* lds, const Gemm g, const Sched& S, const Epi& E) {
;     ...
;             PG8_WAIT_V(8); PG8_WAIT_L(0); PG8_BAR; PG8_MMA(1, 0, At, B0); PG8_MMA(1, 1, At, B1); PG8_BAR; PG8_SCHED;
;             PG8_LDB(B0, 1, 0); PG8_LDB(B1, 1, 1); PG8_SCHED; PG8_LDA(At, 1, 0); PG8_STAGE(PG8_SA(0, 1), a2 + hstep, voffA);
;             PG8_WAIT_V(8); PG8_WAIT_L(0); PG8_BAR; PG8_MMA(0, 0, At, B0); PG8_MMA(0, 1, At, B1); PG8_BAR; PG8_SCHED;
	s_setprio 1
	s_waitcnt lgkmcnt(7)
	v_mfma_f32_16x16x32_bf16 v[64:67], v[132:135], v[168:171], 0
	v_mfma_f32_16x16x32_bf16 v[60:63], v[140:143], v[168:171], 0
	s_waitcnt lgkmcnt(5)
	v_mfma_f32_16x16x32_bf16 v[48:51], v[132:135], v[226:229], 0
	v_mfma_f32_16x16x32_bf16 v[44:47], v[140:143], v[226:229], 0
	s_waitcnt lgkmcnt(3)
	v_mfma_f32_16x16x32_bf16 v[32:35], v[132:135], v[234:237], 0
	v_mfma_f32_16x16x32_bf16 v[28:31], v[140:143], v[234:237], 0
	s_waitcnt lgkmcnt(1)
	v_mfma_f32_16x16x32_bf16 v[16:19], v[132:135], v[242:245], 0
	v_mfma_f32_16x16x32_bf16 v[12:15], v[140:143], v[242:245], 0
	v_mfma_f32_16x16x32_bf16 v[64:67], v[136:139], v[222:225], v[64:67]
	v_mfma_f32_16x16x32_bf16 v[60:63], v[144:147], v[222:225], v[60:63]
	v_mfma_f32_16x16x32_bf16 v[48:51], v[136:139], v[230:233], v[48:51]
	v_mfma_f32_16x16x32_bf16 v[44:47], v[144:147], v[230:233], v[44:47]
	v_mfma_f32_16x16x32_bf16 v[32:35], v[136:139], v[238:241], v[32:35]
	v_mfma_f32_16x16x32_bf16 v[28:31], v[144:147], v[238:241], v[28:31]
	s_waitcnt lgkmcnt(0)
	v_mfma_f32_16x16x32_bf16 v[16:19], v[136:139], v[246:249], v[16:19]
	v_mfma_f32_16x16x32_bf16 v[12:15], v[144:147], v[246:249], v[12:15]
	s_setprio 0
	s_setprio 1
	v_mfma_f32_16x16x32_bf16 v[56:59], v[194:197], v[168:171], 0
	v_mfma_f32_16x16x32_bf16 v[52:55], v[212:215], v[168:171], 0
	v_mfma_f32_16x16x32_bf16 v[40:43], v[194:197], v[226:229], 0
	v_mfma_f32_16x16x32_bf16 v[36:39], v[212:215], v[226:229], 0
	v_mfma_f32_16x16x32_bf16 v[24:27], v[194:197], v[234:237], 0
	v_mfma_f32_16x16x32_bf16 v[20:23], v[212:215], v[234:237], 0
	v_mfma_f32_16x16x32_bf16 v[8:11], v[194:197], v[242:245], 0
	v_mfma_f32_16x16x32_bf16 v[4:7], v[212:215], v[242:245], 0
	v_mfma_f32_16x16x32_bf16 v[56:59], v[208:211], v[222:225], v[56:59]
	v_mfma_f32_16x16x32_bf16 v[52:55], v[218:221], v[222:225], v[52:55]
	v_mfma_f32_16x16x32_bf16 v[40:43], v[208:211], v[230:233], v[40:43]
	v_mfma_f32_16x16x32_bf16 v[36:39], v[218:221], v[230:233], v[36:39]
	v_mfma_f32_16x16x32_bf16 v[24:27], v[208:211], v[238:241], v[24:27]
	v_mfma_f32_16x16x32_bf16 v[20:23], v[218:221], v[238:241], v[20:23]
	v_mfma_f32_16x16x32_bf16 v[8:11], v[208:211], v[246:249], v[8:11]
	v_mfma_f32_16x16x32_bf16 v[4:7], v[218:221], v[246:249], v[4:7]
	s_setprio 0
	s_barrier
	v_add_u32_e32 v2, 0x18000, v192
	ds_read_b128 v[132:135], v2
	ds_read_b128 v[136:139], v2 offset:1024
	ds_read_b128 v[140:143], v2 offset:2048
	ds_read_b128 v[144:147], v2 offset:3072
	v_add_u32_e32 v2, 0x1c000, v192
	ds_read_b128 v[168:171], v2
	ds_read_b128 v[194:197], v2 offset:1024
	ds_read_b128 v[208:211], v2 offset:2048
	ds_read_b128 v[212:215], v2 offset:3072
	s_add_i32 s57, s57, 0x80000
	s_mov_b32 m0, s26
	ds_read_b128 v[218:221], v193 offset:32768
	ds_read_b128 v[222:225], v193 offset:33792
	ds_read_b128 v[226:229], v193 offset:34816
	ds_read_b128 v[230:233], v193 offset:35840
	ds_read_b128 v[234:237], v193 offset:36864
	ds_read_b128 v[238:241], v193 offset:37888
	ds_read_b128 v[242:245], v193 offset:38912
	ds_read_b128 v[246:249], v193 offset:39936
	buffer_load_dwordx4 v151, s[28:31], s57 offen lds
	s_mov_b32 m0, s27
	s_nop 0
	buffer_load_dwordx4 v155, s[28:31], s57 offen lds
	s_waitcnt vmcnt(8)
	s_waitcnt lgkmcnt(0)
	s_barrier
	s_setprio 1
	s_waitcnt lgkmcnt(7)
	v_mfma_f32_16x16x32_bf16 v[128:131], v[132:135], v[218:221], v[128:131]
	v_mfma_f32_16x16x32_bf16 v[124:127], v[140:143], v[218:221], v[124:127]
	s_waitcnt lgkmcnt(5)
	v_mfma_f32_16x16x32_bf16 v[112:115], v[132:135], v[226:229], v[112:115]
	v_mfma_f32_16x16x32_bf16 v[108:111], v[140:143], v[226:229], v[108:111]
	s_waitcnt lgkmcnt(3)
	v_mfma_f32_16x16x32_bf16 v[96:99], v[132:135], v[234:237], v[96:99]
	v_mfma_f32_16x16x32_bf16 v[92:95], v[140:143], v[234:237], v[92:95]
	s_waitcnt lgkmcnt(1)
	v_mfma_f32_16x16x32_bf16 v[80:83], v[132:135], v[242:245], v[80:83]
	v_mfma_f32_16x16x32_bf16 v[76:79], v[140:143], v[242:245], v[76:79]
	v_mfma_f32_16x16x32_bf16 v[128:131], v[136:139], v[222:225], v[128:131]
	v_mfma_f32_16x16x32_bf16 v[124:127], v[144:147], v[222:225], v[124:127]
	v_mfma_f32_16x16x32_bf16 v[112:115], v[136:139], v[230:233], v[112:115]
	v_mfma_f32_16x16x32_bf16 v[108:111], v[144:147], v[230:233], v[108:111]
	v_mfma_f32_16x16x32_bf16 v[96:99], v[136:139], v[238:241], v[96:99]
	v_mfma_f32_16x16x32_bf16 v[92:95], v[144:147], v[238:241], v[92:95]
	s_waitcnt lgkmcnt(0)
	v_mfma_f32_16x16x32_bf16 v[80:83], v[136:139], v[246:249], v[80:83]
	v_mfma_f32_16x16x32_bf16 v[76:79], v[144:147], v[246:249], v[76:79]
	s_setprio 0
	s_setprio 1
	v_mfma_f32_16x16x32_bf16 v[120:123], v[168:171], v[218:221], v[120:123]
	v_mfma_f32_16x16x32_bf16 v[116:119], v[208:211], v[218:221], v[116:119]
	v_mfma_f32_16x16x32_bf16 v[104:107], v[168:171], v[226:229], v[104:107]
	v_mfma_f32_16x16x32_bf16 v[100:103], v[208:211], v[226:229], v[100:103]
	v_mfma_f32_16x16x32_bf16 v[88:91], v[168:171], v[234:237], v[88:91]
	v_mfma_f32_16x16x32_bf16 v[84:87], v[208:211], v[234:237], v[84:87]
	v_mfma_f32_16x16x32_bf16 v[72:75], v[168:171], v[242:245], v[72:75]
	v_mfma_f32_16x16x32_bf16 v[68:71], v[208:211], v[242:245], v[68:71]
	v_mfma_f32_16x16x32_bf16 v[120:123], v[194:197], v[222:225], v[120:123]
	v_mfma_f32_16x16x32_bf16 v[116:119], v[212:215], v[222:225], v[116:119]
	v_mfma_f32_16x16x32_bf16 v[104:107], v[194:197], v[230:233], v[104:107]
	v_mfma_f32_16x16x32_bf16 v[100:103], v[212:215], v[230:233], v[100:103]
	v_mfma_f32_16x16x32_bf16 v[88:91], v[194:197], v[238:241], v[88:91]
	v_mfma_f32_16x16x32_bf16 v[84:87], v[212:215], v[238:241], v[84:87]
	v_mfma_f32_16x16x32_bf16 v[72:75], v[194:197], v[246:249], v[72:75]
	v_mfma_f32_16x16x32_bf16 v[68:71], v[212:215], v[246:249], v[68:71]
	s_setprio 0
	s_barrier
; #define PG8_STAGE(bufoff, soff, voff) do { _Pragma("unroll") for (int _i = 0; _i < 2; ++_i) \
;         __builtin_amdgcn_raw_ptr_buffer_load_lds(PG8_RS_##voff, (PG8_LAS void*)(lds + (bufoff) + ldsw + _i * 8192), 16, (voff)[_i], (soff), 0, 0); } while (0)
; #define PG8_LDA(dst, b, h) do { _Pragma("unroll") for (int m = 0; m < 4; ++m) _Pragma("unroll") for (int k = 0; k < 2; ++k) dst[m][k] = *(const PG8_LAS bf16x8*)(lds + PG8_SA(b, h) + aoff + m * 2048 + k * 1024); } while (0)
; #define PG8_MMA(ai, bj, At, Bt) do { __builtin_amdgcn_s_setprio(1); _Pragma("unroll") for (int m = 0; m < 4; ++m) _Pragma("unroll") for (int n = 0; n < 2; ++n) _Pragma("unroll") for (int k = 0; k < 2; ++k) \
;         acc[ai][bj][m][n] = __builtin_amdgcn_mfma_f32_16x16x32_bf16(Bt[n][k], At[m][k], acc[ai][bj][m][n], 0, 0, 0); __builtin_amdgcn_s_setprio(0); } while (0)
; #define PG8_WAIT_V(n) asm volatile("s_waitcnt vmcnt(" #n ")" ::: "memory")
; #define PG8_WAIT_L(n) asm volatile("s_waitcnt lgkmcnt(" #n ")" ::: "memory")
; #define PG8_BAR __builtin_amdgcn_s_barrier()
; #define PG8_SCHED __builtin_amdgcn_sched_barrier(0)
; template <class Epi, class Sched, bool ALIGN_EPI = false, bool SP2 = false>
; __device__ __forceinline__ void gemm_phase(PG8_LAS unsigned char* lds, const Gemm g, const Sched& S, const Epi& E) {
;     ...
;             PG8_LDA(At, 1, 1); PG8_STAGE(PG8_SB(1, 0), b3, voffB); PG8_STAGE(PG8_SB(1, 1), b3 + hstep, voffB); PG8_STAGE(PG8_SA(1, 0), a3, voffA);
;             PG8_WAIT_V(8); PG8_WAIT_L(0); PG8_BAR; PG8_MMA(1, 0, At, B0); PG8_MMA(1, 1, At, B1); PG8_BAR; PG8_SCHED;
	s_mov_b32 m0, s34
	s_or_b32 s57, s56, 0x80
	ds_read_b128 v[218:221], v193 offset:49152
	ds_read_b128 v[222:225], v193 offset:50176
	ds_read_b128 v[226:229], v193 offset:51200
	ds_read_b128 v[230:233], v193 offset:52224
	ds_read_b128 v[234:237], v193 offset:53248
	ds_read_b128 v[238:241], v193 offset:54272
	ds_read_b128 v[242:245], v193 offset:55296
	ds_read_b128 v[246:249], v193 offset:56320
	buffer_load_dwordx4 v153, s[8:11], s57 offen lds
	s_mov_b32 m0, s35
	s_add_i32 s56, s56, 0x80080
	buffer_load_dwordx4 v157, s[8:11], s57 offen lds
	s_mov_b32 m0, s42
	s_nop 0
	buffer_load_dwordx4 v153, s[8:11], s56 offen lds
	s_mov_b32 m0, s43
	s_nop 0
	buffer_load_dwordx4 v157, s[8:11], s56 offen lds
	s_mov_b32 m0, s36
	s_nop 0
	buffer_load_dwordx4 v151, s[28:31], s55 offen lds
	s_mov_b32 m0, s37
	s_nop 0
	buffer_load_dwordx4 v155, s[28:31], s55 offen lds
	s_waitcnt vmcnt(8)
	s_waitcnt lgkmcnt(0)
	s_barrier
	s_setprio 1
	s_waitcnt lgkmcnt(7)
	v_mfma_f32_16x16x32_bf16 v[64:67], v[132:135], v[218:221], v[64:67]
	v_mfma_f32_16x16x32_bf16 v[60:63], v[140:143], v[218:221], v[60:63]
	s_waitcnt lgkmcnt(5)
	v_mfma_f32_16x16x32_bf16 v[48:51], v[132:135], v[226:229], v[48:51]
	v_mfma_f32_16x16x32_bf16 v[44:47], v[140:143], v[226:229], v[44:47]
	s_waitcnt lgkmcnt(3)
	v_mfma_f32_16x16x32_bf16 v[32:35], v[132:135], v[234:237], v[32:35]
	v_mfma_f32_16x16x32_bf16 v[28:31], v[140:143], v[234:237], v[28:31]
	s_waitcnt lgkmcnt(1)
	v_mfma_f32_16x16x32_bf16 v[16:19], v[132:135], v[242:245], v[16:19]
	v_mfma_f32_16x16x32_bf16 v[12:15], v[140:143], v[242:245], v[12:15]
	v_mfma_f32_16x16x32_bf16 v[64:67], v[136:139], v[222:225], v[64:67]
	v_mfma_f32_16x16x32_bf16 v[60:63], v[144:147], v[222:225], v[60:63]
	v_mfma_f32_16x16x32_bf16 v[48:51], v[136:139], v[230:233], v[48:51]
	v_mfma_f32_16x16x32_bf16 v[44:47], v[144:147], v[230:233], v[44:47]
	v_mfma_f32_16x16x32_bf16 v[32:35], v[136:139], v[238:241], v[32:35]
	v_mfma_f32_16x16x32_bf16 v[28:31], v[144:147], v[238:241], v[28:31]
	s_waitcnt lgkmcnt(0)
	v_mfma_f32_16x16x32_bf16 v[16:19], v[136:139], v[246:249], v[16:19]
	v_mfma_f32_16x16x32_bf16 v[12:15], v[144:147], v[246:249], v[12:15]
	s_setprio 0
	s_setprio 1
	v_mfma_f32_16x16x32_bf16 v[56:59], v[168:171], v[218:221], v[56:59]
	v_mfma_f32_16x16x32_bf16 v[52:55], v[208:211], v[218:221], v[52:55]
	v_mfma_f32_16x16x32_bf16 v[40:43], v[168:171], v[226:229], v[40:43]
	v_mfma_f32_16x16x32_bf16 v[36:39], v[208:211], v[226:229], v[36:39]
	v_mfma_f32_16x16x32_bf16 v[24:27], v[168:171], v[234:237], v[24:27]
	v_mfma_f32_16x16x32_bf16 v[20:23], v[208:211], v[234:237], v[20:23]
	v_mfma_f32_16x16x32_bf16 v[8:11], v[168:171], v[242:245], v[8:11]
	v_mfma_f32_16x16x32_bf16 v[4:7], v[208:211], v[242:245], v[4:7]
	v_mfma_f32_16x16x32_bf16 v[56:59], v[194:197], v[222:225], v[56:59]
	v_mfma_f32_16x16x32_bf16 v[52:55], v[212:215], v[222:225], v[52:55]
	v_mfma_f32_16x16x32_bf16 v[40:43], v[194:197], v[230:233], v[40:43]
	v_mfma_f32_16x16x32_bf16 v[36:39], v[212:215], v[230:233], v[36:39]
	v_mfma_f32_16x16x32_bf16 v[24:27], v[194:197], v[238:241], v[24:27]
	v_mfma_f32_16x16x32_bf16 v[20:23], v[212:215], v[238:241], v[20:23]
	v_mfma_f32_16x16x32_bf16 v[8:11], v[194:197], v[246:249], v[8:11]
	v_mfma_f32_16x16x32_bf16 v[4:7], v[212:215], v[246:249], v[4:7]
	s_setprio 0
	s_barrier
	s_add_i32 s54, s54, 2
	s_addk_i32 s5, 0x100
	s_addk_i32 s4, 0x100
	s_cmp_gt_u32 s54, 29

; template <class Epi, class Sched, bool ALIGN_EPI = false, bool SP2 = false>
; __device__ __forceinline__ void gemm_phase(PG8_LAS unsigned char* lds, const Gemm g, const Sched& S, const Epi& E) {
;     ...
;         if constexpr (!Epi::AFTER_DRAIN) { E(acc, cur, wr, wc, fr, fq); S.done(cur); }
;         if (!has_next) break;
; #pragma unroll
;         for (int a = 0; a < 2; ++a)
; #pragma unroll
;             for (int b = 0; b < 2; ++b)
; #pragma unroll
;                 for (int m = 0; m < 4; ++m)
; #pragma unroll
;                     for (int n = 0; n < 2; ++n) { typedef double d2_t __attribute__((ext_vector_type(2))); d2_t z; double z0, z1;
;                         asm volatile("v_mov_b64 %0, 0" : "=v"(z0)); asm volatile("v_mov_b64 %0, 0" : "=v"(z1)); z.x = z0; z.y = z1; acc[a][b][m][n] = __builtin_bit_cast(f32x4, z); }
;         cur = nxt; cA = nA; cB = nB; ++ui;
.LBB0_452:
	s_andn2_b64 vcc, exec, s[40:41]
	s_mov_b64 s[0:1], -1
	global_store_dwordx4 v[144:145], v[132:135], off offset:256
	s_cbranch_vccnz .LBB0_373
	s_andn2_b64 vcc, exec, s[2:3]
	s_cbranch_vccnz .LBB0_372
	s_barrier
	s_branch .LBB0_372

; #define PG8_STAGE(bufoff, soff, voff) do { _Pragma("unroll") for (int _i = 0; _i < 2; ++_i) \
;         __builtin_amdgcn_raw_ptr_buffer_load_lds(PG8_RS_##voff, (PG8_LAS void*)(lds + (bufoff) + ldsw + _i * 8192), 16, (voff)[_i], (soff), 0, 0); } while (0)
; #define PG8_LDA(dst, b, h) do { _Pragma("unroll") for (int m = 0; m < 4; ++m) _Pragma("unroll") for (int k = 0; k < 2; ++k) dst[m][k] = *(const PG8_LAS bf16x8*)(lds + PG8_SA(b, h) + aoff + m * 2048 + k * 1024); } while (0)
; #define PG8_LDB(dst, b, h) do { _Pragma("unroll") for (int n = 0; n < 2; ++n) _Pragma("unroll") for (int k = 0; k < 2; ++k) dst[n][k] = *(const PG8_LAS bf16x8*)(lds + PG8_SB(b, h) + boff + n * 2048 + k * 1024); } while (0)
; #define PG8_MMA(ai, bj, At, Bt) do { __builtin_amdgcn_s_setprio(1); _Pragma("unroll") for (int m = 0; m < 4; ++m) _Pragma("unroll") for (int n = 0; n < 2; ++n) _Pragma("unroll") for (int k = 0; k < 2; ++k) \
;         acc[ai][bj][m][n] = __builtin_amdgcn_mfma_f32_16x16x32_bf16(Bt[n][k], At[m][k], acc[ai][bj][m][n], 0, 0, 0); __builtin_amdgcn_s_setprio(0); } while (0)
; #define PG8_WAIT_V(n) asm volatile("s_waitcnt vmcnt(" #n ")" ::: "memory")
; #define PG8_WAIT_L(n) asm volatile("s_waitcnt lgkmcnt(" #n ")" ::: "memory")
; #define PG8_BAR __builtin_amdgcn_s_barrier()
; #define PG8_SCHED __builtin_amdgcn_sched_barrier(0)
; template <class Epi, class Sched, bool ALIGN_EPI = false, bool SP2 = false>
; __device__ __forceinline__ void gemm_phase(PG8_LAS unsigned char* lds, const Gemm g, const Sched& S, const Epi& E) {
;     ...
;             PG8_LDB(B0, 0, 0); PG8_LDB(B1, 0, 1); PG8_SCHED; PG8_LDA(At, 0, 0); PG8_STAGE(PG8_SA(1, 1), a1 + hstep, voffA);
;             PG8_WAIT_V(8); PG8_WAIT_L(0); PG8_BAR; PG8_MMA(0, 0, At, B0); PG8_MMA(0, 1, At, B1); PG8_BAR; PG8_SCHED;
;             PG8_LDA(At, 0, 1); PG8_STAGE(PG8_SB(0, 0), b2, voffB); PG8_STAGE(PG8_SB(0, 1), b2 + hstep, voffB); PG8_STAGE(PG8_SA(0, 0), a2, voffA);
;             PG8_WAIT_V(8); PG8_WAIT_L(0); PG8_BAR; PG8_MMA(1, 0, At, B0); PG8_MMA(1, 1, At, B1); PG8_BAR; PG8_SCHED;
.LBB0_526:
	s_lshl_b32 s42, s41, 20
	s_and_b64 s[0:1], s[38:39], exec
	s_cselect_b32 s0, s42, s7
	s_lshl_b32 s43, s40, 20
	s_and_b64 s[46:47], s[38:39], exec
	s_cselect_b32 s1, s43, s6
	s_add_i32 s46, s7, 0x80080
	s_add_i32 s47, s6, 0x100
	s_mov_b32 s48, -2
	v_add_u32_e32 v144, 0x10000, v187
	v_add_u32_e32 v168, 0x14000, v187
	ds_read_b128 v[132:135], v144
	ds_read_b128 v[136:139], v144 offset:1024
	ds_read_b128 v[140:143], v144 offset:2048
	ds_read_b128 v[144:147], v144 offset:3072
	ds_read_b128 v[148:151], v168
	ds_read_b128 v[152:155], v168 offset:1024
	ds_read_b128 v[156:159], v168 offset:2048
	ds_read_b128 v[168:171], v168 offset:3072
	s_add_i32 s6, s46, 0xfff80080
	s_cmp_eq_u32 s48, 28
	s_cselect_b32 s51, s0, s6
	s_cselect_b32 s50, s1, s47
	s_or_b32 s49, s51, 0x80
	s_mov_b32 m0, s35
	ds_read_b128 v[172:175], v188
	ds_read_b128 v[176:179], v188 offset:1024
	ds_read_b128 v[190:193], v188 offset:2048
	ds_read_b128 v[194:197], v188 offset:3072
	ds_read_b128 v[208:211], v188 offset:4096
	ds_read_b128 v[212:215], v188 offset:5120
	ds_read_b128 v[218:221], v188 offset:6144
	ds_read_b128 v[222:225], v188 offset:7168
	buffer_load_dwordx4 v2, s[28:31], s46 offen lds
	s_mov_b32 m0, s36
	s_nop 0
	buffer_load_dwordx4 v181, s[28:31], s46 offen lds
	s_waitcnt vmcnt(8)
	s_waitcnt lgkmcnt(0)
	s_barrier
	s_setprio 1
	s_waitcnt lgkmcnt(7)
	v_mfma_f32_16x16x32_bf16 v[128:131], v[132:135], v[172:175], 0
	v_mfma_f32_16x16x32_bf16 v[124:127], v[140:143], v[172:175], 0
	s_waitcnt lgkmcnt(5)
	v_mfma_f32_16x16x32_bf16 v[112:115], v[132:135], v[190:193], 0
	v_mfma_f32_16x16x32_bf16 v[108:111], v[140:143], v[190:193], 0
	s_waitcnt lgkmcnt(3)
	v_mfma_f32_16x16x32_bf16 v[96:99], v[132:135], v[208:211], 0
	v_mfma_f32_16x16x32_bf16 v[92:95], v[140:143], v[208:211], 0
	s_waitcnt lgkmcnt(1)
	v_mfma_f32_16x16x32_bf16 v[80:83], v[132:135], v[218:221], 0
	v_mfma_f32_16x16x32_bf16 v[76:79], v[140:143], v[218:221], 0
	v_mfma_f32_16x16x32_bf16 v[128:131], v[136:139], v[176:179], v[128:131]
	v_mfma_f32_16x16x32_bf16 v[124:127], v[144:147], v[176:179], v[124:127]
	v_mfma_f32_16x16x32_bf16 v[112:115], v[136:139], v[194:197], v[112:115]
	v_mfma_f32_16x16x32_bf16 v[108:111], v[144:147], v[194:197], v[108:111]
	v_mfma_f32_16x16x32_bf16 v[96:99], v[136:139], v[212:215], v[96:99]
	v_mfma_f32_16x16x32_bf16 v[92:95], v[144:147], v[212:215], v[92:95]
	s_waitcnt lgkmcnt(0)
	v_mfma_f32_16x16x32_bf16 v[80:83], v[136:139], v[222:225], v[80:83]
	v_mfma_f32_16x16x32_bf16 v[76:79], v[144:147], v[222:225], v[76:79]
	s_setprio 0
	s_setprio 1
	v_mfma_f32_16x16x32_bf16 v[120:123], v[148:151], v[172:175], 0
	v_mfma_f32_16x16x32_bf16 v[116:119], v[156:159], v[172:175], 0
	v_mfma_f32_16x16x32_bf16 v[104:107], v[148:151], v[190:193], 0
	v_mfma_f32_16x16x32_bf16 v[100:103], v[156:159], v[190:193], 0
	v_mfma_f32_16x16x32_bf16 v[88:91], v[148:151], v[208:211], 0
	v_mfma_f32_16x16x32_bf16 v[84:87], v[156:159], v[208:211], 0
	v_mfma_f32_16x16x32_bf16 v[72:75], v[148:151], v[218:221], 0
	v_mfma_f32_16x16x32_bf16 v[68:71], v[156:159], v[218:221], 0
	v_mfma_f32_16x16x32_bf16 v[120:123], v[152:155], v[176:179], v[120:123]
	v_mfma_f32_16x16x32_bf16 v[116:119], v[168:171], v[176:179], v[116:119]
	v_mfma_f32_16x16x32_bf16 v[104:107], v[152:155], v[194:197], v[104:107]
	v_mfma_f32_16x16x32_bf16 v[100:103], v[168:171], v[194:197], v[100:103]
	v_mfma_f32_16x16x32_bf16 v[88:91], v[152:155], v[212:215], v[88:91]
	v_mfma_f32_16x16x32_bf16 v[84:87], v[168:171], v[212:215], v[84:87]
	v_mfma_f32_16x16x32_bf16 v[72:75], v[152:155], v[222:225], v[72:75]
	v_mfma_f32_16x16x32_bf16 v[68:71], v[168:171], v[222:225], v[68:71]
	s_setprio 0
	s_barrier
	s_mov_b32 m0, s15
	s_mov_b32 s6, s30
	s_mov_b32 s7, s31
	ds_read_b128 v[172:175], v188 offset:16384
	ds_read_b128 v[176:179], v188 offset:17408
	ds_read_b128 v[190:193], v188 offset:18432
	ds_read_b128 v[194:197], v188 offset:19456
	ds_read_b128 v[208:211], v188 offset:20480
	ds_read_b128 v[212:215], v188 offset:21504
	ds_read_b128 v[218:221], v188 offset:22528
	ds_read_b128 v[222:225], v188 offset:23552
	buffer_load_dwordx4 v180, s[4:7], s50 offen lds
	s_mov_b32 m0, s16
	s_add_i32 s52, s50, 0x80000
	buffer_load_dwordx4 v182, s[4:7], s50 offen lds
	s_mov_b32 m0, s17
	s_nop 0
	buffer_load_dwordx4 v180, s[4:7], s52 offen lds
	s_mov_b32 m0, s18
	s_nop 0
	buffer_load_dwordx4 v182, s[4:7], s52 offen lds
	s_mov_b32 m0, s14
	s_nop 0
	buffer_load_dwordx4 v2, s[28:31], s51 offen lds
	s_mov_b32 m0, s19
	s_nop 0
	buffer_load_dwordx4 v181, s[28:31], s51 offen lds
	s_waitcnt vmcnt(8)
	s_waitcnt lgkmcnt(0)
	s_barrier
; #define PG8_STAGE(bufoff, soff, voff) do { _Pragma("unroll") for (int _i = 0; _i < 2; ++_i) \
;         __builtin_amdgcn_raw_ptr_buffer_load_lds(PG8_RS_##voff, (PG8_LAS void*)(lds + (bufoff) + ldsw + _i * 8192), 16, (voff)[_i], (soff), 0, 0); } while (0)
; #define PG8_LDA(dst, b, h) do { _Pragma("unroll") for (int m = 0; m < 4; ++m) _Pragma("unroll") for (int k = 0; k < 2; ++k) dst[m][k] = *(const PG8_LAS bf16x8*)(lds + PG8_SA(b, h) + aoff + m * 2048 + k * 1024); } while (0)
; #define PG8_LDB(dst, b, h) do { _Pragma("unroll") for (int n = 0; n < 2; ++n) _Pragma("unroll") for (int k = 0; k < 2; ++k) dst[n][k] = *(const PG8_LAS bf16x8*)(lds + PG8_SB(b, h) + boff + n * 2048 + k * 1024); } while (0)
; #define PG8_MMA(ai, bj, At, Bt) do { __builtin_amdgcn_s_setprio(1); _Pragma("unroll") for (int m = 0; m < 4; ++m) _Pragma("unroll") for (int n = 0; n < 2; ++n) _Pragma("unroll") for (int k = 0; k < 2; ++k) \
;         acc[ai][bj][m][n] = __builtin_amdgcn_mfma_f32_16x16x32_bf16(Bt[n][k], At[m][k], acc[ai][bj][m][n], 0, 0, 0); __builtin_amdgcn_s_setprio(0); } while (0)
; #define PG8_WAIT_V(n) asm volatile("s_waitcnt vmcnt(" #n ")" ::: "memory")
; #define PG8_WAIT_L(n) asm volatile("s_waitcnt lgkmcnt(" #n ")" ::: "memory")
; #define PG8_BAR __builtin_amdgcn_s_barrier()
; #define PG8_SCHED __builtin_amdgcn_sched_barrier(0)
; template <class Epi, class Sched, bool ALIGN_EPI = false, bool SP2 = false>
; __device__ __forceinline__ void gemm_phase(PG8_LAS unsigned char* lds, const Gemm g, const Sched& S, const Epi& E) {
;     ...
;             PG8_WAIT_V(8); PG8_WAIT_L(0); PG8_BAR; PG8_MMA(1, 0, At, B0); PG8_MMA(1, 1, At, B1); PG8_BAR; PG8_SCHED;
;             PG8_LDB(B0, 1, 0); PG8_LDB(B1, 1, 1); PG8_SCHED; PG8_LDA(At, 1, 0); PG8_STAGE(PG8_SA(0, 1), a2 + hstep, voffA);
;             PG8_WAIT_V(8); PG8_WAIT_L(0); PG8_BAR; PG8_MMA(0, 0, At, B0); PG8_MMA(0, 1, At, B1); PG8_BAR; PG8_SCHED;
	s_setprio 1
	s_waitcnt lgkmcnt(7)
	v_mfma_f32_16x16x32_bf16 v[64:67], v[132:135], v[172:175], 0
	v_mfma_f32_16x16x32_bf16 v[60:63], v[140:143], v[172:175], 0
	s_waitcnt lgkmcnt(5)
	v_mfma_f32_16x16x32_bf16 v[48:51], v[132:135], v[190:193], 0
	v_mfma_f32_16x16x32_bf16 v[44:47], v[140:143], v[190:193], 0
	s_waitcnt lgkmcnt(3)
	v_mfma_f32_16x16x32_bf16 v[32:35], v[132:135], v[208:211], 0
	v_mfma_f32_16x16x32_bf16 v[28:31], v[140:143], v[208:211], 0
	s_waitcnt lgkmcnt(1)
	v_mfma_f32_16x16x32_bf16 v[16:19], v[132:135], v[218:221], 0
	v_mfma_f32_16x16x32_bf16 v[12:15], v[140:143], v[218:221], 0
	v_mfma_f32_16x16x32_bf16 v[64:67], v[136:139], v[176:179], v[64:67]
	v_mfma_f32_16x16x32_bf16 v[60:63], v[144:147], v[176:179], v[60:63]
	v_mfma_f32_16x16x32_bf16 v[48:51], v[136:139], v[194:197], v[48:51]
	v_mfma_f32_16x16x32_bf16 v[44:47], v[144:147], v[194:197], v[44:47]
	v_mfma_f32_16x16x32_bf16 v[32:35], v[136:139], v[212:215], v[32:35]
	v_mfma_f32_16x16x32_bf16 v[28:31], v[144:147], v[212:215], v[28:31]
	s_waitcnt lgkmcnt(0)
	v_mfma_f32_16x16x32_bf16 v[16:19], v[136:139], v[222:225], v[16:19]
	v_mfma_f32_16x16x32_bf16 v[12:15], v[144:147], v[222:225], v[12:15]
	s_setprio 0
	s_setprio 1
	v_mfma_f32_16x16x32_bf16 v[56:59], v[148:151], v[172:175], 0
	v_mfma_f32_16x16x32_bf16 v[52:55], v[156:159], v[172:175], 0
	v_mfma_f32_16x16x32_bf16 v[40:43], v[148:151], v[190:193], 0
	v_mfma_f32_16x16x32_bf16 v[36:39], v[156:159], v[190:193], 0
	v_mfma_f32_16x16x32_bf16 v[24:27], v[148:151], v[208:211], 0
	v_mfma_f32_16x16x32_bf16 v[20:23], v[156:159], v[208:211], 0
	v_mfma_f32_16x16x32_bf16 v[8:11], v[148:151], v[218:221], 0
	v_mfma_f32_16x16x32_bf16 v[4:7], v[156:159], v[218:221], 0
	v_mfma_f32_16x16x32_bf16 v[56:59], v[152:155], v[176:179], v[56:59]
	v_mfma_f32_16x16x32_bf16 v[52:55], v[168:171], v[176:179], v[52:55]
	v_mfma_f32_16x16x32_bf16 v[40:43], v[152:155], v[194:197], v[40:43]
	v_mfma_f32_16x16x32_bf16 v[36:39], v[168:171], v[194:197], v[36:39]
	v_mfma_f32_16x16x32_bf16 v[24:27], v[152:155], v[212:215], v[24:27]
	v_mfma_f32_16x16x32_bf16 v[20:23], v[168:171], v[212:215], v[20:23]
	v_mfma_f32_16x16x32_bf16 v[8:11], v[152:155], v[222:225], v[8:11]
	v_mfma_f32_16x16x32_bf16 v[4:7], v[168:171], v[222:225], v[4:7]
	s_setprio 0
	s_barrier
	v_add_u32_e32 v144, 0x18000, v187
	v_add_u32_e32 v168, 0x1c000, v187
	ds_read_b128 v[132:135], v144
	ds_read_b128 v[136:139], v144 offset:1024
	ds_read_b128 v[140:143], v144 offset:2048
	ds_read_b128 v[144:147], v144 offset:3072
	ds_read_b128 v[148:151], v168
	ds_read_b128 v[152:155], v168 offset:1024
	ds_read_b128 v[156:159], v168 offset:2048
	ds_read_b128 v[168:171], v168 offset:3072
	s_add_i32 s51, s51, 0x80000
	s_mov_b32 m0, s21
	ds_read_b128 v[172:175], v188 offset:32768
	ds_read_b128 v[176:179], v188 offset:33792
	ds_read_b128 v[190:193], v188 offset:34816
	ds_read_b128 v[194:197], v188 offset:35840
	ds_read_b128 v[208:211], v188 offset:36864
	ds_read_b128 v[212:215], v188 offset:37888
	ds_read_b128 v[218:221], v188 offset:38912
	ds_read_b128 v[222:225], v188 offset:39936
	buffer_load_dwordx4 v2, s[28:31], s51 offen lds
	s_mov_b32 m0, s22
	s_nop 0
	buffer_load_dwordx4 v181, s[28:31], s51 offen lds
	s_waitcnt vmcnt(8)
	s_waitcnt lgkmcnt(0)
	s_barrier
	s_setprio 1
	s_waitcnt lgkmcnt(7)
	v_mfma_f32_16x16x32_bf16 v[128:131], v[132:135], v[172:175], v[128:131]
	v_mfma_f32_16x16x32_bf16 v[124:127], v[140:143], v[172:175], v[124:127]
	s_waitcnt lgkmcnt(5)
	v_mfma_f32_16x16x32_bf16 v[112:115], v[132:135], v[190:193], v[112:115]
	v_mfma_f32_16x16x32_bf16 v[108:111], v[140:143], v[190:193], v[108:111]
	s_waitcnt lgkmcnt(3)
	v_mfma_f32_16x16x32_bf16 v[96:99], v[132:135], v[208:211], v[96:99]
	v_mfma_f32_16x16x32_bf16 v[92:95], v[140:143], v[208:211], v[92:95]
	s_waitcnt lgkmcnt(1)
	v_mfma_f32_16x16x32_bf16 v[80:83], v[132:135], v[218:221], v[80:83]
	v_mfma_f32_16x16x32_bf16 v[76:79], v[140:143], v[218:221], v[76:79]
	v_mfma_f32_16x16x32_bf16 v[128:131], v[136:139], v[176:179], v[128:131]
	v_mfma_f32_16x16x32_bf16 v[124:127], v[144:147], v[176:179], v[124:127]
	v_mfma_f32_16x16x32_bf16 v[112:115], v[136:139], v[194:197], v[112:115]
	v_mfma_f32_16x16x32_bf16 v[108:111], v[144:147], v[194:197], v[108:111]
	v_mfma_f32_16x16x32_bf16 v[96:99], v[136:139], v[212:215], v[96:99]
	v_mfma_f32_16x16x32_bf16 v[92:95], v[144:147], v[212:215], v[92:95]
	s_waitcnt lgkmcnt(0)
	v_mfma_f32_16x16x32_bf16 v[80:83], v[136:139], v[222:225], v[80:83]
	v_mfma_f32_16x16x32_bf16 v[76:79], v[144:147], v[222:225], v[76:79]
	s_setprio 0
	s_setprio 1
	v_mfma_f32_16x16x32_bf16 v[120:123], v[148:151], v[172:175], v[120:123]
	v_mfma_f32_16x16x32_bf16 v[116:119], v[156:159], v[172:175], v[116:119]
	v_mfma_f32_16x16x32_bf16 v[104:107], v[148:151], v[190:193], v[104:107]
	v_mfma_f32_16x16x32_bf16 v[100:103], v[156:159], v[190:193], v[100:103]
	v_mfma_f32_16x16x32_bf16 v[88:91], v[148:151], v[208:211], v[88:91]
	v_mfma_f32_16x16x32_bf16 v[84:87], v[156:159], v[208:211], v[84:87]
	v_mfma_f32_16x16x32_bf16 v[72:75], v[148:151], v[218:221], v[72:75]
	v_mfma_f32_16x16x32_bf16 v[68:71], v[156:159], v[218:221], v[68:71]
	v_mfma_f32_16x16x32_bf16 v[120:123], v[152:155], v[176:179], v[120:123]
	v_mfma_f32_16x16x32_bf16 v[116:119], v[168:171], v[176:179], v[116:119]
	v_mfma_f32_16x16x32_bf16 v[104:107], v[152:155], v[194:197], v[104:107]
	v_mfma_f32_16x16x32_bf16 v[100:103], v[168:171], v[194:197], v[100:103]
	v_mfma_f32_16x16x32_bf16 v[88:91], v[152:155], v[212:215], v[88:91]
	v_mfma_f32_16x16x32_bf16 v[84:87], v[168:171], v[212:215], v[84:87]
	v_mfma_f32_16x16x32_bf16 v[72:75], v[152:155], v[222:225], v[72:75]
	v_mfma_f32_16x16x32_bf16 v[68:71], v[168:171], v[222:225], v[68:71]
	s_setprio 0
	s_barrier
; #define PG8_STAGE(bufoff, soff, voff) do { _Pragma("unroll") for (int _i = 0; _i < 2; ++_i) \
;         __builtin_amdgcn_raw_ptr_buffer_load_lds(PG8_RS_##voff, (PG8_LAS void*)(lds + (bufoff) + ldsw + _i * 8192), 16, (voff)[_i], (soff), 0, 0); } while (0)
; #define PG8_LDA(dst, b, h) do { _Pragma("unroll") for (int m = 0; m < 4; ++m) _Pragma("unroll") for (int k = 0; k < 2; ++k) dst[m][k] = *(const PG8_LAS bf16x8*)(lds + PG8_SA(b, h) + aoff + m * 2048 + k * 1024); } while (0)
; #define PG8_MMA(ai, bj, At, Bt) do { __builtin_amdgcn_s_setprio(1); _Pragma("unroll") for (int m = 0; m < 4; ++m) _Pragma("unroll") for (int n = 0; n < 2; ++n) _Pragma("unroll") for (int k = 0; k < 2; ++k) \
;         acc[ai][bj][m][n] = __builtin_amdgcn_mfma_f32_16x16x32_bf16(Bt[n][k], At[m][k], acc[ai][bj][m][n], 0, 0, 0); __builtin_amdgcn_s_setprio(0); } while (0)
; #define PG8_WAIT_V(n) asm volatile("s_waitcnt vmcnt(" #n ")" ::: "memory")
; #define PG8_WAIT_L(n) asm volatile("s_waitcnt lgkmcnt(" #n ")" ::: "memory")
; #define PG8_BAR __builtin_amdgcn_s_barrier()
; #define PG8_SCHED __builtin_amdgcn_sched_barrier(0)
; template <class Epi, class Sched, bool ALIGN_EPI = false, bool SP2 = false>
; __device__ __forceinline__ void gemm_phase(PG8_LAS unsigned char* lds, const Gemm g, const Sched& S, const Epi& E) {
;     ...
;             PG8_LDA(At, 1, 1); PG8_STAGE(PG8_SB(1, 0), b3, voffB); PG8_STAGE(PG8_SB(1, 1), b3 + hstep, voffB); PG8_STAGE(PG8_SA(1, 0), a3, voffA);
;             PG8_WAIT_V(8); PG8_WAIT_L(0); PG8_BAR; PG8_MMA(1, 0, At, B0); PG8_MMA(1, 1, At, B1); PG8_BAR; PG8_SCHED;
	s_mov_b32 m0, s24
	s_or_b32 s51, s50, 0x80
	ds_read_b128 v[172:175], v188 offset:49152
	ds_read_b128 v[176:179], v188 offset:50176
	ds_read_b128 v[190:193], v188 offset:51200
	ds_read_b128 v[194:197], v188 offset:52224
	ds_read_b128 v[208:211], v188 offset:53248
	ds_read_b128 v[212:215], v188 offset:54272
	ds_read_b128 v[218:221], v188 offset:55296
	ds_read_b128 v[222:225], v188 offset:56320
	buffer_load_dwordx4 v180, s[4:7], s51 offen lds
	s_mov_b32 m0, s25
	s_add_i32 s50, s50, 0x80080
	buffer_load_dwordx4 v182, s[4:7], s51 offen lds
	s_mov_b32 m0, s33
	s_nop 0
	buffer_load_dwordx4 v180, s[4:7], s50 offen lds
	s_mov_b32 m0, s34
	s_nop 0
	buffer_load_dwordx4 v182, s[4:7], s50 offen lds
	s_mov_b32 m0, s26
	s_nop 0
	buffer_load_dwordx4 v2, s[28:31], s49 offen lds
	s_mov_b32 m0, s27
	s_nop 0
	buffer_load_dwordx4 v181, s[28:31], s49 offen lds
	s_waitcnt vmcnt(8)
	s_waitcnt lgkmcnt(0)
	s_barrier
	s_setprio 1
	s_waitcnt lgkmcnt(7)
	v_mfma_f32_16x16x32_bf16 v[64:67], v[132:135], v[172:175], v[64:67]
	v_mfma_f32_16x16x32_bf16 v[60:63], v[140:143], v[172:175], v[60:63]
	s_waitcnt lgkmcnt(5)
	v_mfma_f32_16x16x32_bf16 v[48:51], v[132:135], v[190:193], v[48:51]
	v_mfma_f32_16x16x32_bf16 v[44:47], v[140:143], v[190:193], v[44:47]
	s_waitcnt lgkmcnt(3)
	v_mfma_f32_16x16x32_bf16 v[32:35], v[132:135], v[208:211], v[32:35]
	v_mfma_f32_16x16x32_bf16 v[28:31], v[140:143], v[208:211], v[28:31]
	s_waitcnt lgkmcnt(1)
	v_mfma_f32_16x16x32_bf16 v[16:19], v[132:135], v[218:221], v[16:19]
	v_mfma_f32_16x16x32_bf16 v[12:15], v[140:143], v[218:221], v[12:15]
	v_mfma_f32_16x16x32_bf16 v[64:67], v[136:139], v[176:179], v[64:67]
	v_mfma_f32_16x16x32_bf16 v[60:63], v[144:147], v[176:179], v[60:63]
	v_mfma_f32_16x16x32_bf16 v[48:51], v[136:139], v[194:197], v[48:51]
	v_mfma_f32_16x16x32_bf16 v[44:47], v[144:147], v[194:197], v[44:47]
	v_mfma_f32_16x16x32_bf16 v[32:35], v[136:139], v[212:215], v[32:35]
	v_mfma_f32_16x16x32_bf16 v[28:31], v[144:147], v[212:215], v[28:31]
	s_waitcnt lgkmcnt(0)
	v_mfma_f32_16x16x32_bf16 v[16:19], v[136:139], v[222:225], v[16:19]
	v_mfma_f32_16x16x32_bf16 v[12:15], v[144:147], v[222:225], v[12:15]
	s_setprio 0
	s_setprio 1
	v_mfma_f32_16x16x32_bf16 v[56:59], v[148:151], v[172:175], v[56:59]
	v_mfma_f32_16x16x32_bf16 v[52:55], v[156:159], v[172:175], v[52:55]
	v_mfma_f32_16x16x32_bf16 v[40:43], v[148:151], v[190:193], v[40:43]
	v_mfma_f32_16x16x32_bf16 v[36:39], v[156:159], v[190:193], v[36:39]
	v_mfma_f32_16x16x32_bf16 v[24:27], v[148:151], v[208:211], v[24:27]
	v_mfma_f32_16x16x32_bf16 v[20:23], v[156:159], v[208:211], v[20:23]
	v_mfma_f32_16x16x32_bf16 v[8:11], v[148:151], v[218:221], v[8:11]
	v_mfma_f32_16x16x32_bf16 v[4:7], v[156:159], v[218:221], v[4:7]
	v_mfma_f32_16x16x32_bf16 v[56:59], v[152:155], v[176:179], v[56:59]
	v_mfma_f32_16x16x32_bf16 v[52:55], v[168:171], v[176:179], v[52:55]
	v_mfma_f32_16x16x32_bf16 v[40:43], v[152:155], v[194:197], v[40:43]
	v_mfma_f32_16x16x32_bf16 v[36:39], v[168:171], v[194:197], v[36:39]
	v_mfma_f32_16x16x32_bf16 v[24:27], v[152:155], v[212:215], v[24:27]
	v_mfma_f32_16x16x32_bf16 v[20:23], v[168:171], v[212:215], v[20:23]
	v_mfma_f32_16x16x32_bf16 v[8:11], v[152:155], v[222:225], v[8:11]
	v_mfma_f32_16x16x32_bf16 v[4:7], v[168:171], v[222:225], v[4:7]
	s_setprio 0
	s_barrier
	s_add_i32 s48, s48, 2
	s_addk_i32 s46, 0x100
	s_addk_i32 s47, 0x100
	s_cmp_gt_u32 s48, 29

;     __device__ __forceinline__ void operator()(const f32x4 (&acc)[2][2][4][2], const Unit& u, int wr, int wc, int fr, int fq) const {
;     ...
;             for (int m = 0; m < 4; ++m) { float q = sq[ai][m]; q = fq_sum(q); sq[ai][m] = q; }
;             const float v = fq == 0 ? sq[ai][0] : (fq == 1 ? sq[ai][1] : (fq == 2 ? sq[ai][2] : sq[ai][3]));
;             atomicAdd(ssout + (u.pm * BM + wr * 64 + ai * HALF + fq * 16 + fr), (unsigned long long)(v * 16777216.f));
; template <class Epi, class Sched, bool ALIGN_EPI = false, bool SP2 = false>
; __device__ __forceinline__ void gemm_phase(PG8_LAS unsigned char* lds, const Gemm g, const Sched& S, const Epi& E) {
;     ...
;         if (!has_next) break;
; #pragma unroll
;         for (int a = 0; a < 2; ++a)
; #pragma unroll
;             for (int b = 0; b < 2; ++b)
; #pragma unroll
;                 for (int m = 0; m < 4; ++m)
; #pragma unroll
;                     for (int n = 0; n < 2; ++n) { typedef double d2_t __attribute__((ext_vector_type(2))); d2_t z; double z0, z1;
;                         asm volatile("v_mov_b64 %0, 0" : "=v"(z0)); asm volatile("v_mov_b64 %0, 0" : "=v"(z1)); z.x = z0; z.y = z1; acc[a][b][m][n] = __builtin_bit_cast(f32x4, z); }
.LBB0_550:
	s_or_b64 exec, exec, s[0:1]
	v_add_f32_e32 v4, v8, v9
	v_mul_f32_e32 v4, 0x4b800000, v4
	v_trunc_f32_e32 v4, v4
	v_mul_f32_e32 v5, 0x2f800000, v4
	v_floor_f32_e32 v5, v5
	v_fmac_f32_e32 v4, 0xcf800000, v5
	v_cvt_u32_f32_e32 v4, v4
	v_cvt_u32_f32_e32 v5, v5
	v_add_u32_e32 v6, 0x80, v92
	v_ashrrev_i32_e32 v7, 31, v6
	v_lshl_add_u64 v[6:7], v[6:7], 3, s[10:11]
	global_atomic_add_x2 v[6:7], v[4:5], off
	s_andn2_b64 vcc, exec, s[38:39]
	s_mov_b64 s[0:1], -1
	s_cbranch_vccnz .LBB0_519
	s_andn2_b64 vcc, exec, s[2:3]
	s_cbranch_vccnz .LBB0_518
	s_barrier
	s_branch .LBB0_518

; #define PG8_STAGE(bufoff, soff, voff) do { _Pragma("unroll") for (int _i = 0; _i < 2; ++_i) \
;         __builtin_amdgcn_raw_ptr_buffer_load_lds(PG8_RS_##voff, (PG8_LAS void*)(lds + (bufoff) + ldsw + _i * 8192), 16, (voff)[_i], (soff), 0, 0); } while (0)
; #define PG8_LDA(dst, b, h) do { _Pragma("unroll") for (int m = 0; m < 4; ++m) _Pragma("unroll") for (int k = 0; k < 2; ++k) dst[m][k] = *(const PG8_LAS bf16x8*)(lds + PG8_SA(b, h) + aoff + m * 2048 + k * 1024); } while (0)
; #define PG8_LDB(dst, b, h) do { _Pragma("unroll") for (int n = 0; n < 2; ++n) _Pragma("unroll") for (int k = 0; k < 2; ++k) dst[n][k] = *(const PG8_LAS bf16x8*)(lds + PG8_SB(b, h) + boff + n * 2048 + k * 1024); } while (0)
; #define PG8_WAIT_V(n) asm volatile("s_waitcnt vmcnt(" #n ")" ::: "memory")
; #define PG8_WAIT_L(n) asm volatile("s_waitcnt lgkmcnt(" #n ")" ::: "memory")
; #define PG8_BAR __builtin_amdgcn_s_barrier()
; #define PG8_SCHED __builtin_amdgcn_sched_barrier(0)
; template <class Epi, class Sched, bool ALIGN_EPI = false, bool SP2 = false>
; __device__ __forceinline__ void gemm_phase(PG8_LAS unsigned char* lds, const Gemm g, const Sched& S, const Epi& E) {
;     ...
;         const bool has_next = S.next(ui + 1, nxt);
;         const unsigned nA = has_next ? (unsigned)nxt.pm * tstep + (unsigned)nxt.ko * 2u : cA, nB = has_next ? (unsigned)nxt.pn * tstep + (unsigned)nxt.ko * 2u : cB;
;         for (int t = 0; t < nt; t += 2) {
;             const bool last = (t == nt - 2);
;             const unsigned a1 = cA + (unsigned)(t + 1) * kstep;
;             const unsigned a2 = last ? nA : cA + (unsigned)(t + 2) * kstep, b2 = last ? nB : cB + (unsigned)(t + 2) * kstep;
;             const unsigned a3 = a2 + kstep, b3 = b2 + kstep;
;             if (last && has_next) S.a_ready(nxt);
;             if constexpr (SP2) {
;             PG8_LDB(B0, 0, 0); PG8_LDB(B1, 0, 1); PG8_SCHED; PG8_LDA(At, 0, 0); PG8_STAGE(PG8_SA(1, 1), a1 + hstep, voffA);
;             PG8_WAIT_V(8); PG8_WAIT_L(0); PG8_BAR; PG8_MMA(0, 0, At, B0); PG8_MMA(0, 1, At, B1); PG8_BAR; PG8_SCHED;
;             PG8_LDA(At, 0, 1); PG8_STAGE(PG8_SB(0, 0), b2, voffB); PG8_STAGE(PG8_SB(0, 1), b2 + hstep, voffB); PG8_STAGE(PG8_SA(0, 0), a2, voffA);
;             PG8_WAIT_V(8); PG8_WAIT_L(0); PG8_BAR; PG8_MMA(1, 0, At, B0); PG8_MMA(1, 1, At, B1); PG8_BAR; PG8_SCHED;
.LBB0_617:
	s_add_i32 s42, s42, 1
	s_mul_i32 s6, s42, s26
	s_add_i32 s50, s6, s14
	s_lshl_b32 s6, s50, 10
	s_mov_b32 s51, s16
	s_mov_b32 s13, s44
	s_mov_b32 s16, s43
	s_mov_b32 s46, s44
	s_mov_b32 s48, s43
	s_and_b32 s43, s6, 0x400
	s_bfe_u32 s44, s50, 0x10001
	s_cmpk_lt_i32 s50, 0x100
	s_cselect_b64 s[6:7], -1, 0
	s_and_b64 s[6:7], s[6:7], exec
	s_cselect_b32 s6, s43, s16
	s_cselect_b32 s7, s44, s13
	s_lshl_b32 s13, s6, 1
	s_lshl_b32 s6, s7, 20
	s_mov_b32 s52, s45
	s_add_i32 s45, s6, s13
	s_cmpk_lt_i32 s50, 0x100
	s_cselect_b64 s[6:7], -1, 0
	s_and_b64 s[6:7], s[6:7], exec
	s_mov_b32 s12, s15
	s_mov_b32 s47, s15
	s_cselect_b32 s49, s45, s52
	s_ashr_i32 s15, s50, 2
	s_cmpk_lt_i32 s50, 0x100
	s_cselect_b64 s[6:7], -1, 0
	s_and_b64 s[6:7], s[6:7], exec
	s_cselect_b32 s6, s15, s12
	s_lshl_b32 s6, s6, 20
	s_add_i32 s16, s13, s6
	s_cmpk_lt_i32 s50, 0x100
	s_cselect_b64 s[12:13], -1, 0
	s_and_b64 s[6:7], s[12:13], exec
	s_cselect_b32 s50, s16, s51
	s_add_i32 s51, s51, 0x80080
	s_addk_i32 s52, 0x100
	s_mov_b32 s53, -2
	v_add_u32_e32 v2, 0x10000, v139
	ds_read_b128 v[142:145], v2
	ds_read_b128 v[146:149], v2 offset:1024
	ds_read_b128 v[150:153], v2 offset:2048
	ds_read_b128 v[154:157], v2 offset:3072
	v_add_u32_e32 v2, 0x14000, v139
	ds_read_b128 v[168:171], v2
	ds_read_b128 v[172:175], v2 offset:1024
	ds_read_b128 v[176:179], v2 offset:2048
	ds_read_b128 v[180:183], v2 offset:3072
	s_add_i32 s6, s51, 0xfff80080
	s_cmp_eq_u32 s53, 12
	s_cselect_b32 s56, s50, s6
	s_cselect_b32 s55, s49, s52
	s_add_i32 s54, s56, 0x80
	s_mov_b32 m0, s40
	ds_read_b128 v[184:187], v140
	ds_read_b128 v[188:191], v140 offset:1024
	ds_read_b128 v[192:195], v140 offset:2048
	ds_read_b128 v[196:199], v140 offset:3072
	ds_read_b128 v[208:211], v140 offset:4096
	ds_read_b128 v[212:215], v140 offset:5120
	ds_read_b128 v[218:221], v140 offset:6144
	ds_read_b128 v[222:225], v140 offset:7168
	buffer_load_dwordx4 v134, s[28:31], s51 offen lds
	s_mov_b32 m0, s41
	s_nop 0
	buffer_load_dwordx4 v136, s[28:31], s51 offen lds
	s_waitcnt vmcnt(8)
	s_waitcnt lgkmcnt(0)
	s_barrier
	s_setprio 1
	s_waitcnt lgkmcnt(7)
	v_mfma_f32_16x16x32_bf16 v[128:131], v[142:145], v[184:187], 0
	v_mfma_f32_16x16x32_bf16 v[120:123], v[150:153], v[184:187], 0
	s_waitcnt lgkmcnt(5)
	v_mfma_f32_16x16x32_bf16 v[112:115], v[142:145], v[192:195], 0
	v_mfma_f32_16x16x32_bf16 v[104:107], v[150:153], v[192:195], 0
	s_waitcnt lgkmcnt(3)
	v_mfma_f32_16x16x32_bf16 v[96:99], v[142:145], v[208:211], 0
	v_mfma_f32_16x16x32_bf16 v[88:91], v[150:153], v[208:211], 0
	s_waitcnt lgkmcnt(1)
	v_mfma_f32_16x16x32_bf16 v[80:83], v[142:145], v[218:221], 0
	v_mfma_f32_16x16x32_bf16 v[72:75], v[150:153], v[218:221], 0
	v_mfma_f32_16x16x32_bf16 v[128:131], v[146:149], v[188:191], v[128:131]
	v_mfma_f32_16x16x32_bf16 v[120:123], v[154:157], v[188:191], v[120:123]
	v_mfma_f32_16x16x32_bf16 v[112:115], v[146:149], v[196:199], v[112:115]
	v_mfma_f32_16x16x32_bf16 v[104:107], v[154:157], v[196:199], v[104:107]
	v_mfma_f32_16x16x32_bf16 v[96:99], v[146:149], v[212:215], v[96:99]
	v_mfma_f32_16x16x32_bf16 v[88:91], v[154:157], v[212:215], v[88:91]
	s_waitcnt lgkmcnt(0)
	v_mfma_f32_16x16x32_bf16 v[80:83], v[146:149], v[222:225], v[80:83]
	v_mfma_f32_16x16x32_bf16 v[72:75], v[154:157], v[222:225], v[72:75]
	s_setprio 0
	s_setprio 1
	v_mfma_f32_16x16x32_bf16 v[124:127], v[168:171], v[184:187], 0
	v_mfma_f32_16x16x32_bf16 v[116:119], v[176:179], v[184:187], 0
	v_mfma_f32_16x16x32_bf16 v[108:111], v[168:171], v[192:195], 0
	v_mfma_f32_16x16x32_bf16 v[100:103], v[176:179], v[192:195], 0
	v_mfma_f32_16x16x32_bf16 v[92:95], v[168:171], v[208:211], 0
	v_mfma_f32_16x16x32_bf16 v[84:87], v[176:179], v[208:211], 0
	v_mfma_f32_16x16x32_bf16 v[76:79], v[168:171], v[218:221], 0
	v_mfma_f32_16x16x32_bf16 v[68:71], v[176:179], v[218:221], 0
	v_mfma_f32_16x16x32_bf16 v[124:127], v[172:175], v[188:191], v[124:127]
	v_mfma_f32_16x16x32_bf16 v[116:119], v[180:183], v[188:191], v[116:119]
	v_mfma_f32_16x16x32_bf16 v[108:111], v[172:175], v[196:199], v[108:111]
	v_mfma_f32_16x16x32_bf16 v[100:103], v[180:183], v[196:199], v[100:103]
	v_mfma_f32_16x16x32_bf16 v[92:95], v[172:175], v[212:215], v[92:95]
	v_mfma_f32_16x16x32_bf16 v[84:87], v[180:183], v[212:215], v[84:87]
	v_mfma_f32_16x16x32_bf16 v[76:79], v[172:175], v[222:225], v[76:79]
	v_mfma_f32_16x16x32_bf16 v[68:71], v[180:183], v[222:225], v[68:71]
	s_setprio 0
	s_barrier
	s_mov_b32 m0, s18
	s_mov_b32 s6, s30
	s_mov_b32 s7, s31
	ds_read_b128 v[184:187], v140 offset:16384
	ds_read_b128 v[188:191], v140 offset:17408
	ds_read_b128 v[192:195], v140 offset:18432
	ds_read_b128 v[196:199], v140 offset:19456
	ds_read_b128 v[208:211], v140 offset:20480
	ds_read_b128 v[212:215], v140 offset:21504
	ds_read_b128 v[218:221], v140 offset:22528
	ds_read_b128 v[222:225], v140 offset:23552
	buffer_load_dwordx4 v135, s[4:7], s55 offen lds
	s_mov_b32 m0, s19
	s_add_i32 s57, s55, 0x80000
	buffer_load_dwordx4 v137, s[4:7], s55 offen lds
	s_mov_b32 m0, s21
	s_nop 0
	buffer_load_dwordx4 v135, s[4:7], s57 offen lds
	s_mov_b32 m0, s22
	s_nop 0
	buffer_load_dwordx4 v137, s[4:7], s57 offen lds
	s_mov_b32 m0, s17
	s_nop 0
	buffer_load_dwordx4 v134, s[28:31], s56 offen lds
	s_mov_b32 m0, s23
	s_nop 0
	buffer_load_dwordx4 v136, s[28:31], s56 offen lds
	s_waitcnt vmcnt(8)
	s_waitcnt lgkmcnt(0)
	s_barrier
; #define PG8_STAGE(bufoff, soff, voff) do { _Pragma("unroll") for (int _i = 0; _i < 2; ++_i) \
;         __builtin_amdgcn_raw_ptr_buffer_load_lds(PG8_RS_##voff, (PG8_LAS void*)(lds + (bufoff) + ldsw + _i * 8192), 16, (voff)[_i], (soff), 0, 0); } while (0)
; #define PG8_LDA(dst, b, h) do { _Pragma("unroll") for (int m = 0; m < 4; ++m) _Pragma("unroll") for (int k = 0; k < 2; ++k) dst[m][k] = *(const PG8_LAS bf16x8*)(lds + PG8_SA(b, h) + aoff + m * 2048 + k * 1024); } while (0)
; #define PG8_LDB(dst, b, h) do { _Pragma("unroll") for (int n = 0; n < 2; ++n) _Pragma("unroll") for (int k = 0; k < 2; ++k) dst[n][k] = *(const PG8_LAS bf16x8*)(lds + PG8_SB(b, h) + boff + n * 2048 + k * 1024); } while (0)
; #define PG8_MMA(ai, bj, At, Bt) do { __builtin_amdgcn_s_setprio(1); _Pragma("unroll") for (int m = 0; m < 4; ++m) _Pragma("unroll") for (int n = 0; n < 2; ++n) _Pragma("unroll") for (int k = 0; k < 2; ++k) \
;         acc[ai][bj][m][n] = __builtin_amdgcn_mfma_f32_16x16x32_bf16(Bt[n][k], At[m][k], acc[ai][bj][m][n], 0, 0, 0); __builtin_amdgcn_s_setprio(0); } while (0)
; #define PG8_WAIT_V(n) asm volatile("s_waitcnt vmcnt(" #n ")" ::: "memory")
; #define PG8_WAIT_L(n) asm volatile("s_waitcnt lgkmcnt(" #n ")" ::: "memory")
; #define PG8_BAR __builtin_amdgcn_s_barrier()
; #define PG8_SCHED __builtin_amdgcn_sched_barrier(0)
; template <class Epi, class Sched, bool ALIGN_EPI = false, bool SP2 = false>
; __device__ __forceinline__ void gemm_phase(PG8_LAS unsigned char* lds, const Gemm g, const Sched& S, const Epi& E) {
;     ...
;             PG8_WAIT_V(8); PG8_WAIT_L(0); PG8_BAR; PG8_MMA(1, 0, At, B0); PG8_MMA(1, 1, At, B1); PG8_BAR; PG8_SCHED;
;             PG8_LDB(B0, 1, 0); PG8_LDB(B1, 1, 1); PG8_SCHED; PG8_LDA(At, 1, 0); PG8_STAGE(PG8_SA(0, 1), a2 + hstep, voffA);
;             PG8_WAIT_V(8); PG8_WAIT_L(0); PG8_BAR; PG8_MMA(0, 0, At, B0); PG8_MMA(0, 1, At, B1); PG8_BAR; PG8_SCHED;
	s_setprio 1
	s_waitcnt lgkmcnt(7)
	v_mfma_f32_16x16x32_bf16 v[64:67], v[142:145], v[184:187], 0
	v_mfma_f32_16x16x32_bf16 v[60:63], v[150:153], v[184:187], 0
	s_waitcnt lgkmcnt(5)
	v_mfma_f32_16x16x32_bf16 v[48:51], v[142:145], v[192:195], 0
	v_mfma_f32_16x16x32_bf16 v[44:47], v[150:153], v[192:195], 0
	s_waitcnt lgkmcnt(3)
	v_mfma_f32_16x16x32_bf16 v[32:35], v[142:145], v[208:211], 0
	v_mfma_f32_16x16x32_bf16 v[28:31], v[150:153], v[208:211], 0
	s_waitcnt lgkmcnt(1)
	v_mfma_f32_16x16x32_bf16 v[16:19], v[142:145], v[218:221], 0
	v_mfma_f32_16x16x32_bf16 v[12:15], v[150:153], v[218:221], 0
	v_mfma_f32_16x16x32_bf16 v[64:67], v[146:149], v[188:191], v[64:67]
	v_mfma_f32_16x16x32_bf16 v[60:63], v[154:157], v[188:191], v[60:63]
	v_mfma_f32_16x16x32_bf16 v[48:51], v[146:149], v[196:199], v[48:51]
	v_mfma_f32_16x16x32_bf16 v[44:47], v[154:157], v[196:199], v[44:47]
	v_mfma_f32_16x16x32_bf16 v[32:35], v[146:149], v[212:215], v[32:35]
	v_mfma_f32_16x16x32_bf16 v[28:31], v[154:157], v[212:215], v[28:31]
	s_waitcnt lgkmcnt(0)
	v_mfma_f32_16x16x32_bf16 v[16:19], v[146:149], v[222:225], v[16:19]
	v_mfma_f32_16x16x32_bf16 v[12:15], v[154:157], v[222:225], v[12:15]
	s_setprio 0
	s_setprio 1
	v_mfma_f32_16x16x32_bf16 v[56:59], v[168:171], v[184:187], 0
	v_mfma_f32_16x16x32_bf16 v[52:55], v[176:179], v[184:187], 0
	v_mfma_f32_16x16x32_bf16 v[40:43], v[168:171], v[192:195], 0
	v_mfma_f32_16x16x32_bf16 v[36:39], v[176:179], v[192:195], 0
	v_mfma_f32_16x16x32_bf16 v[24:27], v[168:171], v[208:211], 0
	v_mfma_f32_16x16x32_bf16 v[20:23], v[176:179], v[208:211], 0
	v_mfma_f32_16x16x32_bf16 v[8:11], v[168:171], v[218:221], 0
	v_mfma_f32_16x16x32_bf16 v[4:7], v[176:179], v[218:221], 0
	v_mfma_f32_16x16x32_bf16 v[56:59], v[172:175], v[188:191], v[56:59]
	v_mfma_f32_16x16x32_bf16 v[52:55], v[180:183], v[188:191], v[52:55]
	v_mfma_f32_16x16x32_bf16 v[40:43], v[172:175], v[196:199], v[40:43]
	v_mfma_f32_16x16x32_bf16 v[36:39], v[180:183], v[196:199], v[36:39]
	v_mfma_f32_16x16x32_bf16 v[24:27], v[172:175], v[212:215], v[24:27]
	v_mfma_f32_16x16x32_bf16 v[20:23], v[180:183], v[212:215], v[20:23]
	v_mfma_f32_16x16x32_bf16 v[8:11], v[172:175], v[222:225], v[8:11]
	v_mfma_f32_16x16x32_bf16 v[4:7], v[180:183], v[222:225], v[4:7]
	s_setprio 0
	s_barrier
	v_add_u32_e32 v2, 0x18000, v139
	ds_read_b128 v[142:145], v2
	ds_read_b128 v[146:149], v2 offset:1024
	ds_read_b128 v[150:153], v2 offset:2048
	ds_read_b128 v[154:157], v2 offset:3072
	v_add_u32_e32 v2, 0x1c000, v139
	ds_read_b128 v[168:171], v2
	ds_read_b128 v[172:175], v2 offset:1024
	ds_read_b128 v[176:179], v2 offset:2048
	ds_read_b128 v[180:183], v2 offset:3072
	s_add_i32 s56, s56, 0x80000
	s_mov_b32 m0, s24
	ds_read_b128 v[184:187], v140 offset:32768
	ds_read_b128 v[188:191], v140 offset:33792
	ds_read_b128 v[192:195], v140 offset:34816
	ds_read_b128 v[196:199], v140 offset:35840
	ds_read_b128 v[208:211], v140 offset:36864
	ds_read_b128 v[212:215], v140 offset:37888
	ds_read_b128 v[218:221], v140 offset:38912
	ds_read_b128 v[222:225], v140 offset:39936
	buffer_load_dwordx4 v134, s[28:31], s56 offen lds
	s_mov_b32 m0, s25
	s_nop 0
	buffer_load_dwordx4 v136, s[28:31], s56 offen lds
	s_waitcnt vmcnt(8)
	s_waitcnt lgkmcnt(0)
	s_barrier
	s_setprio 1
	s_waitcnt lgkmcnt(7)
	v_mfma_f32_16x16x32_bf16 v[128:131], v[142:145], v[184:187], v[128:131]
	v_mfma_f32_16x16x32_bf16 v[120:123], v[150:153], v[184:187], v[120:123]
	s_waitcnt lgkmcnt(5)
	v_mfma_f32_16x16x32_bf16 v[112:115], v[142:145], v[192:195], v[112:115]
	v_mfma_f32_16x16x32_bf16 v[104:107], v[150:153], v[192:195], v[104:107]
	s_waitcnt lgkmcnt(3)
	v_mfma_f32_16x16x32_bf16 v[96:99], v[142:145], v[208:211], v[96:99]
	v_mfma_f32_16x16x32_bf16 v[88:91], v[150:153], v[208:211], v[88:91]
	s_waitcnt lgkmcnt(1)
	v_mfma_f32_16x16x32_bf16 v[80:83], v[142:145], v[218:221], v[80:83]
	v_mfma_f32_16x16x32_bf16 v[72:75], v[150:153], v[218:221], v[72:75]
	v_mfma_f32_16x16x32_bf16 v[128:131], v[146:149], v[188:191], v[128:131]
	v_mfma_f32_16x16x32_bf16 v[120:123], v[154:157], v[188:191], v[120:123]
	v_mfma_f32_16x16x32_bf16 v[112:115], v[146:149], v[196:199], v[112:115]
	v_mfma_f32_16x16x32_bf16 v[104:107], v[154:157], v[196:199], v[104:107]
	v_mfma_f32_16x16x32_bf16 v[96:99], v[146:149], v[212:215], v[96:99]
	v_mfma_f32_16x16x32_bf16 v[88:91], v[154:157], v[212:215], v[88:91]
	s_waitcnt lgkmcnt(0)
	v_mfma_f32_16x16x32_bf16 v[80:83], v[146:149], v[222:225], v[80:83]
	v_mfma_f32_16x16x32_bf16 v[72:75], v[154:157], v[222:225], v[72:75]
	s_setprio 0
	s_setprio 1
	v_mfma_f32_16x16x32_bf16 v[124:127], v[168:171], v[184:187], v[124:127]
	v_mfma_f32_16x16x32_bf16 v[116:119], v[176:179], v[184:187], v[116:119]
	v_mfma_f32_16x16x32_bf16 v[108:111], v[168:171], v[192:195], v[108:111]
	v_mfma_f32_16x16x32_bf16 v[100:103], v[176:179], v[192:195], v[100:103]
	v_mfma_f32_16x16x32_bf16 v[92:95], v[168:171], v[208:211], v[92:95]
	v_mfma_f32_16x16x32_bf16 v[84:87], v[176:179], v[208:211], v[84:87]
	v_mfma_f32_16x16x32_bf16 v[76:79], v[168:171], v[218:221], v[76:79]
	v_mfma_f32_16x16x32_bf16 v[68:71], v[176:179], v[218:221], v[68:71]
	v_mfma_f32_16x16x32_bf16 v[124:127], v[172:175], v[188:191], v[124:127]
	v_mfma_f32_16x16x32_bf16 v[116:119], v[180:183], v[188:191], v[116:119]
	v_mfma_f32_16x16x32_bf16 v[108:111], v[172:175], v[196:199], v[108:111]
	v_mfma_f32_16x16x32_bf16 v[100:103], v[180:183], v[196:199], v[100:103]
	v_mfma_f32_16x16x32_bf16 v[92:95], v[172:175], v[212:215], v[92:95]
	v_mfma_f32_16x16x32_bf16 v[84:87], v[180:183], v[212:215], v[84:87]
	v_mfma_f32_16x16x32_bf16 v[76:79], v[172:175], v[222:225], v[76:79]
	v_mfma_f32_16x16x32_bf16 v[68:71], v[180:183], v[222:225], v[68:71]
	s_setprio 0
	s_barrier
; #define PG8_STAGE(bufoff, soff, voff) do { _Pragma("unroll") for (int _i = 0; _i < 2; ++_i) \
;         __builtin_amdgcn_raw_ptr_buffer_load_lds(PG8_RS_##voff, (PG8_LAS void*)(lds + (bufoff) + ldsw + _i * 8192), 16, (voff)[_i], (soff), 0, 0); } while (0)
; #define PG8_LDA(dst, b, h) do { _Pragma("unroll") for (int m = 0; m < 4; ++m) _Pragma("unroll") for (int k = 0; k < 2; ++k) dst[m][k] = *(const PG8_LAS bf16x8*)(lds + PG8_SA(b, h) + aoff + m * 2048 + k * 1024); } while (0)
; #define PG8_LDB(dst, b, h) do { _Pragma("unroll") for (int n = 0; n < 2; ++n) _Pragma("unroll") for (int k = 0; k < 2; ++k) dst[n][k] = *(const PG8_LAS bf16x8*)(lds + PG8_SB(b, h) + boff + n * 2048 + k * 1024); } while (0)
; template <class Epi, class Sched, bool ALIGN_EPI = false, bool SP2 = false>
; __device__ __forceinline__ void gemm_phase(PG8_LAS unsigned char* lds, const Gemm g, const Sched& S, const Epi& E) {
;     ...
;         for (int t = 0; t < nt; t += 2) {
;             const bool last = (t == nt - 2);
;             const unsigned a1 = cA + (unsigned)(t + 1) * kstep;
;             const unsigned a2 = last ? nA : cA + (unsigned)(t + 2) * kstep, b2 = last ? nB : cB + (unsigned)(t + 2) * kstep;
;             const unsigned a3 = a2 + kstep, b3 = b2 + kstep;
;             if (last && has_next) S.a_ready(nxt);
;             if constexpr (SP2) {
;             PG8_LDB(B0, 0, 0); PG8_LDB(B1, 0, 1); PG8_SCHED; PG8_LDA(At, 0, 0); PG8_STAGE(PG8_SA(1, 1), a1 + hstep, voffA);
;             PG8_WAIT_V(8); PG8_WAIT_L(0); PG8_BAR; PG8_MMA(0, 0, At, B0); PG8_MMA(0, 1, At, B1); PG8_BAR; PG8_SCHED;
;             PG8_LDA(At, 0, 1); PG8_STAGE(PG8_SB(0, 0), b2, voffB); PG8_STAGE(PG8_SB(0, 1), b2 + hstep, voffB); PG8_STAGE(PG8_SA(0, 0), a2, voffA);
;             PG8_WAIT_V(8); PG8_WAIT_L(0); PG8_BAR; PG8_MMA(1, 0, At, B0); PG8_MMA(1, 1, At, B1); PG8_BAR; PG8_SCHED;
;             PG8_LDB(B0, 1, 0); PG8_LDB(B1, 1, 1); PG8_SCHED; PG8_LDA(At, 1, 0); PG8_STAGE(PG8_SA(0, 1), a2 + hstep, voffA);
;             PG8_WAIT_V(8); PG8_WAIT_L(0); PG8_BAR; PG8_MMA(0, 0, At, B0); PG8_MMA(0, 1, At, B1); PG8_BAR; PG8_SCHED;
;             PG8_LDA(At, 1, 1); PG8_STAGE(PG8_SB(1, 0), b3, voffB); PG8_STAGE(PG8_SB(1, 1), b3 + hstep, voffB); PG8_STAGE(PG8_SA(1, 0), a3, voffA);
;             PG8_WAIT_V(8); PG8_WAIT_L(0); PG8_BAR; PG8_MMA(1, 0, At, B0); PG8_MMA(1, 1, At, B1); PG8_BAR; PG8_SCHED;
	s_mov_b32 m0, s34
	s_add_i32 s56, s55, 0x80
	ds_read_b128 v[184:187], v140 offset:49152
	ds_read_b128 v[188:191], v140 offset:50176
	ds_read_b128 v[192:195], v140 offset:51200
	ds_read_b128 v[196:199], v140 offset:52224
	ds_read_b128 v[208:211], v140 offset:53248
	ds_read_b128 v[212:215], v140 offset:54272
	ds_read_b128 v[218:221], v140 offset:55296
	ds_read_b128 v[222:225], v140 offset:56320
	buffer_load_dwordx4 v135, s[4:7], s56 offen lds
	s_mov_b32 m0, s35
	s_add_i32 s55, s55, 0x80080
	buffer_load_dwordx4 v137, s[4:7], s56 offen lds
	s_mov_b32 m0, s38
	s_nop 0
	buffer_load_dwordx4 v135, s[4:7], s55 offen lds
	s_mov_b32 m0, s39
	s_nop 0
	buffer_load_dwordx4 v137, s[4:7], s55 offen lds
	s_mov_b32 m0, s36
	s_nop 0
	buffer_load_dwordx4 v134, s[28:31], s54 offen lds
	s_mov_b32 m0, s37
	s_nop 0
	buffer_load_dwordx4 v136, s[28:31], s54 offen lds
	s_waitcnt vmcnt(8)
	s_waitcnt lgkmcnt(0)
	s_barrier
	s_setprio 1
	s_waitcnt lgkmcnt(7)
	v_mfma_f32_16x16x32_bf16 v[64:67], v[142:145], v[184:187], v[64:67]
	v_mfma_f32_16x16x32_bf16 v[60:63], v[150:153], v[184:187], v[60:63]
	s_waitcnt lgkmcnt(5)
	v_mfma_f32_16x16x32_bf16 v[48:51], v[142:145], v[192:195], v[48:51]
	v_mfma_f32_16x16x32_bf16 v[44:47], v[150:153], v[192:195], v[44:47]
	s_waitcnt lgkmcnt(3)
	v_mfma_f32_16x16x32_bf16 v[32:35], v[142:145], v[208:211], v[32:35]
	v_mfma_f32_16x16x32_bf16 v[28:31], v[150:153], v[208:211], v[28:31]
	s_waitcnt lgkmcnt(1)
	v_mfma_f32_16x16x32_bf16 v[16:19], v[142:145], v[218:221], v[16:19]
	v_mfma_f32_16x16x32_bf16 v[12:15], v[150:153], v[218:221], v[12:15]
	v_mfma_f32_16x16x32_bf16 v[64:67], v[146:149], v[188:191], v[64:67]
	v_mfma_f32_16x16x32_bf16 v[60:63], v[154:157], v[188:191], v[60:63]
	v_mfma_f32_16x16x32_bf16 v[48:51], v[146:149], v[196:199], v[48:51]
	v_mfma_f32_16x16x32_bf16 v[44:47], v[154:157], v[196:199], v[44:47]
	v_mfma_f32_16x16x32_bf16 v[32:35], v[146:149], v[212:215], v[32:35]
	v_mfma_f32_16x16x32_bf16 v[28:31], v[154:157], v[212:215], v[28:31]
	s_waitcnt lgkmcnt(0)
	v_mfma_f32_16x16x32_bf16 v[16:19], v[146:149], v[222:225], v[16:19]
	v_mfma_f32_16x16x32_bf16 v[12:15], v[154:157], v[222:225], v[12:15]
	s_setprio 0
	s_setprio 1
	v_mfma_f32_16x16x32_bf16 v[56:59], v[168:171], v[184:187], v[56:59]
	v_mfma_f32_16x16x32_bf16 v[52:55], v[176:179], v[184:187], v[52:55]
	v_mfma_f32_16x16x32_bf16 v[40:43], v[168:171], v[192:195], v[40:43]
	v_mfma_f32_16x16x32_bf16 v[36:39], v[176:179], v[192:195], v[36:39]
	v_mfma_f32_16x16x32_bf16 v[24:27], v[168:171], v[208:211], v[24:27]
	v_mfma_f32_16x16x32_bf16 v[20:23], v[176:179], v[208:211], v[20:23]
	v_mfma_f32_16x16x32_bf16 v[8:11], v[168:171], v[218:221], v[8:11]
	v_mfma_f32_16x16x32_bf16 v[4:7], v[176:179], v[218:221], v[4:7]
	v_mfma_f32_16x16x32_bf16 v[56:59], v[172:175], v[188:191], v[56:59]
	v_mfma_f32_16x16x32_bf16 v[52:55], v[180:183], v[188:191], v[52:55]
	v_mfma_f32_16x16x32_bf16 v[40:43], v[172:175], v[196:199], v[40:43]
	v_mfma_f32_16x16x32_bf16 v[36:39], v[180:183], v[196:199], v[36:39]
	v_mfma_f32_16x16x32_bf16 v[24:27], v[172:175], v[212:215], v[24:27]
	v_mfma_f32_16x16x32_bf16 v[20:23], v[180:183], v[212:215], v[20:23]
	v_mfma_f32_16x16x32_bf16 v[8:11], v[172:175], v[222:225], v[8:11]
	v_mfma_f32_16x16x32_bf16 v[4:7], v[180:183], v[222:225], v[4:7]
	s_setprio 0
	s_barrier
	s_add_i32 s53, s53, 2
	s_addk_i32 s51, 0x100
	s_addk_i32 s52, 0x100
	s_cmp_gt_u32 s53, 13

; __device__ __forceinline__ unsigned cvt_pk_bf16(float lo, float hi) { unsigned r; asm volatile("v_cvt_pk_bf16_f32 %0, %1, %2" : "=v"(r) : "v"(lo), "v"(hi)); return r; }
;     __device__ __forceinline__ void operator()(const f32x4 (&acc)[2][2][4][2], const Unit& u, int wr, int wc, int fr, int fq) const {
;     ...
;         const int col0 = colt + wc * 32 + 8 * fq;
; #pragma unroll
;         for (int ai = 0; ai < 2; ++ai)
; #pragma unroll
;             for (int m = 0; m < 4; ++m) { bf16_t* rowp = base + (size_t)(row0 + ai * HALF + m * 16) * ldc + col0;
; #pragma unroll
;                 for (int bj = 0; bj < 2; ++bj) { f32x4 v0 = acc[ai][bj][m][0], v1 = acc[ai][bj][m][1];
;                     if (ACT == 2) {
; #pragma unroll
;                         for (int e = 0; e < 4; ++e) { const float a = fmaxf(v0[e], 0.f), b = fmaxf(v1[e], 0.f); v0[e] = a * a; v1[e] = b * b; } }
;                     u32x4 w; w.x = cvt_pk_bf16(v0[0], v0[1]); w.y = cvt_pk_bf16(v0[2], v0[3]); w.z = cvt_pk_bf16(v1[0], v1[1]); w.w = cvt_pk_bf16(v1[2], v1[3]);
;                     *(u32x4*)(rowp + bj * HALF) = w; } }
; template <class Epi, class Sched, bool ALIGN_EPI = false, bool SP2 = false>
; __device__ __forceinline__ void gemm_phase(PG8_LAS unsigned char* lds, const Gemm g, const Sched& S, const Epi& E) {
;     ...
; #pragma unroll
;         for (int a = 0; a < 2; ++a)
; #pragma unroll
;             for (int b = 0; b < 2; ++b)
; #pragma unroll
;                 for (int m = 0; m < 4; ++m)
; #pragma unroll
;                     for (int n = 0; n < 2; ++n) { typedef double d2_t __attribute__((ext_vector_type(2))); d2_t z; double z0, z1;
;                         asm volatile("v_mov_b64 %0, 0" : "=v"(z0)); asm volatile("v_mov_b64 %0, 0" : "=v"(z1)); z.x = z0; z.y = z1; acc[a][b][m][n] = __builtin_bit_cast(f32x4, z); }
.LBB0_621:
	s_cmp_eq_u32 s48, 0
	s_cselect_b32 s6, 0, 0x1b000000
	s_add_u32 s6, s27, s6
	v_lshl_add_u32 v142, s47, 8, v138
	s_addc_u32 s7, s33, 0
	v_lshl_or_b32 v2, s46, 9, v141
	v_ashrrev_i32_e32 v143, 31, v142
	v_lshl_add_u64 v[144:145], s[6:7], 0, v[2:3]
	v_lshlrev_b64 v[132:133], 10, v[142:143]
	v_lshl_add_u64 v[132:133], v[144:145], 0, v[132:133]
	v_cvt_pk_bf16_f32 v128, v128, v129
	v_cvt_pk_bf16_f32 v129, v130, v131
	v_cvt_pk_bf16_f32 v130, v120, v121
	v_cvt_pk_bf16_f32 v131, v122, v123
	global_store_dwordx4 v[132:133], v[128:131], off
	v_cvt_pk_bf16_f32 v120, v124, v125
	v_cvt_pk_bf16_f32 v121, v126, v127
	v_cvt_pk_bf16_f32 v122, v116, v117
	v_or_b32_e32 v116, 16, v142
	v_ashrrev_i32_e32 v117, 31, v116
	v_lshlrev_b64 v[116:117], 10, v[116:117]
	v_lshl_add_u64 v[116:117], v[144:145], 0, v[116:117]
	v_cvt_pk_bf16_f32 v123, v118, v119
	global_store_dwordx4 v[132:133], v[120:123], off offset:256
	v_cvt_pk_bf16_f32 v112, v112, v113
	v_cvt_pk_bf16_f32 v113, v114, v115
	v_cvt_pk_bf16_f32 v114, v104, v105
	v_cvt_pk_bf16_f32 v115, v106, v107
	global_store_dwordx4 v[116:117], v[112:115], off
	v_cvt_pk_bf16_f32 v104, v108, v109
	v_cvt_pk_bf16_f32 v105, v110, v111
	v_cvt_pk_bf16_f32 v106, v100, v101
	v_or_b32_e32 v100, 32, v142
	v_ashrrev_i32_e32 v101, 31, v100
	v_lshlrev_b64 v[100:101], 10, v[100:101]
	v_lshl_add_u64 v[100:101], v[144:145], 0, v[100:101]
	v_cvt_pk_bf16_f32 v107, v102, v103
	global_store_dwordx4 v[116:117], v[104:107], off offset:256
	v_cvt_pk_bf16_f32 v96, v96, v97
	v_cvt_pk_bf16_f32 v97, v98, v99
	v_cvt_pk_bf16_f32 v98, v88, v89
	v_cvt_pk_bf16_f32 v99, v90, v91
	global_store_dwordx4 v[100:101], v[96:99], off
	v_cvt_pk_bf16_f32 v88, v92, v93
	v_cvt_pk_bf16_f32 v89, v94, v95
	v_cvt_pk_bf16_f32 v90, v84, v85
	v_or_b32_e32 v84, 48, v142
	v_ashrrev_i32_e32 v85, 31, v84
	v_lshlrev_b64 v[84:85], 10, v[84:85]
	v_lshl_add_u64 v[84:85], v[144:145], 0, v[84:85]
	v_cvt_pk_bf16_f32 v91, v86, v87
	global_store_dwordx4 v[100:101], v[88:91], off offset:256
	v_cvt_pk_bf16_f32 v80, v80, v81
	v_cvt_pk_bf16_f32 v81, v82, v83
	v_cvt_pk_bf16_f32 v82, v72, v73
	v_cvt_pk_bf16_f32 v83, v74, v75
	global_store_dwordx4 v[84:85], v[80:83], off
	v_cvt_pk_bf16_f32 v72, v76, v77
	v_cvt_pk_bf16_f32 v73, v78, v79
	v_cvt_pk_bf16_f32 v74, v68, v69
	v_cvt_pk_bf16_f32 v75, v70, v71
	global_store_dwordx4 v[84:85], v[72:75], off offset:256
	s_mov_b64 s[6:7], 0x20000
	v_cvt_pk_bf16_f32 v64, v64, v65
	v_cvt_pk_bf16_f32 v65, v66, v67
	v_cvt_pk_bf16_f32 v66, v60, v61
	v_add_co_u32_e32 v60, vcc, s31, v132
	v_lshl_add_u64 v[68:69], v[132:133], 0, s[6:7]
	s_nop 0
	v_addc_co_u32_e32 v61, vcc, 0, v133, vcc
	s_mov_b64 s[6:7], 0x24000
	v_cvt_pk_bf16_f32 v67, v62, v63
	global_store_dwordx4 v[60:61], v[64:67], off
	v_cvt_pk_bf16_f32 v56, v56, v57
	v_cvt_pk_bf16_f32 v57, v58, v59
	v_cvt_pk_bf16_f32 v58, v52, v53
	v_lshl_add_u64 v[52:53], v[132:133], 0, s[6:7]
	s_mov_b32 s6, 0x24000
	v_cvt_pk_bf16_f32 v59, v54, v55
	global_store_dwordx4 v[68:69], v[56:59], off offset:256
	v_cvt_pk_bf16_f32 v48, v48, v49
	v_cvt_pk_bf16_f32 v49, v50, v51
	v_cvt_pk_bf16_f32 v50, v44, v45
	v_add_co_u32_e32 v44, vcc, s6, v132
	s_mov_b64 s[6:7], 0x28000
	s_nop 0
	v_addc_co_u32_e32 v45, vcc, 0, v133, vcc
	v_cvt_pk_bf16_f32 v51, v46, v47
	global_store_dwordx4 v[44:45], v[48:51], off
	v_cvt_pk_bf16_f32 v40, v40, v41
	v_cvt_pk_bf16_f32 v41, v42, v43
	v_cvt_pk_bf16_f32 v42, v36, v37
	v_lshl_add_u64 v[36:37], v[132:133], 0, s[6:7]
	s_mov_b32 s6, 0x28000
	v_cvt_pk_bf16_f32 v43, v38, v39
	global_store_dwordx4 v[52:53], v[40:43], off offset:256
	v_cvt_pk_bf16_f32 v32, v32, v33
	v_cvt_pk_bf16_f32 v33, v34, v35
	v_cvt_pk_bf16_f32 v34, v28, v29
	v_add_co_u32_e32 v28, vcc, s6, v132
	s_mov_b64 s[6:7], 0x2c000
	s_nop 0
	v_addc_co_u32_e32 v29, vcc, 0, v133, vcc
	v_cvt_pk_bf16_f32 v35, v30, v31
	global_store_dwordx4 v[28:29], v[32:35], off
	v_cvt_pk_bf16_f32 v24, v24, v25
	v_cvt_pk_bf16_f32 v25, v26, v27
	v_cvt_pk_bf16_f32 v26, v20, v21
	v_lshl_add_u64 v[20:21], v[132:133], 0, s[6:7]
	s_mov_b32 s6, 0x2c000
	v_cvt_pk_bf16_f32 v27, v22, v23
	global_store_dwordx4 v[36:37], v[24:27], off offset:256
	v_cvt_pk_bf16_f32 v16, v16, v17
	v_cvt_pk_bf16_f32 v17, v18, v19
	v_cvt_pk_bf16_f32 v18, v12, v13
	v_add_co_u32_e32 v12, vcc, s6, v132
	v_cvt_pk_bf16_f32 v19, v14, v15
	s_mov_b64 s[6:7], -1
	s_nop 0
	v_addc_co_u32_e32 v13, vcc, 0, v133, vcc
	global_store_dwordx4 v[12:13], v[16:19], off
	v_cvt_pk_bf16_f32 v8, v8, v9
	v_cvt_pk_bf16_f32 v9, v10, v11
	v_cvt_pk_bf16_f32 v10, v4, v5
	v_cvt_pk_bf16_f32 v11, v6, v7
	s_andn2_b64 vcc, exec, s[12:13]
	v_readlane_b32 s46, v254, 18
	global_store_dwordx4 v[20:21], v[8:11], off offset:256
	v_readlane_b32 s47, v254, 19
	s_cbranch_vccnz .LBB0_616
	s_andn2_b64 vcc, exec, s[8:9]
	s_cbranch_vccnz .LBB0_615
	s_barrier
	s_branch .LBB0_615

; #define PG8_STAGE(bufoff, soff, voff) do { _Pragma("unroll") for (int _i = 0; _i < 2; ++_i) \
;         __builtin_amdgcn_raw_ptr_buffer_load_lds(PG8_RS_##voff, (PG8_LAS void*)(lds + (bufoff) + ldsw + _i * 8192), 16, (voff)[_i], (soff), 0, 0); } while (0)
; #define PG8_LDA(dst, b, h) do { _Pragma("unroll") for (int m = 0; m < 4; ++m) _Pragma("unroll") for (int k = 0; k < 2; ++k) dst[m][k] = *(const PG8_LAS bf16x8*)(lds + PG8_SA(b, h) + aoff + m * 2048 + k * 1024); } while (0)
; #define PG8_LDB(dst, b, h) do { _Pragma("unroll") for (int n = 0; n < 2; ++n) _Pragma("unroll") for (int k = 0; k < 2; ++k) dst[n][k] = *(const PG8_LAS bf16x8*)(lds + PG8_SB(b, h) + boff + n * 2048 + k * 1024); } while (0)
; #define PG8_WAIT_V(n) asm volatile("s_waitcnt vmcnt(" #n ")" ::: "memory")
; #define PG8_WAIT_L(n) asm volatile("s_waitcnt lgkmcnt(" #n ")" ::: "memory")
; #define PG8_BAR __builtin_amdgcn_s_barrier()
; #define PG8_SCHED __builtin_amdgcn_sched_barrier(0)
; template <class Epi, class Sched, bool ALIGN_EPI = false, bool SP2 = false>
; __device__ __forceinline__ void gemm_phase(PG8_LAS unsigned char* lds, const Gemm g, const Sched& S, const Epi& E) {
;     ...
;         const bool has_next = S.next(ui + 1, nxt);
;         const unsigned nA = has_next ? (unsigned)nxt.pm * tstep + (unsigned)nxt.ko * 2u : cA, nB = has_next ? (unsigned)nxt.pn * tstep + (unsigned)nxt.ko * 2u : cB;
;         for (int t = 0; t < nt; t += 2) {
;             const bool last = (t == nt - 2);
;             const unsigned a1 = cA + (unsigned)(t + 1) * kstep;
;             const unsigned a2 = last ? nA : cA + (unsigned)(t + 2) * kstep, b2 = last ? nB : cB + (unsigned)(t + 2) * kstep;
;             const unsigned a3 = a2 + kstep, b3 = b2 + kstep;
;             if (last && has_next) S.a_ready(nxt);
;             if constexpr (SP2) {
;             PG8_LDB(B0, 0, 0); PG8_LDB(B1, 0, 1); PG8_SCHED; PG8_LDA(At, 0, 0); PG8_STAGE(PG8_SA(1, 1), a1 + hstep, voffA);
;             PG8_WAIT_V(8); PG8_WAIT_L(0); PG8_BAR; PG8_MMA(0, 0, At, B0); PG8_MMA(0, 1, At, B1); PG8_BAR; PG8_SCHED;
;             PG8_LDA(At, 0, 1); PG8_STAGE(PG8_SB(0, 0), b2, voffB); PG8_STAGE(PG8_SB(0, 1), b2 + hstep, voffB); PG8_STAGE(PG8_SA(0, 0), a2, voffA);
;             PG8_WAIT_V(8); PG8_WAIT_L(0); PG8_BAR; PG8_MMA(1, 0, At, B0); PG8_MMA(1, 1, At, B1); PG8_BAR; PG8_SCHED;
.LBB0_634:
	s_lshl_b32 s37, s35, 20
	s_and_b64 s[42:43], s[10:11], exec
	s_cselect_b32 s41, s37, s7
	s_lshl_b32 s38, s36, 20
	s_and_b64 s[42:43], s[10:11], exec
	s_cselect_b32 s42, s38, s6
	s_add_i32 s43, s7, 0x80080
	s_add_i32 s44, s6, 0x100
	s_mov_b32 s45, -2
	v_add_u32_e32 v132, 0x10000, v139
	ds_read_b128 v[142:145], v132
	ds_read_b128 v[146:149], v132 offset:1024
	ds_read_b128 v[150:153], v132 offset:2048
	ds_read_b128 v[154:157], v132 offset:3072
	v_add_u32_e32 v132, 0x14000, v139
	ds_read_b128 v[168:171], v132
	ds_read_b128 v[172:175], v132 offset:1024
	ds_read_b128 v[176:179], v132 offset:2048
	ds_read_b128 v[180:183], v132 offset:3072
	s_add_i32 s6, s43, 0xfff80080
	s_cmp_eq_u32 s45, 28
	s_cselect_b32 s48, s41, s6
	s_cselect_b32 s47, s42, s44
	s_or_b32 s46, s48, 0x80
	s_mov_b32 m0, s27
	ds_read_b128 v[184:187], v140
	ds_read_b128 v[188:191], v140 offset:1024
	ds_read_b128 v[192:195], v140 offset:2048
	ds_read_b128 v[196:199], v140 offset:3072
	ds_read_b128 v[208:211], v140 offset:4096
	ds_read_b128 v[212:215], v140 offset:5120
	ds_read_b128 v[218:221], v140 offset:6144
	ds_read_b128 v[222:225], v140 offset:7168
	buffer_load_dwordx4 v2, s[28:31], s43 offen lds
	s_mov_b32 m0, s33
	s_nop 0
	buffer_load_dwordx4 v135, s[28:31], s43 offen lds
	s_waitcnt vmcnt(8)
	s_waitcnt lgkmcnt(0)
	s_barrier
	s_setprio 1
	s_waitcnt lgkmcnt(7)
	v_mfma_f32_16x16x32_bf16 v[128:131], v[142:145], v[184:187], 0
	v_mfma_f32_16x16x32_bf16 v[120:123], v[150:153], v[184:187], 0
	s_waitcnt lgkmcnt(5)
	v_mfma_f32_16x16x32_bf16 v[112:115], v[142:145], v[192:195], 0
	v_mfma_f32_16x16x32_bf16 v[104:107], v[150:153], v[192:195], 0
	s_waitcnt lgkmcnt(3)
	v_mfma_f32_16x16x32_bf16 v[96:99], v[142:145], v[208:211], 0
	v_mfma_f32_16x16x32_bf16 v[88:91], v[150:153], v[208:211], 0
	s_waitcnt lgkmcnt(1)
	v_mfma_f32_16x16x32_bf16 v[80:83], v[142:145], v[218:221], 0
	v_mfma_f32_16x16x32_bf16 v[72:75], v[150:153], v[218:221], 0
	v_mfma_f32_16x16x32_bf16 v[128:131], v[146:149], v[188:191], v[128:131]
	v_mfma_f32_16x16x32_bf16 v[120:123], v[154:157], v[188:191], v[120:123]
	v_mfma_f32_16x16x32_bf16 v[112:115], v[146:149], v[196:199], v[112:115]
	v_mfma_f32_16x16x32_bf16 v[104:107], v[154:157], v[196:199], v[104:107]
	v_mfma_f32_16x16x32_bf16 v[96:99], v[146:149], v[212:215], v[96:99]
	v_mfma_f32_16x16x32_bf16 v[88:91], v[154:157], v[212:215], v[88:91]
	s_waitcnt lgkmcnt(0)
	v_mfma_f32_16x16x32_bf16 v[80:83], v[146:149], v[222:225], v[80:83]
	v_mfma_f32_16x16x32_bf16 v[72:75], v[154:157], v[222:225], v[72:75]
	s_setprio 0
	s_setprio 1
	v_mfma_f32_16x16x32_bf16 v[124:127], v[168:171], v[184:187], 0
	v_mfma_f32_16x16x32_bf16 v[116:119], v[176:179], v[184:187], 0
	v_mfma_f32_16x16x32_bf16 v[108:111], v[168:171], v[192:195], 0
	v_mfma_f32_16x16x32_bf16 v[100:103], v[176:179], v[192:195], 0
	v_mfma_f32_16x16x32_bf16 v[92:95], v[168:171], v[208:211], 0
	v_mfma_f32_16x16x32_bf16 v[84:87], v[176:179], v[208:211], 0
	v_mfma_f32_16x16x32_bf16 v[76:79], v[168:171], v[218:221], 0
	v_mfma_f32_16x16x32_bf16 v[68:71], v[176:179], v[218:221], 0
	v_mfma_f32_16x16x32_bf16 v[124:127], v[172:175], v[188:191], v[124:127]
	v_mfma_f32_16x16x32_bf16 v[116:119], v[180:183], v[188:191], v[116:119]
	v_mfma_f32_16x16x32_bf16 v[108:111], v[172:175], v[196:199], v[108:111]
	v_mfma_f32_16x16x32_bf16 v[100:103], v[180:183], v[196:199], v[100:103]
	v_mfma_f32_16x16x32_bf16 v[92:95], v[172:175], v[212:215], v[92:95]
	v_mfma_f32_16x16x32_bf16 v[84:87], v[180:183], v[212:215], v[84:87]
	v_mfma_f32_16x16x32_bf16 v[76:79], v[172:175], v[222:225], v[76:79]
	v_mfma_f32_16x16x32_bf16 v[68:71], v[180:183], v[222:225], v[68:71]
	s_setprio 0
	s_barrier
	s_mov_b32 m0, s13
	s_mov_b32 s6, s30
	s_mov_b32 s7, s31
	ds_read_b128 v[184:187], v140 offset:16384
	ds_read_b128 v[188:191], v140 offset:17408
	ds_read_b128 v[192:195], v140 offset:18432
	ds_read_b128 v[196:199], v140 offset:19456
	ds_read_b128 v[208:211], v140 offset:20480
	ds_read_b128 v[212:215], v140 offset:21504
	ds_read_b128 v[218:221], v140 offset:22528
	ds_read_b128 v[222:225], v140 offset:23552
	buffer_load_dwordx4 v134, s[4:7], s47 offen lds
	s_mov_b32 m0, s14
	s_add_i32 s49, s47, 0x80000
	buffer_load_dwordx4 v136, s[4:7], s47 offen lds
	s_mov_b32 m0, s15
	s_nop 0
	buffer_load_dwordx4 v134, s[4:7], s49 offen lds
	s_mov_b32 m0, s16
	s_nop 0
	buffer_load_dwordx4 v136, s[4:7], s49 offen lds
	s_mov_b32 m0, s12
	s_nop 0
	buffer_load_dwordx4 v2, s[28:31], s48 offen lds
	s_mov_b32 m0, s17
	s_nop 0
	buffer_load_dwordx4 v135, s[28:31], s48 offen lds
	s_waitcnt vmcnt(8)
	s_waitcnt lgkmcnt(0)
	s_barrier
; #define PG8_STAGE(bufoff, soff, voff) do { _Pragma("unroll") for (int _i = 0; _i < 2; ++_i) \
;         __builtin_amdgcn_raw_ptr_buffer_load_lds(PG8_RS_##voff, (PG8_LAS void*)(lds + (bufoff) + ldsw + _i * 8192), 16, (voff)[_i], (soff), 0, 0); } while (0)
; #define PG8_LDA(dst, b, h) do { _Pragma("unroll") for (int m = 0; m < 4; ++m) _Pragma("unroll") for (int k = 0; k < 2; ++k) dst[m][k] = *(const PG8_LAS bf16x8*)(lds + PG8_SA(b, h) + aoff + m * 2048 + k * 1024); } while (0)
; #define PG8_LDB(dst, b, h) do { _Pragma("unroll") for (int n = 0; n < 2; ++n) _Pragma("unroll") for (int k = 0; k < 2; ++k) dst[n][k] = *(const PG8_LAS bf16x8*)(lds + PG8_SB(b, h) + boff + n * 2048 + k * 1024); } while (0)
; #define PG8_MMA(ai, bj, At, Bt) do { __builtin_amdgcn_s_setprio(1); _Pragma("unroll") for (int m = 0; m < 4; ++m) _Pragma("unroll") for (int n = 0; n < 2; ++n) _Pragma("unroll") for (int k = 0; k < 2; ++k) \
;         acc[ai][bj][m][n] = __builtin_amdgcn_mfma_f32_16x16x32_bf16(Bt[n][k], At[m][k], acc[ai][bj][m][n], 0, 0, 0); __builtin_amdgcn_s_setprio(0); } while (0)
; #define PG8_WAIT_V(n) asm volatile("s_waitcnt vmcnt(" #n ")" ::: "memory")
; #define PG8_WAIT_L(n) asm volatile("s_waitcnt lgkmcnt(" #n ")" ::: "memory")
; #define PG8_BAR __builtin_amdgcn_s_barrier()
; #define PG8_SCHED __builtin_amdgcn_sched_barrier(0)
; template <class Epi, class Sched, bool ALIGN_EPI = false, bool SP2 = false>
; __device__ __forceinline__ void gemm_phase(PG8_LAS unsigned char* lds, const Gemm g, const Sched& S, const Epi& E) {
;     ...
;             PG8_WAIT_V(8); PG8_WAIT_L(0); PG8_BAR; PG8_MMA(1, 0, At, B0); PG8_MMA(1, 1, At, B1); PG8_BAR; PG8_SCHED;
;             PG8_LDB(B0, 1, 0); PG8_LDB(B1, 1, 1); PG8_SCHED; PG8_LDA(At, 1, 0); PG8_STAGE(PG8_SA(0, 1), a2 + hstep, voffA);
;             PG8_WAIT_V(8); PG8_WAIT_L(0); PG8_BAR; PG8_MMA(0, 0, At, B0); PG8_MMA(0, 1, At, B1); PG8_BAR; PG8_SCHED;
	s_setprio 1
	s_waitcnt lgkmcnt(7)
	v_mfma_f32_16x16x32_bf16 v[64:67], v[142:145], v[184:187], 0
	v_mfma_f32_16x16x32_bf16 v[60:63], v[150:153], v[184:187], 0
	s_waitcnt lgkmcnt(5)
	v_mfma_f32_16x16x32_bf16 v[48:51], v[142:145], v[192:195], 0
	v_mfma_f32_16x16x32_bf16 v[44:47], v[150:153], v[192:195], 0
	s_waitcnt lgkmcnt(3)
	v_mfma_f32_16x16x32_bf16 v[32:35], v[142:145], v[208:211], 0
	v_mfma_f32_16x16x32_bf16 v[28:31], v[150:153], v[208:211], 0
	s_waitcnt lgkmcnt(1)
	v_mfma_f32_16x16x32_bf16 v[16:19], v[142:145], v[218:221], 0
	v_mfma_f32_16x16x32_bf16 v[12:15], v[150:153], v[218:221], 0
	v_mfma_f32_16x16x32_bf16 v[64:67], v[146:149], v[188:191], v[64:67]
	v_mfma_f32_16x16x32_bf16 v[60:63], v[154:157], v[188:191], v[60:63]
	v_mfma_f32_16x16x32_bf16 v[48:51], v[146:149], v[196:199], v[48:51]
	v_mfma_f32_16x16x32_bf16 v[44:47], v[154:157], v[196:199], v[44:47]
	v_mfma_f32_16x16x32_bf16 v[32:35], v[146:149], v[212:215], v[32:35]
	v_mfma_f32_16x16x32_bf16 v[28:31], v[154:157], v[212:215], v[28:31]
	s_waitcnt lgkmcnt(0)
	v_mfma_f32_16x16x32_bf16 v[16:19], v[146:149], v[222:225], v[16:19]
	v_mfma_f32_16x16x32_bf16 v[12:15], v[154:157], v[222:225], v[12:15]
	s_setprio 0
	s_setprio 1
	v_mfma_f32_16x16x32_bf16 v[56:59], v[168:171], v[184:187], 0
	v_mfma_f32_16x16x32_bf16 v[52:55], v[176:179], v[184:187], 0
	v_mfma_f32_16x16x32_bf16 v[40:43], v[168:171], v[192:195], 0
	v_mfma_f32_16x16x32_bf16 v[36:39], v[176:179], v[192:195], 0
	v_mfma_f32_16x16x32_bf16 v[24:27], v[168:171], v[208:211], 0
	v_mfma_f32_16x16x32_bf16 v[20:23], v[176:179], v[208:211], 0
	v_mfma_f32_16x16x32_bf16 v[8:11], v[168:171], v[218:221], 0
	v_mfma_f32_16x16x32_bf16 v[4:7], v[176:179], v[218:221], 0
	v_mfma_f32_16x16x32_bf16 v[56:59], v[172:175], v[188:191], v[56:59]
	v_mfma_f32_16x16x32_bf16 v[52:55], v[180:183], v[188:191], v[52:55]
	v_mfma_f32_16x16x32_bf16 v[40:43], v[172:175], v[196:199], v[40:43]
	v_mfma_f32_16x16x32_bf16 v[36:39], v[180:183], v[196:199], v[36:39]
	v_mfma_f32_16x16x32_bf16 v[24:27], v[172:175], v[212:215], v[24:27]
	v_mfma_f32_16x16x32_bf16 v[20:23], v[180:183], v[212:215], v[20:23]
	v_mfma_f32_16x16x32_bf16 v[8:11], v[172:175], v[222:225], v[8:11]
	v_mfma_f32_16x16x32_bf16 v[4:7], v[180:183], v[222:225], v[4:7]
	s_setprio 0
	s_barrier
	v_add_u32_e32 v132, 0x18000, v139
	ds_read_b128 v[142:145], v132
	ds_read_b128 v[146:149], v132 offset:1024
	ds_read_b128 v[150:153], v132 offset:2048
	ds_read_b128 v[154:157], v132 offset:3072
	v_add_u32_e32 v132, 0x1c000, v139
	ds_read_b128 v[168:171], v132
	ds_read_b128 v[172:175], v132 offset:1024
	ds_read_b128 v[176:179], v132 offset:2048
	ds_read_b128 v[180:183], v132 offset:3072
	s_add_i32 s48, s48, 0x80000
	s_mov_b32 m0, s18
	ds_read_b128 v[184:187], v140 offset:32768
	ds_read_b128 v[188:191], v140 offset:33792
	ds_read_b128 v[192:195], v140 offset:34816
	ds_read_b128 v[196:199], v140 offset:35840
	ds_read_b128 v[208:211], v140 offset:36864
	ds_read_b128 v[212:215], v140 offset:37888
	ds_read_b128 v[218:221], v140 offset:38912
	ds_read_b128 v[222:225], v140 offset:39936
	buffer_load_dwordx4 v2, s[28:31], s48 offen lds
	s_mov_b32 m0, s19
	s_nop 0
	buffer_load_dwordx4 v135, s[28:31], s48 offen lds
	s_waitcnt vmcnt(8)
	s_waitcnt lgkmcnt(0)
	s_barrier
	s_setprio 1
	s_waitcnt lgkmcnt(7)
	v_mfma_f32_16x16x32_bf16 v[128:131], v[142:145], v[184:187], v[128:131]
	v_mfma_f32_16x16x32_bf16 v[120:123], v[150:153], v[184:187], v[120:123]
	s_waitcnt lgkmcnt(5)
	v_mfma_f32_16x16x32_bf16 v[112:115], v[142:145], v[192:195], v[112:115]
	v_mfma_f32_16x16x32_bf16 v[104:107], v[150:153], v[192:195], v[104:107]
	s_waitcnt lgkmcnt(3)
	v_mfma_f32_16x16x32_bf16 v[96:99], v[142:145], v[208:211], v[96:99]
	v_mfma_f32_16x16x32_bf16 v[88:91], v[150:153], v[208:211], v[88:91]
	s_waitcnt lgkmcnt(1)
	v_mfma_f32_16x16x32_bf16 v[80:83], v[142:145], v[218:221], v[80:83]
	v_mfma_f32_16x16x32_bf16 v[72:75], v[150:153], v[218:221], v[72:75]
	v_mfma_f32_16x16x32_bf16 v[128:131], v[146:149], v[188:191], v[128:131]
	v_mfma_f32_16x16x32_bf16 v[120:123], v[154:157], v[188:191], v[120:123]
	v_mfma_f32_16x16x32_bf16 v[112:115], v[146:149], v[196:199], v[112:115]
	v_mfma_f32_16x16x32_bf16 v[104:107], v[154:157], v[196:199], v[104:107]
	v_mfma_f32_16x16x32_bf16 v[96:99], v[146:149], v[212:215], v[96:99]
	v_mfma_f32_16x16x32_bf16 v[88:91], v[154:157], v[212:215], v[88:91]
	s_waitcnt lgkmcnt(0)
	v_mfma_f32_16x16x32_bf16 v[80:83], v[146:149], v[222:225], v[80:83]
	v_mfma_f32_16x16x32_bf16 v[72:75], v[154:157], v[222:225], v[72:75]
	s_setprio 0
	s_setprio 1
	v_mfma_f32_16x16x32_bf16 v[124:127], v[168:171], v[184:187], v[124:127]
	v_mfma_f32_16x16x32_bf16 v[116:119], v[176:179], v[184:187], v[116:119]
	v_mfma_f32_16x16x32_bf16 v[108:111], v[168:171], v[192:195], v[108:111]
	v_mfma_f32_16x16x32_bf16 v[100:103], v[176:179], v[192:195], v[100:103]
	v_mfma_f32_16x16x32_bf16 v[92:95], v[168:171], v[208:211], v[92:95]
	v_mfma_f32_16x16x32_bf16 v[84:87], v[176:179], v[208:211], v[84:87]
	v_mfma_f32_16x16x32_bf16 v[76:79], v[168:171], v[218:221], v[76:79]
	v_mfma_f32_16x16x32_bf16 v[68:71], v[176:179], v[218:221], v[68:71]
	v_mfma_f32_16x16x32_bf16 v[124:127], v[172:175], v[188:191], v[124:127]
	v_mfma_f32_16x16x32_bf16 v[116:119], v[180:183], v[188:191], v[116:119]
	v_mfma_f32_16x16x32_bf16 v[108:111], v[172:175], v[196:199], v[108:111]
	v_mfma_f32_16x16x32_bf16 v[100:103], v[180:183], v[196:199], v[100:103]
	v_mfma_f32_16x16x32_bf16 v[92:95], v[172:175], v[212:215], v[92:95]
	v_mfma_f32_16x16x32_bf16 v[84:87], v[180:183], v[212:215], v[84:87]
	v_mfma_f32_16x16x32_bf16 v[76:79], v[172:175], v[222:225], v[76:79]
	v_mfma_f32_16x16x32_bf16 v[68:71], v[180:183], v[222:225], v[68:71]
	s_setprio 0
	s_barrier
; #define PG8_STAGE(bufoff, soff, voff) do { _Pragma("unroll") for (int _i = 0; _i < 2; ++_i) \
;         __builtin_amdgcn_raw_ptr_buffer_load_lds(PG8_RS_##voff, (PG8_LAS void*)(lds + (bufoff) + ldsw + _i * 8192), 16, (voff)[_i], (soff), 0, 0); } while (0)
; #define PG8_LDA(dst, b, h) do { _Pragma("unroll") for (int m = 0; m < 4; ++m) _Pragma("unroll") for (int k = 0; k < 2; ++k) dst[m][k] = *(const PG8_LAS bf16x8*)(lds + PG8_SA(b, h) + aoff + m * 2048 + k * 1024); } while (0)
; #define PG8_MMA(ai, bj, At, Bt) do { __builtin_amdgcn_s_setprio(1); _Pragma("unroll") for (int m = 0; m < 4; ++m) _Pragma("unroll") for (int n = 0; n < 2; ++n) _Pragma("unroll") for (int k = 0; k < 2; ++k) \
;         acc[ai][bj][m][n] = __builtin_amdgcn_mfma_f32_16x16x32_bf16(Bt[n][k], At[m][k], acc[ai][bj][m][n], 0, 0, 0); __builtin_amdgcn_s_setprio(0); } while (0)
; #define PG8_WAIT_V(n) asm volatile("s_waitcnt vmcnt(" #n ")" ::: "memory")
; #define PG8_WAIT_L(n) asm volatile("s_waitcnt lgkmcnt(" #n ")" ::: "memory")
; #define PG8_BAR __builtin_amdgcn_s_barrier()
; #define PG8_SCHED __builtin_amdgcn_sched_barrier(0)
; template <class Epi, class Sched, bool ALIGN_EPI = false, bool SP2 = false>
; __device__ __forceinline__ void gemm_phase(PG8_LAS unsigned char* lds, const Gemm g, const Sched& S, const Epi& E) {
;     ...
;             PG8_LDA(At, 1, 1); PG8_STAGE(PG8_SB(1, 0), b3, voffB); PG8_STAGE(PG8_SB(1, 1), b3 + hstep, voffB); PG8_STAGE(PG8_SA(1, 0), a3, voffA);
;             PG8_WAIT_V(8); PG8_WAIT_L(0); PG8_BAR; PG8_MMA(1, 0, At, B0); PG8_MMA(1, 1, At, B1); PG8_BAR; PG8_SCHED;
	s_mov_b32 m0, s21
	s_or_b32 s48, s47, 0x80
	ds_read_b128 v[184:187], v140 offset:49152
	ds_read_b128 v[188:191], v140 offset:50176
	ds_read_b128 v[192:195], v140 offset:51200
	ds_read_b128 v[196:199], v140 offset:52224
	ds_read_b128 v[208:211], v140 offset:53248
	ds_read_b128 v[212:215], v140 offset:54272
	ds_read_b128 v[218:221], v140 offset:55296
	ds_read_b128 v[222:225], v140 offset:56320
	buffer_load_dwordx4 v134, s[4:7], s48 offen lds
	s_mov_b32 m0, s22
	s_add_i32 s47, s47, 0x80080
	buffer_load_dwordx4 v136, s[4:7], s48 offen lds
	s_mov_b32 m0, s25
	s_nop 0
	buffer_load_dwordx4 v134, s[4:7], s47 offen lds
	s_mov_b32 m0, s26
	s_nop 0
	buffer_load_dwordx4 v136, s[4:7], s47 offen lds
	s_mov_b32 m0, s23
	s_nop 0
	buffer_load_dwordx4 v2, s[28:31], s46 offen lds
	s_mov_b32 m0, s24
	s_nop 0
	buffer_load_dwordx4 v135, s[28:31], s46 offen lds
	s_waitcnt vmcnt(8)
	s_waitcnt lgkmcnt(0)
	s_barrier
	s_setprio 1
	s_waitcnt lgkmcnt(7)
	v_mfma_f32_16x16x32_bf16 v[64:67], v[142:145], v[184:187], v[64:67]
	v_mfma_f32_16x16x32_bf16 v[60:63], v[150:153], v[184:187], v[60:63]
	s_waitcnt lgkmcnt(5)
	v_mfma_f32_16x16x32_bf16 v[48:51], v[142:145], v[192:195], v[48:51]
	v_mfma_f32_16x16x32_bf16 v[44:47], v[150:153], v[192:195], v[44:47]
	s_waitcnt lgkmcnt(3)
	v_mfma_f32_16x16x32_bf16 v[32:35], v[142:145], v[208:211], v[32:35]
	v_mfma_f32_16x16x32_bf16 v[28:31], v[150:153], v[208:211], v[28:31]
	s_waitcnt lgkmcnt(1)
	v_mfma_f32_16x16x32_bf16 v[16:19], v[142:145], v[218:221], v[16:19]
	v_mfma_f32_16x16x32_bf16 v[12:15], v[150:153], v[218:221], v[12:15]
	v_mfma_f32_16x16x32_bf16 v[64:67], v[146:149], v[188:191], v[64:67]
	v_mfma_f32_16x16x32_bf16 v[60:63], v[154:157], v[188:191], v[60:63]
	v_mfma_f32_16x16x32_bf16 v[48:51], v[146:149], v[196:199], v[48:51]
	v_mfma_f32_16x16x32_bf16 v[44:47], v[154:157], v[196:199], v[44:47]
	v_mfma_f32_16x16x32_bf16 v[32:35], v[146:149], v[212:215], v[32:35]
	v_mfma_f32_16x16x32_bf16 v[28:31], v[154:157], v[212:215], v[28:31]
	s_waitcnt lgkmcnt(0)
	v_mfma_f32_16x16x32_bf16 v[16:19], v[146:149], v[222:225], v[16:19]
	v_mfma_f32_16x16x32_bf16 v[12:15], v[154:157], v[222:225], v[12:15]
	s_setprio 0
	s_setprio 1
	v_mfma_f32_16x16x32_bf16 v[56:59], v[168:171], v[184:187], v[56:59]
	v_mfma_f32_16x16x32_bf16 v[52:55], v[176:179], v[184:187], v[52:55]
	v_mfma_f32_16x16x32_bf16 v[40:43], v[168:171], v[192:195], v[40:43]
	v_mfma_f32_16x16x32_bf16 v[36:39], v[176:179], v[192:195], v[36:39]
	v_mfma_f32_16x16x32_bf16 v[24:27], v[168:171], v[208:211], v[24:27]
	v_mfma_f32_16x16x32_bf16 v[20:23], v[176:179], v[208:211], v[20:23]
	v_mfma_f32_16x16x32_bf16 v[8:11], v[168:171], v[218:221], v[8:11]
	v_mfma_f32_16x16x32_bf16 v[4:7], v[176:179], v[218:221], v[4:7]
	v_mfma_f32_16x16x32_bf16 v[56:59], v[172:175], v[188:191], v[56:59]
	v_mfma_f32_16x16x32_bf16 v[52:55], v[180:183], v[188:191], v[52:55]
	v_mfma_f32_16x16x32_bf16 v[40:43], v[172:175], v[196:199], v[40:43]
	v_mfma_f32_16x16x32_bf16 v[36:39], v[180:183], v[196:199], v[36:39]
	v_mfma_f32_16x16x32_bf16 v[24:27], v[172:175], v[212:215], v[24:27]
	v_mfma_f32_16x16x32_bf16 v[20:23], v[180:183], v[212:215], v[20:23]
	v_mfma_f32_16x16x32_bf16 v[8:11], v[172:175], v[222:225], v[8:11]
	v_mfma_f32_16x16x32_bf16 v[4:7], v[180:183], v[222:225], v[4:7]
	s_setprio 0
	s_barrier
	s_add_i32 s45, s45, 2
	s_addk_i32 s43, 0x100
	s_addk_i32 s44, 0x100
	s_cmp_gt_u32 s45, 29

; __device__ __forceinline__ unsigned cvt_pk_bf16(float lo, float hi) { unsigned r; asm volatile("v_cvt_pk_bf16_f32 %0, %1, %2" : "=v"(r) : "v"(lo), "v"(hi)); return r; }
;     __device__ __forceinline__ void operator()(const f32x4 (&acc)[2][2][4][2], const Unit& u, int wr, int wc, int fr, int fq) const {
;         const int row0 = u.pm * BM + wr * 64 + fr; int colt = u.pn * BM; bf16_t* base = O;
;         if (split_cols) { const int t = colt / split_cols; base += (size_t)t * split_stride; colt -= t * split_cols; }
;         if (u.ko) base += ko_stride;
;         const int col0 = colt + wc * 32 + 8 * fq;
; #pragma unroll
;         for (int ai = 0; ai < 2; ++ai)
; #pragma unroll
;             for (int m = 0; m < 4; ++m) { bf16_t* rowp = base + (size_t)(row0 + ai * HALF + m * 16) * ldc + col0;
; #pragma unroll
;                 for (int bj = 0; bj < 2; ++bj) { f32x4 v0 = acc[ai][bj][m][0], v1 = acc[ai][bj][m][1];
;                     if (ACT == 2) {
; #pragma unroll
;                         for (int e = 0; e < 4; ++e) { const float a = fmaxf(v0[e], 0.f), b = fmaxf(v1[e], 0.f); v0[e] = a * a; v1[e] = b * b; } }
;                     u32x4 w; w.x = cvt_pk_bf16(v0[0], v0[1]); w.y = cvt_pk_bf16(v0[2], v0[3]); w.z = cvt_pk_bf16(v1[0], v1[1]); w.w = cvt_pk_bf16(v1[2], v1[3]);
;                     *(u32x4*)(rowp + bj * HALF) = w; } }
; template <class Epi, class Sched, bool ALIGN_EPI = false, bool SP2 = false>
; __device__ __forceinline__ void gemm_phase(PG8_LAS unsigned char* lds, const Gemm g, const Sched& S, const Epi& E) {
;     ...
; #pragma unroll
;         for (int a = 0; a < 2; ++a)
; #pragma unroll
;             for (int b = 0; b < 2; ++b)
; #pragma unroll
;                 for (int m = 0; m < 4; ++m)
; #pragma unroll
;                     for (int n = 0; n < 2; ++n) { typedef double d2_t __attribute__((ext_vector_type(2))); d2_t z; double z0, z1;
;                         asm volatile("v_mov_b64 %0, 0" : "=v"(z0)); asm volatile("v_mov_b64 %0, 0" : "=v"(z1)); z.x = z0; z.y = z1; acc[a][b][m][n] = __builtin_bit_cast(f32x4, z); }
.LBB0_638:
	s_ashr_i32 s7, s40, 31
	s_lshr_b32 s7, s7, 30
	s_add_i32 s7, s40, s7
	s_lshl_b32 s7, s7, 8
	s_lshl_b32 s6, s40, 8
	s_and_b32 s7, s7, 0xfffffc00
	s_sub_i32 s6, s6, s7
	v_or_b32_e32 v132, s6, v138
	v_lshl_add_u32 v142, s39, 8, v137
	v_ashrrev_i32_e32 v133, 31, v132
	v_ashrrev_i32_e32 v143, 31, v142
	v_lshl_add_u64 v[144:145], v[132:133], 1, s[2:3]
	v_lshlrev_b64 v[132:133], 11, v[142:143]
	v_lshl_add_u64 v[132:133], v[144:145], 0, v[132:133]
	v_cvt_pk_bf16_f32 v128, v128, v129
	v_cvt_pk_bf16_f32 v129, v130, v131
	v_cvt_pk_bf16_f32 v130, v120, v121
	v_cvt_pk_bf16_f32 v131, v122, v123
	global_store_dwordx4 v[132:133], v[128:131], off
	v_cvt_pk_bf16_f32 v120, v124, v125
	v_cvt_pk_bf16_f32 v121, v126, v127
	v_cvt_pk_bf16_f32 v122, v116, v117
	v_or_b32_e32 v116, 16, v142
	v_ashrrev_i32_e32 v117, 31, v116
	v_lshlrev_b64 v[116:117], 11, v[116:117]
	v_lshl_add_u64 v[116:117], v[144:145], 0, v[116:117]
	v_cvt_pk_bf16_f32 v123, v118, v119
	global_store_dwordx4 v[132:133], v[120:123], off offset:256
	v_cvt_pk_bf16_f32 v112, v112, v113
	v_cvt_pk_bf16_f32 v113, v114, v115
	v_cvt_pk_bf16_f32 v114, v104, v105
	v_cvt_pk_bf16_f32 v115, v106, v107
	global_store_dwordx4 v[116:117], v[112:115], off
	v_cvt_pk_bf16_f32 v104, v108, v109
	v_cvt_pk_bf16_f32 v105, v110, v111
	v_cvt_pk_bf16_f32 v106, v100, v101
	v_or_b32_e32 v100, 32, v142
	v_ashrrev_i32_e32 v101, 31, v100
	v_lshlrev_b64 v[100:101], 11, v[100:101]
	v_lshl_add_u64 v[100:101], v[144:145], 0, v[100:101]
	v_cvt_pk_bf16_f32 v107, v102, v103
	global_store_dwordx4 v[116:117], v[104:107], off offset:256
	v_cvt_pk_bf16_f32 v96, v96, v97
	v_cvt_pk_bf16_f32 v97, v98, v99
	v_cvt_pk_bf16_f32 v98, v88, v89
	v_cvt_pk_bf16_f32 v99, v90, v91
	global_store_dwordx4 v[100:101], v[96:99], off
	v_cvt_pk_bf16_f32 v88, v92, v93
	v_cvt_pk_bf16_f32 v89, v94, v95
	v_cvt_pk_bf16_f32 v90, v84, v85
	v_or_b32_e32 v84, 48, v142
	v_ashrrev_i32_e32 v85, 31, v84
	v_lshlrev_b64 v[84:85], 11, v[84:85]
	v_lshl_add_u64 v[84:85], v[144:145], 0, v[84:85]
	s_mov_b64 s[6:7], 0x40000
	v_cvt_pk_bf16_f32 v91, v86, v87
	global_store_dwordx4 v[100:101], v[88:91], off offset:256
	v_cvt_pk_bf16_f32 v80, v80, v81
	v_cvt_pk_bf16_f32 v81, v82, v83
	v_cvt_pk_bf16_f32 v82, v72, v73
	v_cvt_pk_bf16_f32 v83, v74, v75
	global_store_dwordx4 v[84:85], v[80:83], off
	v_cvt_pk_bf16_f32 v72, v76, v77
	v_cvt_pk_bf16_f32 v73, v78, v79
	v_cvt_pk_bf16_f32 v74, v68, v69
	v_lshl_add_u64 v[68:69], v[132:133], 0, s[6:7]
	s_mov_b32 s6, 0x40000
	v_cvt_pk_bf16_f32 v75, v70, v71
	global_store_dwordx4 v[84:85], v[72:75], off offset:256
	v_cvt_pk_bf16_f32 v64, v64, v65
	v_cvt_pk_bf16_f32 v65, v66, v67
	v_cvt_pk_bf16_f32 v66, v60, v61
	v_add_co_u32_e32 v60, vcc, s6, v132
	s_mov_b64 s[6:7], 0x48000
	s_nop 0
	v_addc_co_u32_e32 v61, vcc, 0, v133, vcc
	v_cvt_pk_bf16_f32 v67, v62, v63
	global_store_dwordx4 v[60:61], v[64:67], off
	v_cvt_pk_bf16_f32 v56, v56, v57
	v_cvt_pk_bf16_f32 v57, v58, v59
	v_cvt_pk_bf16_f32 v58, v52, v53
	v_lshl_add_u64 v[52:53], v[132:133], 0, s[6:7]
	s_mov_b32 s6, 0x48000
	v_cvt_pk_bf16_f32 v59, v54, v55
	global_store_dwordx4 v[68:69], v[56:59], off offset:256
	v_cvt_pk_bf16_f32 v48, v48, v49
	v_cvt_pk_bf16_f32 v49, v50, v51
	v_cvt_pk_bf16_f32 v50, v44, v45
	v_add_co_u32_e32 v44, vcc, s6, v132
	s_mov_b64 s[6:7], 0x50000
	s_nop 0
	v_addc_co_u32_e32 v45, vcc, 0, v133, vcc
	v_cvt_pk_bf16_f32 v51, v46, v47
	global_store_dwordx4 v[44:45], v[48:51], off
	v_cvt_pk_bf16_f32 v40, v40, v41
	v_cvt_pk_bf16_f32 v41, v42, v43
	v_cvt_pk_bf16_f32 v42, v36, v37
	v_lshl_add_u64 v[36:37], v[132:133], 0, s[6:7]
	s_mov_b32 s6, 0x50000
	v_cvt_pk_bf16_f32 v43, v38, v39
	global_store_dwordx4 v[52:53], v[40:43], off offset:256
	v_cvt_pk_bf16_f32 v32, v32, v33
	v_cvt_pk_bf16_f32 v33, v34, v35
	v_cvt_pk_bf16_f32 v34, v28, v29
	v_add_co_u32_e32 v28, vcc, s6, v132
	s_mov_b64 s[6:7], 0x58000
	s_nop 0
	v_addc_co_u32_e32 v29, vcc, 0, v133, vcc
	v_cvt_pk_bf16_f32 v35, v30, v31
	global_store_dwordx4 v[28:29], v[32:35], off
	v_cvt_pk_bf16_f32 v24, v24, v25
	v_cvt_pk_bf16_f32 v25, v26, v27
	v_cvt_pk_bf16_f32 v26, v20, v21
	v_lshl_add_u64 v[20:21], v[132:133], 0, s[6:7]
	s_mov_b32 s6, 0x58000
	v_cvt_pk_bf16_f32 v27, v22, v23
	global_store_dwordx4 v[36:37], v[24:27], off offset:256
	v_cvt_pk_bf16_f32 v16, v16, v17
	v_cvt_pk_bf16_f32 v17, v18, v19
	v_cvt_pk_bf16_f32 v18, v12, v13
	v_add_co_u32_e32 v12, vcc, s6, v132
	v_cvt_pk_bf16_f32 v19, v14, v15
	s_mov_b64 s[6:7], -1
	s_nop 0
	v_addc_co_u32_e32 v13, vcc, 0, v133, vcc
	global_store_dwordx4 v[12:13], v[16:19], off
	v_cvt_pk_bf16_f32 v8, v8, v9
	v_cvt_pk_bf16_f32 v9, v10, v11
	v_cvt_pk_bf16_f32 v10, v4, v5
	v_cvt_pk_bf16_f32 v11, v6, v7
	s_andn2_b64 vcc, exec, s[10:11]
	v_readlane_b32 s46, v254, 18
	v_readlane_b32 s45, v254, 43
	global_store_dwordx4 v[20:21], v[8:11], off offset:256
	v_readlane_b32 s47, v254, 19
	s_cbranch_vccnz .LBB0_631
	s_andn2_b64 vcc, exec, s[0:1]
	s_cbranch_vccnz .LBB0_630
	s_barrier
	s_branch .LBB0_630

; #define PG8_STAGE(bufoff, soff, voff) do { _Pragma("unroll") for (int _i = 0; _i < 2; ++_i) \
;         __builtin_amdgcn_raw_ptr_buffer_load_lds(PG8_RS_##voff, (PG8_LAS void*)(lds + (bufoff) + ldsw + _i * 8192), 16, (voff)[_i], (soff), 0, 0); } while (0)
; #define PG8_LDA(dst, b, h) do { _Pragma("unroll") for (int m = 0; m < 4; ++m) _Pragma("unroll") for (int k = 0; k < 2; ++k) dst[m][k] = *(const PG8_LAS bf16x8*)(lds + PG8_SA(b, h) + aoff + m * 2048 + k * 1024); } while (0)
; #define PG8_LDB(dst, b, h) do { _Pragma("unroll") for (int n = 0; n < 2; ++n) _Pragma("unroll") for (int k = 0; k < 2; ++k) dst[n][k] = *(const PG8_LAS bf16x8*)(lds + PG8_SB(b, h) + boff + n * 2048 + k * 1024); } while (0)
; #define PG8_WAIT_V(n) asm volatile("s_waitcnt vmcnt(" #n ")" ::: "memory")
; #define PG8_WAIT_L(n) asm volatile("s_waitcnt lgkmcnt(" #n ")" ::: "memory")
; #define PG8_BAR __builtin_amdgcn_s_barrier()
; #define PG8_SCHED __builtin_amdgcn_sched_barrier(0)
; template <class Epi, class Sched, bool ALIGN_EPI = false, bool SP2 = false>
; __device__ __forceinline__ void gemm_phase(PG8_LAS unsigned char* lds, const Gemm g, const Sched& S, const Epi& E) {
;     ...
;         const bool has_next = S.next(ui + 1, nxt);
;         const unsigned nA = has_next ? (unsigned)nxt.pm * tstep + (unsigned)nxt.ko * 2u : cA, nB = has_next ? (unsigned)nxt.pn * tstep + (unsigned)nxt.ko * 2u : cB;
;         for (int t = 0; t < nt; t += 2) {
;             const bool last = (t == nt - 2);
;             const unsigned a1 = cA + (unsigned)(t + 1) * kstep;
;             const unsigned a2 = last ? nA : cA + (unsigned)(t + 2) * kstep, b2 = last ? nB : cB + (unsigned)(t + 2) * kstep;
;             const unsigned a3 = a2 + kstep, b3 = b2 + kstep;
;             if (last && has_next) S.a_ready(nxt);
;             if constexpr (SP2) {
;             PG8_LDB(B0, 0, 0); PG8_LDB(B1, 0, 1); PG8_SCHED; PG8_LDA(At, 0, 0); PG8_STAGE(PG8_SA(1, 1), a1 + hstep, voffA);
;             PG8_WAIT_V(8); PG8_WAIT_L(0); PG8_BAR; PG8_MMA(0, 0, At, B0); PG8_MMA(0, 1, At, B1); PG8_BAR; PG8_SCHED;
;             PG8_LDA(At, 0, 1); PG8_STAGE(PG8_SB(0, 0), b2, voffB); PG8_STAGE(PG8_SB(0, 1), b2 + hstep, voffB); PG8_STAGE(PG8_SA(0, 0), a2, voffA);
;             PG8_WAIT_V(8); PG8_WAIT_L(0); PG8_BAR; PG8_MMA(1, 0, At, B0); PG8_MMA(1, 1, At, B1); PG8_BAR; PG8_SCHED;
.LBB0_778:
	s_lshl_b32 s44, s43, 18
	s_and_b64 s[0:1], s[40:41], exec
	s_cselect_b32 s0, s44, s7
	s_lshl_b32 s45, s42, 18
	s_and_b64 s[48:49], s[40:41], exec
	s_cselect_b32 s1, s45, s6
	s_add_i32 s48, s7, 0x20080
	s_add_i32 s49, s6, 0x100
	s_mov_b32 s50, -2
	v_add_u32_e32 v144, 0x10000, v187
	v_add_u32_e32 v168, 0x14000, v187
	ds_read_b128 v[132:135], v144
	ds_read_b128 v[136:139], v144 offset:1024
	ds_read_b128 v[140:143], v144 offset:2048
	ds_read_b128 v[144:147], v144 offset:3072
	ds_read_b128 v[148:151], v168
	ds_read_b128 v[152:155], v168 offset:1024
	ds_read_b128 v[156:159], v168 offset:2048
	ds_read_b128 v[168:171], v168 offset:3072
	s_add_i32 s6, s48, 0xfffe0080
	s_cmp_eq_u32 s50, 4
	s_cselect_b32 s53, s0, s6
	s_cselect_b32 s52, s1, s49
	s_or_b32 s51, s53, 0x80
	s_mov_b32 m0, s35
	ds_read_b128 v[172:175], v188
	ds_read_b128 v[176:179], v188 offset:1024
	ds_read_b128 v[190:193], v188 offset:2048
	ds_read_b128 v[194:197], v188 offset:3072
	ds_read_b128 v[208:211], v188 offset:4096
	ds_read_b128 v[212:215], v188 offset:5120
	ds_read_b128 v[218:221], v188 offset:6144
	ds_read_b128 v[222:225], v188 offset:7168
	buffer_load_dwordx4 v2, s[28:31], s48 offen lds
	s_mov_b32 m0, s36
	s_nop 0
	buffer_load_dwordx4 v181, s[28:31], s48 offen lds
	s_waitcnt vmcnt(8)
	s_waitcnt lgkmcnt(0)
	s_barrier
	s_setprio 1
	s_waitcnt lgkmcnt(7)
	v_mfma_f32_16x16x32_bf16 v[128:131], v[132:135], v[172:175], 0
	v_mfma_f32_16x16x32_bf16 v[124:127], v[140:143], v[172:175], 0
	s_waitcnt lgkmcnt(5)
	v_mfma_f32_16x16x32_bf16 v[112:115], v[132:135], v[190:193], 0
	v_mfma_f32_16x16x32_bf16 v[108:111], v[140:143], v[190:193], 0
	s_waitcnt lgkmcnt(3)
	v_mfma_f32_16x16x32_bf16 v[96:99], v[132:135], v[208:211], 0
	v_mfma_f32_16x16x32_bf16 v[92:95], v[140:143], v[208:211], 0
	s_waitcnt lgkmcnt(1)
	v_mfma_f32_16x16x32_bf16 v[80:83], v[132:135], v[218:221], 0
	v_mfma_f32_16x16x32_bf16 v[76:79], v[140:143], v[218:221], 0
	v_mfma_f32_16x16x32_bf16 v[128:131], v[136:139], v[176:179], v[128:131]
	v_mfma_f32_16x16x32_bf16 v[124:127], v[144:147], v[176:179], v[124:127]
	v_mfma_f32_16x16x32_bf16 v[112:115], v[136:139], v[194:197], v[112:115]
	v_mfma_f32_16x16x32_bf16 v[108:111], v[144:147], v[194:197], v[108:111]
	v_mfma_f32_16x16x32_bf16 v[96:99], v[136:139], v[212:215], v[96:99]
	v_mfma_f32_16x16x32_bf16 v[92:95], v[144:147], v[212:215], v[92:95]
	s_waitcnt lgkmcnt(0)
	v_mfma_f32_16x16x32_bf16 v[80:83], v[136:139], v[222:225], v[80:83]
	v_mfma_f32_16x16x32_bf16 v[76:79], v[144:147], v[222:225], v[76:79]
	s_setprio 0
	s_setprio 1
	v_mfma_f32_16x16x32_bf16 v[120:123], v[148:151], v[172:175], 0
	v_mfma_f32_16x16x32_bf16 v[116:119], v[156:159], v[172:175], 0
	v_mfma_f32_16x16x32_bf16 v[104:107], v[148:151], v[190:193], 0
	v_mfma_f32_16x16x32_bf16 v[100:103], v[156:159], v[190:193], 0
	v_mfma_f32_16x16x32_bf16 v[88:91], v[148:151], v[208:211], 0
	v_mfma_f32_16x16x32_bf16 v[84:87], v[156:159], v[208:211], 0
	v_mfma_f32_16x16x32_bf16 v[72:75], v[148:151], v[218:221], 0
	v_mfma_f32_16x16x32_bf16 v[68:71], v[156:159], v[218:221], 0
	v_mfma_f32_16x16x32_bf16 v[120:123], v[152:155], v[176:179], v[120:123]
	v_mfma_f32_16x16x32_bf16 v[116:119], v[168:171], v[176:179], v[116:119]
	v_mfma_f32_16x16x32_bf16 v[104:107], v[152:155], v[194:197], v[104:107]
	v_mfma_f32_16x16x32_bf16 v[100:103], v[168:171], v[194:197], v[100:103]
	v_mfma_f32_16x16x32_bf16 v[88:91], v[152:155], v[212:215], v[88:91]
	v_mfma_f32_16x16x32_bf16 v[84:87], v[168:171], v[212:215], v[84:87]
	v_mfma_f32_16x16x32_bf16 v[72:75], v[152:155], v[222:225], v[72:75]
	v_mfma_f32_16x16x32_bf16 v[68:71], v[168:171], v[222:225], v[68:71]
	s_setprio 0
	s_barrier
	s_mov_b32 m0, s15
	s_mov_b32 s6, s30
	s_mov_b32 s7, s31
	ds_read_b128 v[172:175], v188 offset:16384
	ds_read_b128 v[176:179], v188 offset:17408
	ds_read_b128 v[190:193], v188 offset:18432
	ds_read_b128 v[194:197], v188 offset:19456
	ds_read_b128 v[208:211], v188 offset:20480
	ds_read_b128 v[212:215], v188 offset:21504
	ds_read_b128 v[218:221], v188 offset:22528
	ds_read_b128 v[222:225], v188 offset:23552
	buffer_load_dwordx4 v180, s[4:7], s52 offen lds
	s_mov_b32 m0, s16
	s_add_i32 s54, s52, 0x20000
	buffer_load_dwordx4 v182, s[4:7], s52 offen lds
	s_mov_b32 m0, s17
	s_nop 0
	buffer_load_dwordx4 v180, s[4:7], s54 offen lds
	s_mov_b32 m0, s18
	s_nop 0
	buffer_load_dwordx4 v182, s[4:7], s54 offen lds
	s_mov_b32 m0, s14
	s_nop 0
	buffer_load_dwordx4 v2, s[28:31], s53 offen lds
	s_mov_b32 m0, s19
	s_nop 0
	buffer_load_dwordx4 v181, s[28:31], s53 offen lds
	s_waitcnt vmcnt(8)
	s_waitcnt lgkmcnt(0)
	s_barrier
; #define PG8_STAGE(bufoff, soff, voff) do { _Pragma("unroll") for (int _i = 0; _i < 2; ++_i) \
;         __builtin_amdgcn_raw_ptr_buffer_load_lds(PG8_RS_##voff, (PG8_LAS void*)(lds + (bufoff) + ldsw + _i * 8192), 16, (voff)[_i], (soff), 0, 0); } while (0)
; #define PG8_LDA(dst, b, h) do { _Pragma("unroll") for (int m = 0; m < 4; ++m) _Pragma("unroll") for (int k = 0; k < 2; ++k) dst[m][k] = *(const PG8_LAS bf16x8*)(lds + PG8_SA(b, h) + aoff + m * 2048 + k * 1024); } while (0)
; #define PG8_LDB(dst, b, h) do { _Pragma("unroll") for (int n = 0; n < 2; ++n) _Pragma("unroll") for (int k = 0; k < 2; ++k) dst[n][k] = *(const PG8_LAS bf16x8*)(lds + PG8_SB(b, h) + boff + n * 2048 + k * 1024); } while (0)
; #define PG8_MMA(ai, bj, At, Bt) do { __builtin_amdgcn_s_setprio(1); _Pragma("unroll") for (int m = 0; m < 4; ++m) _Pragma("unroll") for (int n = 0; n < 2; ++n) _Pragma("unroll") for (int k = 0; k < 2; ++k) \
;         acc[ai][bj][m][n] = __builtin_amdgcn_mfma_f32_16x16x32_bf16(Bt[n][k], At[m][k], acc[ai][bj][m][n], 0, 0, 0); __builtin_amdgcn_s_setprio(0); } while (0)
; #define PG8_WAIT_V(n) asm volatile("s_waitcnt vmcnt(" #n ")" ::: "memory")
; #define PG8_WAIT_L(n) asm volatile("s_waitcnt lgkmcnt(" #n ")" ::: "memory")
; #define PG8_BAR __builtin_amdgcn_s_barrier()
; #define PG8_SCHED __builtin_amdgcn_sched_barrier(0)
; template <class Epi, class Sched, bool ALIGN_EPI = false, bool SP2 = false>
; __device__ __forceinline__ void gemm_phase(PG8_LAS unsigned char* lds, const Gemm g, const Sched& S, const Epi& E) {
;     ...
;             PG8_WAIT_V(8); PG8_WAIT_L(0); PG8_BAR; PG8_MMA(1, 0, At, B0); PG8_MMA(1, 1, At, B1); PG8_BAR; PG8_SCHED;
;             PG8_LDB(B0, 1, 0); PG8_LDB(B1, 1, 1); PG8_SCHED; PG8_LDA(At, 1, 0); PG8_STAGE(PG8_SA(0, 1), a2 + hstep, voffA);
;             PG8_WAIT_V(8); PG8_WAIT_L(0); PG8_BAR; PG8_MMA(0, 0, At, B0); PG8_MMA(0, 1, At, B1); PG8_BAR; PG8_SCHED;
	s_setprio 1
	s_waitcnt lgkmcnt(7)
	v_mfma_f32_16x16x32_bf16 v[64:67], v[132:135], v[172:175], 0
	v_mfma_f32_16x16x32_bf16 v[60:63], v[140:143], v[172:175], 0
	s_waitcnt lgkmcnt(5)
	v_mfma_f32_16x16x32_bf16 v[48:51], v[132:135], v[190:193], 0
	v_mfma_f32_16x16x32_bf16 v[44:47], v[140:143], v[190:193], 0
	s_waitcnt lgkmcnt(3)
	v_mfma_f32_16x16x32_bf16 v[32:35], v[132:135], v[208:211], 0
	v_mfma_f32_16x16x32_bf16 v[28:31], v[140:143], v[208:211], 0
	s_waitcnt lgkmcnt(1)
	v_mfma_f32_16x16x32_bf16 v[16:19], v[132:135], v[218:221], 0
	v_mfma_f32_16x16x32_bf16 v[12:15], v[140:143], v[218:221], 0
	v_mfma_f32_16x16x32_bf16 v[64:67], v[136:139], v[176:179], v[64:67]
	v_mfma_f32_16x16x32_bf16 v[60:63], v[144:147], v[176:179], v[60:63]
	v_mfma_f32_16x16x32_bf16 v[48:51], v[136:139], v[194:197], v[48:51]
	v_mfma_f32_16x16x32_bf16 v[44:47], v[144:147], v[194:197], v[44:47]
	v_mfma_f32_16x16x32_bf16 v[32:35], v[136:139], v[212:215], v[32:35]
	v_mfma_f32_16x16x32_bf16 v[28:31], v[144:147], v[212:215], v[28:31]
	s_waitcnt lgkmcnt(0)
	v_mfma_f32_16x16x32_bf16 v[16:19], v[136:139], v[222:225], v[16:19]
	v_mfma_f32_16x16x32_bf16 v[12:15], v[144:147], v[222:225], v[12:15]
	s_setprio 0
	s_setprio 1
	v_mfma_f32_16x16x32_bf16 v[56:59], v[148:151], v[172:175], 0
	v_mfma_f32_16x16x32_bf16 v[52:55], v[156:159], v[172:175], 0
	v_mfma_f32_16x16x32_bf16 v[40:43], v[148:151], v[190:193], 0
	v_mfma_f32_16x16x32_bf16 v[36:39], v[156:159], v[190:193], 0
	v_mfma_f32_16x16x32_bf16 v[24:27], v[148:151], v[208:211], 0
	v_mfma_f32_16x16x32_bf16 v[20:23], v[156:159], v[208:211], 0
	v_mfma_f32_16x16x32_bf16 v[8:11], v[148:151], v[218:221], 0
	v_mfma_f32_16x16x32_bf16 v[4:7], v[156:159], v[218:221], 0
	v_mfma_f32_16x16x32_bf16 v[56:59], v[152:155], v[176:179], v[56:59]
	v_mfma_f32_16x16x32_bf16 v[52:55], v[168:171], v[176:179], v[52:55]
	v_mfma_f32_16x16x32_bf16 v[40:43], v[152:155], v[194:197], v[40:43]
	v_mfma_f32_16x16x32_bf16 v[36:39], v[168:171], v[194:197], v[36:39]
	v_mfma_f32_16x16x32_bf16 v[24:27], v[152:155], v[212:215], v[24:27]
	v_mfma_f32_16x16x32_bf16 v[20:23], v[168:171], v[212:215], v[20:23]
	v_mfma_f32_16x16x32_bf16 v[8:11], v[152:155], v[222:225], v[8:11]
	v_mfma_f32_16x16x32_bf16 v[4:7], v[168:171], v[222:225], v[4:7]
	s_setprio 0
	s_barrier
	v_add_u32_e32 v144, 0x18000, v187
	v_add_u32_e32 v168, 0x1c000, v187
	ds_read_b128 v[132:135], v144
	ds_read_b128 v[136:139], v144 offset:1024
	ds_read_b128 v[140:143], v144 offset:2048
	ds_read_b128 v[144:147], v144 offset:3072
	ds_read_b128 v[148:151], v168
	ds_read_b128 v[152:155], v168 offset:1024
	ds_read_b128 v[156:159], v168 offset:2048
	ds_read_b128 v[168:171], v168 offset:3072
	s_add_i32 s53, s53, 0x20000
	s_mov_b32 m0, s21
	ds_read_b128 v[172:175], v188 offset:32768
	ds_read_b128 v[176:179], v188 offset:33792
	ds_read_b128 v[190:193], v188 offset:34816
	ds_read_b128 v[194:197], v188 offset:35840
	ds_read_b128 v[208:211], v188 offset:36864
	ds_read_b128 v[212:215], v188 offset:37888
	ds_read_b128 v[218:221], v188 offset:38912
	ds_read_b128 v[222:225], v188 offset:39936
	buffer_load_dwordx4 v2, s[28:31], s53 offen lds
	s_mov_b32 m0, s22
	s_nop 0
	buffer_load_dwordx4 v181, s[28:31], s53 offen lds
	s_waitcnt vmcnt(8)
	s_waitcnt lgkmcnt(0)
	s_barrier
	s_setprio 1
	s_waitcnt lgkmcnt(7)
	v_mfma_f32_16x16x32_bf16 v[128:131], v[132:135], v[172:175], v[128:131]
	v_mfma_f32_16x16x32_bf16 v[124:127], v[140:143], v[172:175], v[124:127]
	s_waitcnt lgkmcnt(5)
	v_mfma_f32_16x16x32_bf16 v[112:115], v[132:135], v[190:193], v[112:115]
	v_mfma_f32_16x16x32_bf16 v[108:111], v[140:143], v[190:193], v[108:111]
	s_waitcnt lgkmcnt(3)
	v_mfma_f32_16x16x32_bf16 v[96:99], v[132:135], v[208:211], v[96:99]
	v_mfma_f32_16x16x32_bf16 v[92:95], v[140:143], v[208:211], v[92:95]
	s_waitcnt lgkmcnt(1)
	v_mfma_f32_16x16x32_bf16 v[80:83], v[132:135], v[218:221], v[80:83]
	v_mfma_f32_16x16x32_bf16 v[76:79], v[140:143], v[218:221], v[76:79]
	v_mfma_f32_16x16x32_bf16 v[128:131], v[136:139], v[176:179], v[128:131]
	v_mfma_f32_16x16x32_bf16 v[124:127], v[144:147], v[176:179], v[124:127]
	v_mfma_f32_16x16x32_bf16 v[112:115], v[136:139], v[194:197], v[112:115]
	v_mfma_f32_16x16x32_bf16 v[108:111], v[144:147], v[194:197], v[108:111]
	v_mfma_f32_16x16x32_bf16 v[96:99], v[136:139], v[212:215], v[96:99]
	v_mfma_f32_16x16x32_bf16 v[92:95], v[144:147], v[212:215], v[92:95]
	s_waitcnt lgkmcnt(0)
	v_mfma_f32_16x16x32_bf16 v[80:83], v[136:139], v[222:225], v[80:83]
	v_mfma_f32_16x16x32_bf16 v[76:79], v[144:147], v[222:225], v[76:79]
	s_setprio 0
	s_setprio 1
	v_mfma_f32_16x16x32_bf16 v[120:123], v[148:151], v[172:175], v[120:123]
	v_mfma_f32_16x16x32_bf16 v[116:119], v[156:159], v[172:175], v[116:119]
	v_mfma_f32_16x16x32_bf16 v[104:107], v[148:151], v[190:193], v[104:107]
	v_mfma_f32_16x16x32_bf16 v[100:103], v[156:159], v[190:193], v[100:103]
	v_mfma_f32_16x16x32_bf16 v[88:91], v[148:151], v[208:211], v[88:91]
	v_mfma_f32_16x16x32_bf16 v[84:87], v[156:159], v[208:211], v[84:87]
	v_mfma_f32_16x16x32_bf16 v[72:75], v[148:151], v[218:221], v[72:75]
	v_mfma_f32_16x16x32_bf16 v[68:71], v[156:159], v[218:221], v[68:71]
	v_mfma_f32_16x16x32_bf16 v[120:123], v[152:155], v[176:179], v[120:123]
	v_mfma_f32_16x16x32_bf16 v[116:119], v[168:171], v[176:179], v[116:119]
	v_mfma_f32_16x16x32_bf16 v[104:107], v[152:155], v[194:197], v[104:107]
	v_mfma_f32_16x16x32_bf16 v[100:103], v[168:171], v[194:197], v[100:103]
	v_mfma_f32_16x16x32_bf16 v[88:91], v[152:155], v[212:215], v[88:91]
	v_mfma_f32_16x16x32_bf16 v[84:87], v[168:171], v[212:215], v[84:87]
	v_mfma_f32_16x16x32_bf16 v[72:75], v[152:155], v[222:225], v[72:75]
	v_mfma_f32_16x16x32_bf16 v[68:71], v[168:171], v[222:225], v[68:71]
	s_setprio 0
	s_barrier
; #define PG8_STAGE(bufoff, soff, voff) do { _Pragma("unroll") for (int _i = 0; _i < 2; ++_i) \
;         __builtin_amdgcn_raw_ptr_buffer_load_lds(PG8_RS_##voff, (PG8_LAS void*)(lds + (bufoff) + ldsw + _i * 8192), 16, (voff)[_i], (soff), 0, 0); } while (0)
; #define PG8_LDA(dst, b, h) do { _Pragma("unroll") for (int m = 0; m < 4; ++m) _Pragma("unroll") for (int k = 0; k < 2; ++k) dst[m][k] = *(const PG8_LAS bf16x8*)(lds + PG8_SA(b, h) + aoff + m * 2048 + k * 1024); } while (0)
; #define PG8_MMA(ai, bj, At, Bt) do { __builtin_amdgcn_s_setprio(1); _Pragma("unroll") for (int m = 0; m < 4; ++m) _Pragma("unroll") for (int n = 0; n < 2; ++n) _Pragma("unroll") for (int k = 0; k < 2; ++k) \
;         acc[ai][bj][m][n] = __builtin_amdgcn_mfma_f32_16x16x32_bf16(Bt[n][k], At[m][k], acc[ai][bj][m][n], 0, 0, 0); __builtin_amdgcn_s_setprio(0); } while (0)
; #define PG8_WAIT_V(n) asm volatile("s_waitcnt vmcnt(" #n ")" ::: "memory")
; #define PG8_WAIT_L(n) asm volatile("s_waitcnt lgkmcnt(" #n ")" ::: "memory")
; #define PG8_BAR __builtin_amdgcn_s_barrier()
; #define PG8_SCHED __builtin_amdgcn_sched_barrier(0)
; template <class Epi, class Sched, bool ALIGN_EPI = false, bool SP2 = false>
; __device__ __forceinline__ void gemm_phase(PG8_LAS unsigned char* lds, const Gemm g, const Sched& S, const Epi& E) {
;     ...
;             PG8_LDA(At, 1, 1); PG8_STAGE(PG8_SB(1, 0), b3, voffB); PG8_STAGE(PG8_SB(1, 1), b3 + hstep, voffB); PG8_STAGE(PG8_SA(1, 0), a3, voffA);
;             PG8_WAIT_V(8); PG8_WAIT_L(0); PG8_BAR; PG8_MMA(1, 0, At, B0); PG8_MMA(1, 1, At, B1); PG8_BAR; PG8_SCHED;
	s_mov_b32 m0, s24
	s_or_b32 s53, s52, 0x80
	ds_read_b128 v[172:175], v188 offset:49152
	ds_read_b128 v[176:179], v188 offset:50176
	ds_read_b128 v[190:193], v188 offset:51200
	ds_read_b128 v[194:197], v188 offset:52224
	ds_read_b128 v[208:211], v188 offset:53248
	ds_read_b128 v[212:215], v188 offset:54272
	ds_read_b128 v[218:221], v188 offset:55296
	ds_read_b128 v[222:225], v188 offset:56320
	buffer_load_dwordx4 v180, s[4:7], s53 offen lds
	s_mov_b32 m0, s25
	s_add_i32 s52, s52, 0x20080
	buffer_load_dwordx4 v182, s[4:7], s53 offen lds
	s_mov_b32 m0, s33
	s_nop 0
	buffer_load_dwordx4 v180, s[4:7], s52 offen lds
	s_mov_b32 m0, s34
	s_nop 0
	buffer_load_dwordx4 v182, s[4:7], s52 offen lds
	s_mov_b32 m0, s26
	s_nop 0
	buffer_load_dwordx4 v2, s[28:31], s51 offen lds
	s_mov_b32 m0, s27
	s_nop 0
	buffer_load_dwordx4 v181, s[28:31], s51 offen lds
	s_waitcnt vmcnt(8)
	s_waitcnt lgkmcnt(0)
	s_barrier
	s_setprio 1
	s_waitcnt lgkmcnt(7)
	v_mfma_f32_16x16x32_bf16 v[64:67], v[132:135], v[172:175], v[64:67]
	v_mfma_f32_16x16x32_bf16 v[60:63], v[140:143], v[172:175], v[60:63]
	s_waitcnt lgkmcnt(5)
	v_mfma_f32_16x16x32_bf16 v[48:51], v[132:135], v[190:193], v[48:51]
	v_mfma_f32_16x16x32_bf16 v[44:47], v[140:143], v[190:193], v[44:47]
	s_waitcnt lgkmcnt(3)
	v_mfma_f32_16x16x32_bf16 v[32:35], v[132:135], v[208:211], v[32:35]
	v_mfma_f32_16x16x32_bf16 v[28:31], v[140:143], v[208:211], v[28:31]
	s_waitcnt lgkmcnt(1)
	v_mfma_f32_16x16x32_bf16 v[16:19], v[132:135], v[218:221], v[16:19]
	v_mfma_f32_16x16x32_bf16 v[12:15], v[140:143], v[218:221], v[12:15]
	v_mfma_f32_16x16x32_bf16 v[64:67], v[136:139], v[176:179], v[64:67]
	v_mfma_f32_16x16x32_bf16 v[60:63], v[144:147], v[176:179], v[60:63]
	v_mfma_f32_16x16x32_bf16 v[48:51], v[136:139], v[194:197], v[48:51]
	v_mfma_f32_16x16x32_bf16 v[44:47], v[144:147], v[194:197], v[44:47]
	v_mfma_f32_16x16x32_bf16 v[32:35], v[136:139], v[212:215], v[32:35]
	v_mfma_f32_16x16x32_bf16 v[28:31], v[144:147], v[212:215], v[28:31]
	s_waitcnt lgkmcnt(0)
	v_mfma_f32_16x16x32_bf16 v[16:19], v[136:139], v[222:225], v[16:19]
	v_mfma_f32_16x16x32_bf16 v[12:15], v[144:147], v[222:225], v[12:15]
	s_setprio 0
	s_setprio 1
	v_mfma_f32_16x16x32_bf16 v[56:59], v[148:151], v[172:175], v[56:59]
	v_mfma_f32_16x16x32_bf16 v[52:55], v[156:159], v[172:175], v[52:55]
	v_mfma_f32_16x16x32_bf16 v[40:43], v[148:151], v[190:193], v[40:43]
	v_mfma_f32_16x16x32_bf16 v[36:39], v[156:159], v[190:193], v[36:39]
	v_mfma_f32_16x16x32_bf16 v[24:27], v[148:151], v[208:211], v[24:27]
	v_mfma_f32_16x16x32_bf16 v[20:23], v[156:159], v[208:211], v[20:23]
	v_mfma_f32_16x16x32_bf16 v[8:11], v[148:151], v[218:221], v[8:11]
	v_mfma_f32_16x16x32_bf16 v[4:7], v[156:159], v[218:221], v[4:7]
	v_mfma_f32_16x16x32_bf16 v[56:59], v[152:155], v[176:179], v[56:59]
	v_mfma_f32_16x16x32_bf16 v[52:55], v[168:171], v[176:179], v[52:55]
	v_mfma_f32_16x16x32_bf16 v[40:43], v[152:155], v[194:197], v[40:43]
	v_mfma_f32_16x16x32_bf16 v[36:39], v[168:171], v[194:197], v[36:39]
	v_mfma_f32_16x16x32_bf16 v[24:27], v[152:155], v[212:215], v[24:27]
	v_mfma_f32_16x16x32_bf16 v[20:23], v[168:171], v[212:215], v[20:23]
	v_mfma_f32_16x16x32_bf16 v[8:11], v[152:155], v[222:225], v[8:11]
	v_mfma_f32_16x16x32_bf16 v[4:7], v[168:171], v[222:225], v[4:7]
	s_setprio 0
	s_barrier
	s_add_i32 s50, s50, 2
	s_addk_i32 s48, 0x100
	s_addk_i32 s49, 0x100
	s_cmp_gt_u32 s50, 5

;     __device__ __forceinline__ void operator()(const f32x4 (&acc)[2][2][4][2], const Unit& u, int wr, int wc, int fr, int fq) const {
;     ...
;             for (int m = 0; m < 4; ++m) { float q = sq[ai][m]; q = fq_sum(q); sq[ai][m] = q; }
;             const float v = fq == 0 ? sq[ai][0] : (fq == 1 ? sq[ai][1] : (fq == 2 ? sq[ai][2] : sq[ai][3]));
;             atomicAdd(ssout + (u.pm * BM + wr * 64 + ai * HALF + fq * 16 + fr), (unsigned long long)(v * 16777216.f));
; template <class Epi, class Sched, bool ALIGN_EPI = false, bool SP2 = false>
; __device__ __forceinline__ void gemm_phase(PG8_LAS unsigned char* lds, const Gemm g, const Sched& S, const Epi& E) {
;     ...
; #pragma unroll
;         for (int a = 0; a < 2; ++a)
; #pragma unroll
;             for (int b = 0; b < 2; ++b)
; #pragma unroll
;                 for (int m = 0; m < 4; ++m)
; #pragma unroll
;                     for (int n = 0; n < 2; ++n) { typedef double d2_t __attribute__((ext_vector_type(2))); d2_t z; double z0, z1;
;                         asm volatile("v_mov_b64 %0, 0" : "=v"(z0)); asm volatile("v_mov_b64 %0, 0" : "=v"(z1)); z.x = z0; z.y = z1; acc[a][b][m][n] = __builtin_bit_cast(f32x4, z); }
.LBB0_802:
	s_or_b64 exec, exec, s[0:1]
	v_add_f32_e32 v4, v8, v9
	v_mul_f32_e32 v4, 0x4b800000, v4
	v_trunc_f32_e32 v4, v4
	v_mul_f32_e32 v5, 0x2f800000, v4
	v_floor_f32_e32 v5, v5
	v_fmac_f32_e32 v4, 0xcf800000, v5
	v_cvt_u32_f32_e32 v4, v4
	v_cvt_u32_f32_e32 v5, v5
	v_add_u32_e32 v6, 0x80, v92
	v_ashrrev_i32_e32 v7, 31, v6
	v_lshl_add_u64 v[6:7], v[6:7], 3, s[10:11]
	global_atomic_add_x2 v[6:7], v[4:5], off
	s_andn2_b64 vcc, exec, s[40:41]
	s_mov_b64 s[0:1], -1
	s_cbranch_vccnz .LBB0_771
	s_andn2_b64 vcc, exec, s[2:3]
	s_cbranch_vccnz .LBB0_770
	s_barrier
	s_branch .LBB0_770

; #define PG8_STAGE(bufoff, soff, voff) do { _Pragma("unroll") for (int _i = 0; _i < 2; ++_i) \
;         __builtin_amdgcn_raw_ptr_buffer_load_lds(PG8_RS_##voff, (PG8_LAS void*)(lds + (bufoff) + ldsw + _i * 8192), 16, (voff)[_i], (soff), 0, 0); } while (0)
; #define PG8_LDA(dst, b, h) do { _Pragma("unroll") for (int m = 0; m < 4; ++m) _Pragma("unroll") for (int k = 0; k < 2; ++k) dst[m][k] = *(const PG8_LAS bf16x8*)(lds + PG8_SA(b, h) + aoff + m * 2048 + k * 1024); } while (0)
; #define PG8_LDB(dst, b, h) do { _Pragma("unroll") for (int n = 0; n < 2; ++n) _Pragma("unroll") for (int k = 0; k < 2; ++k) dst[n][k] = *(const PG8_LAS bf16x8*)(lds + PG8_SB(b, h) + boff + n * 2048 + k * 1024); } while (0)
; #define PG8_WAIT_V(n) asm volatile("s_waitcnt vmcnt(" #n ")" ::: "memory")
; #define PG8_WAIT_L(n) asm volatile("s_waitcnt lgkmcnt(" #n ")" ::: "memory")
; #define PG8_BAR __builtin_amdgcn_s_barrier()
; #define PG8_SCHED __builtin_amdgcn_sched_barrier(0)
; template <class Epi, class Sched, bool ALIGN_EPI = false, bool SP2 = false>
; __device__ __forceinline__ void gemm_phase(PG8_LAS unsigned char* lds, const Gemm g, const Sched& S, const Epi& E) {
;     ...
;         const bool has_next = S.next(ui + 1, nxt);
;         const unsigned nA = has_next ? (unsigned)nxt.pm * tstep + (unsigned)nxt.ko * 2u : cA, nB = has_next ? (unsigned)nxt.pn * tstep + (unsigned)nxt.ko * 2u : cB;
;         for (int t = 0; t < nt; t += 2) {
;             const bool last = (t == nt - 2);
;             const unsigned a1 = cA + (unsigned)(t + 1) * kstep;
;             const unsigned a2 = last ? nA : cA + (unsigned)(t + 2) * kstep, b2 = last ? nB : cB + (unsigned)(t + 2) * kstep;
;             const unsigned a3 = a2 + kstep, b3 = b2 + kstep;
;             if (last && has_next) S.a_ready(nxt);
;             if constexpr (SP2) {
;             PG8_LDB(B0, 0, 0); PG8_LDB(B1, 0, 1); PG8_SCHED; PG8_LDA(At, 0, 0); PG8_STAGE(PG8_SA(1, 1), a1 + hstep, voffA);
;             PG8_WAIT_V(8); PG8_WAIT_L(0); PG8_BAR; PG8_MMA(0, 0, At, B0); PG8_MMA(0, 1, At, B1); PG8_BAR; PG8_SCHED;
;             PG8_LDA(At, 0, 1); PG8_STAGE(PG8_SB(0, 0), b2, voffB); PG8_STAGE(PG8_SB(0, 1), b2 + hstep, voffB); PG8_STAGE(PG8_SA(0, 0), a2, voffA);
;             PG8_WAIT_V(8); PG8_WAIT_L(0); PG8_BAR; PG8_MMA(1, 0, At, B0); PG8_MMA(1, 1, At, B1); PG8_BAR; PG8_SCHED;
.LBB0_878:
	s_lshl_b32 s41, s40, 20
	s_and_b64 s[0:1], s[4:5], exec
	s_cselect_b32 s0, s41, s11
	s_lshl_b32 s42, s37, 20
	s_and_b64 s[46:47], s[4:5], exec
	s_cselect_b32 s1, s42, s10
	s_add_i32 s45, s11, 0x80080
	s_add_i32 s46, s10, 0x100
	s_mov_b32 s47, -2
	v_add_u32_e32 v132, 0x10000, v139
	ds_read_b128 v[142:145], v132
	ds_read_b128 v[146:149], v132 offset:1024
	ds_read_b128 v[150:153], v132 offset:2048
	ds_read_b128 v[154:157], v132 offset:3072
	v_add_u32_e32 v132, 0x14000, v139
	ds_read_b128 v[168:171], v132
	ds_read_b128 v[172:175], v132 offset:1024
	ds_read_b128 v[176:179], v132 offset:2048
	ds_read_b128 v[180:183], v132 offset:3072
	s_add_i32 s10, s45, 0xfff80080
	s_cmp_eq_u32 s47, 28
	s_cselect_b32 s50, s0, s10
	s_cselect_b32 s49, s1, s46
	s_or_b32 s48, s50, 0x80
	s_mov_b32 m0, s34
	ds_read_b128 v[184:187], v140
	ds_read_b128 v[188:191], v140 offset:1024
	ds_read_b128 v[192:195], v140 offset:2048
	ds_read_b128 v[196:199], v140 offset:3072
	ds_read_b128 v[208:211], v140 offset:4096
	ds_read_b128 v[212:215], v140 offset:5120
	ds_read_b128 v[218:221], v140 offset:6144
	ds_read_b128 v[222:225], v140 offset:7168
	buffer_load_dwordx4 v2, s[28:31], s45 offen lds
	s_mov_b32 m0, s35
	s_nop 0
	buffer_load_dwordx4 v135, s[28:31], s45 offen lds
	s_waitcnt vmcnt(8)
	s_waitcnt lgkmcnt(0)
	s_barrier
	s_setprio 1
	s_waitcnt lgkmcnt(7)
	v_mfma_f32_16x16x32_bf16 v[128:131], v[142:145], v[184:187], 0
	v_mfma_f32_16x16x32_bf16 v[124:127], v[150:153], v[184:187], 0
	s_waitcnt lgkmcnt(5)
	v_mfma_f32_16x16x32_bf16 v[112:115], v[142:145], v[192:195], 0
	v_mfma_f32_16x16x32_bf16 v[108:111], v[150:153], v[192:195], 0
	s_waitcnt lgkmcnt(3)
	v_mfma_f32_16x16x32_bf16 v[96:99], v[142:145], v[208:211], 0
	v_mfma_f32_16x16x32_bf16 v[92:95], v[150:153], v[208:211], 0
	s_waitcnt lgkmcnt(1)
	v_mfma_f32_16x16x32_bf16 v[80:83], v[142:145], v[218:221], 0
	v_mfma_f32_16x16x32_bf16 v[76:79], v[150:153], v[218:221], 0
	v_mfma_f32_16x16x32_bf16 v[128:131], v[146:149], v[188:191], v[128:131]
	v_mfma_f32_16x16x32_bf16 v[124:127], v[154:157], v[188:191], v[124:127]
	v_mfma_f32_16x16x32_bf16 v[112:115], v[146:149], v[196:199], v[112:115]
	v_mfma_f32_16x16x32_bf16 v[108:111], v[154:157], v[196:199], v[108:111]
	v_mfma_f32_16x16x32_bf16 v[96:99], v[146:149], v[212:215], v[96:99]
	v_mfma_f32_16x16x32_bf16 v[92:95], v[154:157], v[212:215], v[92:95]
	s_waitcnt lgkmcnt(0)
	v_mfma_f32_16x16x32_bf16 v[80:83], v[146:149], v[222:225], v[80:83]
	v_mfma_f32_16x16x32_bf16 v[76:79], v[154:157], v[222:225], v[76:79]
	s_setprio 0
	s_setprio 1
	v_mfma_f32_16x16x32_bf16 v[120:123], v[168:171], v[184:187], 0
	v_mfma_f32_16x16x32_bf16 v[116:119], v[176:179], v[184:187], 0
	v_mfma_f32_16x16x32_bf16 v[104:107], v[168:171], v[192:195], 0
	v_mfma_f32_16x16x32_bf16 v[100:103], v[176:179], v[192:195], 0
	v_mfma_f32_16x16x32_bf16 v[88:91], v[168:171], v[208:211], 0
	v_mfma_f32_16x16x32_bf16 v[84:87], v[176:179], v[208:211], 0
	v_mfma_f32_16x16x32_bf16 v[72:75], v[168:171], v[218:221], 0
	v_mfma_f32_16x16x32_bf16 v[68:71], v[176:179], v[218:221], 0
	v_mfma_f32_16x16x32_bf16 v[120:123], v[172:175], v[188:191], v[120:123]
	v_mfma_f32_16x16x32_bf16 v[116:119], v[180:183], v[188:191], v[116:119]
	v_mfma_f32_16x16x32_bf16 v[104:107], v[172:175], v[196:199], v[104:107]
	v_mfma_f32_16x16x32_bf16 v[100:103], v[180:183], v[196:199], v[100:103]
	v_mfma_f32_16x16x32_bf16 v[88:91], v[172:175], v[212:215], v[88:91]
	v_mfma_f32_16x16x32_bf16 v[84:87], v[180:183], v[212:215], v[84:87]
	v_mfma_f32_16x16x32_bf16 v[72:75], v[172:175], v[222:225], v[72:75]
	v_mfma_f32_16x16x32_bf16 v[68:71], v[180:183], v[222:225], v[68:71]
	s_setprio 0
	s_barrier
	s_mov_b32 m0, s15
	s_mov_b32 s10, s30
	s_mov_b32 s11, s31
	ds_read_b128 v[184:187], v140 offset:16384
	ds_read_b128 v[188:191], v140 offset:17408
	ds_read_b128 v[192:195], v140 offset:18432
	ds_read_b128 v[196:199], v140 offset:19456
	ds_read_b128 v[208:211], v140 offset:20480
	ds_read_b128 v[212:215], v140 offset:21504
	ds_read_b128 v[218:221], v140 offset:22528
	ds_read_b128 v[222:225], v140 offset:23552
	buffer_load_dwordx4 v134, s[8:11], s49 offen lds
	s_mov_b32 m0, s16
	s_add_i32 s51, s49, 0x80000
	buffer_load_dwordx4 v136, s[8:11], s49 offen lds
	s_mov_b32 m0, s17
	s_nop 0
	buffer_load_dwordx4 v134, s[8:11], s51 offen lds
	s_mov_b32 m0, s18
	s_nop 0
	buffer_load_dwordx4 v136, s[8:11], s51 offen lds
	s_mov_b32 m0, s14
	s_nop 0
	buffer_load_dwordx4 v2, s[28:31], s50 offen lds
	s_mov_b32 m0, s19
	s_nop 0
	buffer_load_dwordx4 v135, s[28:31], s50 offen lds
	s_waitcnt vmcnt(8)
	s_waitcnt lgkmcnt(0)
	s_barrier
; #define PG8_STAGE(bufoff, soff, voff) do { _Pragma("unroll") for (int _i = 0; _i < 2; ++_i) \
;         __builtin_amdgcn_raw_ptr_buffer_load_lds(PG8_RS_##voff, (PG8_LAS void*)(lds + (bufoff) + ldsw + _i * 8192), 16, (voff)[_i], (soff), 0, 0); } while (0)
; #define PG8_LDA(dst, b, h) do { _Pragma("unroll") for (int m = 0; m < 4; ++m) _Pragma("unroll") for (int k = 0; k < 2; ++k) dst[m][k] = *(const PG8_LAS bf16x8*)(lds + PG8_SA(b, h) + aoff + m * 2048 + k * 1024); } while (0)
; #define PG8_LDB(dst, b, h) do { _Pragma("unroll") for (int n = 0; n < 2; ++n) _Pragma("unroll") for (int k = 0; k < 2; ++k) dst[n][k] = *(const PG8_LAS bf16x8*)(lds + PG8_SB(b, h) + boff + n * 2048 + k * 1024); } while (0)
; #define PG8_MMA(ai, bj, At, Bt) do { __builtin_amdgcn_s_setprio(1); _Pragma("unroll") for (int m = 0; m < 4; ++m) _Pragma("unroll") for (int n = 0; n < 2; ++n) _Pragma("unroll") for (int k = 0; k < 2; ++k) \
;         acc[ai][bj][m][n] = __builtin_amdgcn_mfma_f32_16x16x32_bf16(Bt[n][k], At[m][k], acc[ai][bj][m][n], 0, 0, 0); __builtin_amdgcn_s_setprio(0); } while (0)
; #define PG8_WAIT_V(n) asm volatile("s_waitcnt vmcnt(" #n ")" ::: "memory")
; #define PG8_WAIT_L(n) asm volatile("s_waitcnt lgkmcnt(" #n ")" ::: "memory")
; #define PG8_BAR __builtin_amdgcn_s_barrier()
; #define PG8_SCHED __builtin_amdgcn_sched_barrier(0)
; template <class Epi, class Sched, bool ALIGN_EPI = false, bool SP2 = false>
; __device__ __forceinline__ void gemm_phase(PG8_LAS unsigned char* lds, const Gemm g, const Sched& S, const Epi& E) {
;     ...
;             PG8_WAIT_V(8); PG8_WAIT_L(0); PG8_BAR; PG8_MMA(1, 0, At, B0); PG8_MMA(1, 1, At, B1); PG8_BAR; PG8_SCHED;
;             PG8_LDB(B0, 1, 0); PG8_LDB(B1, 1, 1); PG8_SCHED; PG8_LDA(At, 1, 0); PG8_STAGE(PG8_SA(0, 1), a2 + hstep, voffA);
;             PG8_WAIT_V(8); PG8_WAIT_L(0); PG8_BAR; PG8_MMA(0, 0, At, B0); PG8_MMA(0, 1, At, B1); PG8_BAR; PG8_SCHED;
	s_setprio 1
	s_waitcnt lgkmcnt(7)
	v_mfma_f32_16x16x32_bf16 v[64:67], v[142:145], v[184:187], 0
	v_mfma_f32_16x16x32_bf16 v[60:63], v[150:153], v[184:187], 0
	s_waitcnt lgkmcnt(5)
	v_mfma_f32_16x16x32_bf16 v[48:51], v[142:145], v[192:195], 0
	v_mfma_f32_16x16x32_bf16 v[44:47], v[150:153], v[192:195], 0
	s_waitcnt lgkmcnt(3)
	v_mfma_f32_16x16x32_bf16 v[32:35], v[142:145], v[208:211], 0
	v_mfma_f32_16x16x32_bf16 v[28:31], v[150:153], v[208:211], 0
	s_waitcnt lgkmcnt(1)
	v_mfma_f32_16x16x32_bf16 v[16:19], v[142:145], v[218:221], 0
	v_mfma_f32_16x16x32_bf16 v[12:15], v[150:153], v[218:221], 0
	v_mfma_f32_16x16x32_bf16 v[64:67], v[146:149], v[188:191], v[64:67]
	v_mfma_f32_16x16x32_bf16 v[60:63], v[154:157], v[188:191], v[60:63]
	v_mfma_f32_16x16x32_bf16 v[48:51], v[146:149], v[196:199], v[48:51]
	v_mfma_f32_16x16x32_bf16 v[44:47], v[154:157], v[196:199], v[44:47]
	v_mfma_f32_16x16x32_bf16 v[32:35], v[146:149], v[212:215], v[32:35]
	v_mfma_f32_16x16x32_bf16 v[28:31], v[154:157], v[212:215], v[28:31]
	s_waitcnt lgkmcnt(0)
	v_mfma_f32_16x16x32_bf16 v[16:19], v[146:149], v[222:225], v[16:19]
	v_mfma_f32_16x16x32_bf16 v[12:15], v[154:157], v[222:225], v[12:15]
	s_setprio 0
	s_setprio 1
	v_mfma_f32_16x16x32_bf16 v[56:59], v[168:171], v[184:187], 0
	v_mfma_f32_16x16x32_bf16 v[52:55], v[176:179], v[184:187], 0
	v_mfma_f32_16x16x32_bf16 v[40:43], v[168:171], v[192:195], 0
	v_mfma_f32_16x16x32_bf16 v[36:39], v[176:179], v[192:195], 0
	v_mfma_f32_16x16x32_bf16 v[24:27], v[168:171], v[208:211], 0
	v_mfma_f32_16x16x32_bf16 v[20:23], v[176:179], v[208:211], 0
	v_mfma_f32_16x16x32_bf16 v[8:11], v[168:171], v[218:221], 0
	v_mfma_f32_16x16x32_bf16 v[4:7], v[176:179], v[218:221], 0
	v_mfma_f32_16x16x32_bf16 v[56:59], v[172:175], v[188:191], v[56:59]
	v_mfma_f32_16x16x32_bf16 v[52:55], v[180:183], v[188:191], v[52:55]
	v_mfma_f32_16x16x32_bf16 v[40:43], v[172:175], v[196:199], v[40:43]
	v_mfma_f32_16x16x32_bf16 v[36:39], v[180:183], v[196:199], v[36:39]
	v_mfma_f32_16x16x32_bf16 v[24:27], v[172:175], v[212:215], v[24:27]
	v_mfma_f32_16x16x32_bf16 v[20:23], v[180:183], v[212:215], v[20:23]
	v_mfma_f32_16x16x32_bf16 v[8:11], v[172:175], v[222:225], v[8:11]
	v_mfma_f32_16x16x32_bf16 v[4:7], v[180:183], v[222:225], v[4:7]
	s_setprio 0
	s_barrier
	v_add_u32_e32 v132, 0x18000, v139
	ds_read_b128 v[142:145], v132
	ds_read_b128 v[146:149], v132 offset:1024
	ds_read_b128 v[150:153], v132 offset:2048
	ds_read_b128 v[154:157], v132 offset:3072
	v_add_u32_e32 v132, 0x1c000, v139
	ds_read_b128 v[168:171], v132
	ds_read_b128 v[172:175], v132 offset:1024
	ds_read_b128 v[176:179], v132 offset:2048
	ds_read_b128 v[180:183], v132 offset:3072
	s_add_i32 s50, s50, 0x80000
	s_mov_b32 m0, s21
	ds_read_b128 v[184:187], v140 offset:32768
	ds_read_b128 v[188:191], v140 offset:33792
	ds_read_b128 v[192:195], v140 offset:34816
	ds_read_b128 v[196:199], v140 offset:35840
	ds_read_b128 v[208:211], v140 offset:36864
	ds_read_b128 v[212:215], v140 offset:37888
	ds_read_b128 v[218:221], v140 offset:38912
	ds_read_b128 v[222:225], v140 offset:39936
	buffer_load_dwordx4 v2, s[28:31], s50 offen lds
	s_mov_b32 m0, s22
	s_nop 0
	buffer_load_dwordx4 v135, s[28:31], s50 offen lds
	s_waitcnt vmcnt(8)
	s_waitcnt lgkmcnt(0)
	s_barrier
	s_setprio 1
	s_waitcnt lgkmcnt(7)
	v_mfma_f32_16x16x32_bf16 v[128:131], v[142:145], v[184:187], v[128:131]
	v_mfma_f32_16x16x32_bf16 v[124:127], v[150:153], v[184:187], v[124:127]
	s_waitcnt lgkmcnt(5)
	v_mfma_f32_16x16x32_bf16 v[112:115], v[142:145], v[192:195], v[112:115]
	v_mfma_f32_16x16x32_bf16 v[108:111], v[150:153], v[192:195], v[108:111]
	s_waitcnt lgkmcnt(3)
	v_mfma_f32_16x16x32_bf16 v[96:99], v[142:145], v[208:211], v[96:99]
	v_mfma_f32_16x16x32_bf16 v[92:95], v[150:153], v[208:211], v[92:95]
	s_waitcnt lgkmcnt(1)
	v_mfma_f32_16x16x32_bf16 v[80:83], v[142:145], v[218:221], v[80:83]
	v_mfma_f32_16x16x32_bf16 v[76:79], v[150:153], v[218:221], v[76:79]
	v_mfma_f32_16x16x32_bf16 v[128:131], v[146:149], v[188:191], v[128:131]
	v_mfma_f32_16x16x32_bf16 v[124:127], v[154:157], v[188:191], v[124:127]
	v_mfma_f32_16x16x32_bf16 v[112:115], v[146:149], v[196:199], v[112:115]
	v_mfma_f32_16x16x32_bf16 v[108:111], v[154:157], v[196:199], v[108:111]
	v_mfma_f32_16x16x32_bf16 v[96:99], v[146:149], v[212:215], v[96:99]
	v_mfma_f32_16x16x32_bf16 v[92:95], v[154:157], v[212:215], v[92:95]
	s_waitcnt lgkmcnt(0)
	v_mfma_f32_16x16x32_bf16 v[80:83], v[146:149], v[222:225], v[80:83]
	v_mfma_f32_16x16x32_bf16 v[76:79], v[154:157], v[222:225], v[76:79]
	s_setprio 0
	s_setprio 1
	v_mfma_f32_16x16x32_bf16 v[120:123], v[168:171], v[184:187], v[120:123]
	v_mfma_f32_16x16x32_bf16 v[116:119], v[176:179], v[184:187], v[116:119]
	v_mfma_f32_16x16x32_bf16 v[104:107], v[168:171], v[192:195], v[104:107]
	v_mfma_f32_16x16x32_bf16 v[100:103], v[176:179], v[192:195], v[100:103]
	v_mfma_f32_16x16x32_bf16 v[88:91], v[168:171], v[208:211], v[88:91]
	v_mfma_f32_16x16x32_bf16 v[84:87], v[176:179], v[208:211], v[84:87]
	v_mfma_f32_16x16x32_bf16 v[72:75], v[168:171], v[218:221], v[72:75]
	v_mfma_f32_16x16x32_bf16 v[68:71], v[176:179], v[218:221], v[68:71]
	v_mfma_f32_16x16x32_bf16 v[120:123], v[172:175], v[188:191], v[120:123]
	v_mfma_f32_16x16x32_bf16 v[116:119], v[180:183], v[188:191], v[116:119]
	v_mfma_f32_16x16x32_bf16 v[104:107], v[172:175], v[196:199], v[104:107]
	v_mfma_f32_16x16x32_bf16 v[100:103], v[180:183], v[196:199], v[100:103]
	v_mfma_f32_16x16x32_bf16 v[88:91], v[172:175], v[212:215], v[88:91]
	v_mfma_f32_16x16x32_bf16 v[84:87], v[180:183], v[212:215], v[84:87]
	v_mfma_f32_16x16x32_bf16 v[72:75], v[172:175], v[222:225], v[72:75]
	v_mfma_f32_16x16x32_bf16 v[68:71], v[180:183], v[222:225], v[68:71]
	s_setprio 0
	s_barrier
; #define PG8_STAGE(bufoff, soff, voff) do { _Pragma("unroll") for (int _i = 0; _i < 2; ++_i) \
;         __builtin_amdgcn_raw_ptr_buffer_load_lds(PG8_RS_##voff, (PG8_LAS void*)(lds + (bufoff) + ldsw + _i * 8192), 16, (voff)[_i], (soff), 0, 0); } while (0)
; #define PG8_LDA(dst, b, h) do { _Pragma("unroll") for (int m = 0; m < 4; ++m) _Pragma("unroll") for (int k = 0; k < 2; ++k) dst[m][k] = *(const PG8_LAS bf16x8*)(lds + PG8_SA(b, h) + aoff + m * 2048 + k * 1024); } while (0)
; #define PG8_MMA(ai, bj, At, Bt) do { __builtin_amdgcn_s_setprio(1); _Pragma("unroll") for (int m = 0; m < 4; ++m) _Pragma("unroll") for (int n = 0; n < 2; ++n) _Pragma("unroll") for (int k = 0; k < 2; ++k) \
;         acc[ai][bj][m][n] = __builtin_amdgcn_mfma_f32_16x16x32_bf16(Bt[n][k], At[m][k], acc[ai][bj][m][n], 0, 0, 0); __builtin_amdgcn_s_setprio(0); } while (0)
; #define PG8_WAIT_V(n) asm volatile("s_waitcnt vmcnt(" #n ")" ::: "memory")
; #define PG8_WAIT_L(n) asm volatile("s_waitcnt lgkmcnt(" #n ")" ::: "memory")
; #define PG8_BAR __builtin_amdgcn_s_barrier()
; #define PG8_SCHED __builtin_amdgcn_sched_barrier(0)
; template <class Epi, class Sched, bool ALIGN_EPI = false, bool SP2 = false>
; __device__ __forceinline__ void gemm_phase(PG8_LAS unsigned char* lds, const Gemm g, const Sched& S, const Epi& E) {
;     ...
;             PG8_LDA(At, 1, 1); PG8_STAGE(PG8_SB(1, 0), b3, voffB); PG8_STAGE(PG8_SB(1, 1), b3 + hstep, voffB); PG8_STAGE(PG8_SA(1, 0), a3, voffA);
;             PG8_WAIT_V(8); PG8_WAIT_L(0); PG8_BAR; PG8_MMA(1, 0, At, B0); PG8_MMA(1, 1, At, B1); PG8_BAR; PG8_SCHED;
	s_mov_b32 m0, s23
	s_or_b32 s50, s49, 0x80
	ds_read_b128 v[184:187], v140 offset:49152
	ds_read_b128 v[188:191], v140 offset:50176
	ds_read_b128 v[192:195], v140 offset:51200
	ds_read_b128 v[196:199], v140 offset:52224
	ds_read_b128 v[208:211], v140 offset:53248
	ds_read_b128 v[212:215], v140 offset:54272
	ds_read_b128 v[218:221], v140 offset:55296
	ds_read_b128 v[222:225], v140 offset:56320
	buffer_load_dwordx4 v134, s[8:11], s50 offen lds
	s_mov_b32 m0, s24
	s_add_i32 s49, s49, 0x80080
	buffer_load_dwordx4 v136, s[8:11], s50 offen lds
	s_mov_b32 m0, s27
	s_nop 0
	buffer_load_dwordx4 v134, s[8:11], s49 offen lds
	s_mov_b32 m0, s33
	s_nop 0
	buffer_load_dwordx4 v136, s[8:11], s49 offen lds
	s_mov_b32 m0, s25
	s_nop 0
	buffer_load_dwordx4 v2, s[28:31], s48 offen lds
	s_mov_b32 m0, s26
	s_nop 0
	buffer_load_dwordx4 v135, s[28:31], s48 offen lds
	s_waitcnt vmcnt(8)
	s_waitcnt lgkmcnt(0)
	s_barrier
	s_setprio 1
	s_waitcnt lgkmcnt(7)
	v_mfma_f32_16x16x32_bf16 v[64:67], v[142:145], v[184:187], v[64:67]
	v_mfma_f32_16x16x32_bf16 v[60:63], v[150:153], v[184:187], v[60:63]
	s_waitcnt lgkmcnt(5)
	v_mfma_f32_16x16x32_bf16 v[48:51], v[142:145], v[192:195], v[48:51]
	v_mfma_f32_16x16x32_bf16 v[44:47], v[150:153], v[192:195], v[44:47]
	s_waitcnt lgkmcnt(3)
	v_mfma_f32_16x16x32_bf16 v[32:35], v[142:145], v[208:211], v[32:35]
	v_mfma_f32_16x16x32_bf16 v[28:31], v[150:153], v[208:211], v[28:31]
	s_waitcnt lgkmcnt(1)
	v_mfma_f32_16x16x32_bf16 v[16:19], v[142:145], v[218:221], v[16:19]
	v_mfma_f32_16x16x32_bf16 v[12:15], v[150:153], v[218:221], v[12:15]
	v_mfma_f32_16x16x32_bf16 v[64:67], v[146:149], v[188:191], v[64:67]
	v_mfma_f32_16x16x32_bf16 v[60:63], v[154:157], v[188:191], v[60:63]
	v_mfma_f32_16x16x32_bf16 v[48:51], v[146:149], v[196:199], v[48:51]
	v_mfma_f32_16x16x32_bf16 v[44:47], v[154:157], v[196:199], v[44:47]
	v_mfma_f32_16x16x32_bf16 v[32:35], v[146:149], v[212:215], v[32:35]
	v_mfma_f32_16x16x32_bf16 v[28:31], v[154:157], v[212:215], v[28:31]
	s_waitcnt lgkmcnt(0)
	v_mfma_f32_16x16x32_bf16 v[16:19], v[146:149], v[222:225], v[16:19]
	v_mfma_f32_16x16x32_bf16 v[12:15], v[154:157], v[222:225], v[12:15]
	s_setprio 0
	s_setprio 1
	v_mfma_f32_16x16x32_bf16 v[56:59], v[168:171], v[184:187], v[56:59]
	v_mfma_f32_16x16x32_bf16 v[52:55], v[176:179], v[184:187], v[52:55]
	v_mfma_f32_16x16x32_bf16 v[40:43], v[168:171], v[192:195], v[40:43]
	v_mfma_f32_16x16x32_bf16 v[36:39], v[176:179], v[192:195], v[36:39]
	v_mfma_f32_16x16x32_bf16 v[24:27], v[168:171], v[208:211], v[24:27]
	v_mfma_f32_16x16x32_bf16 v[20:23], v[176:179], v[208:211], v[20:23]
	v_mfma_f32_16x16x32_bf16 v[8:11], v[168:171], v[218:221], v[8:11]
	v_mfma_f32_16x16x32_bf16 v[4:7], v[176:179], v[218:221], v[4:7]
	v_mfma_f32_16x16x32_bf16 v[56:59], v[172:175], v[188:191], v[56:59]
	v_mfma_f32_16x16x32_bf16 v[52:55], v[180:183], v[188:191], v[52:55]
	v_mfma_f32_16x16x32_bf16 v[40:43], v[172:175], v[196:199], v[40:43]
	v_mfma_f32_16x16x32_bf16 v[36:39], v[180:183], v[196:199], v[36:39]
	v_mfma_f32_16x16x32_bf16 v[24:27], v[172:175], v[212:215], v[24:27]
	v_mfma_f32_16x16x32_bf16 v[20:23], v[180:183], v[212:215], v[20:23]
	v_mfma_f32_16x16x32_bf16 v[8:11], v[172:175], v[222:225], v[8:11]
	v_mfma_f32_16x16x32_bf16 v[4:7], v[180:183], v[222:225], v[4:7]
	s_setprio 0
	s_barrier
	s_add_i32 s47, s47, 2
	s_addk_i32 s45, 0x100
	s_addk_i32 s46, 0x100
	s_cmp_gt_u32 s47, 29

; __device__ __forceinline__ unsigned cvt_pk_bf16(float lo, float hi) { unsigned r; asm volatile("v_cvt_pk_bf16_f32 %0, %1, %2" : "=v"(r) : "v"(lo), "v"(hi)); return r; }
;     __device__ __forceinline__ void operator()(const f32x4 (&acc)[2][2][4][2], const Unit& u, int wr, int wc, int fr, int fq) const {
;     ...
;             for (int m = 0; m < 4; ++m) { bf16_t* rowp = base + (size_t)(row0 + ai * HALF + m * 16) * ldc + col0;
; #pragma unroll
;                 for (int bj = 0; bj < 2; ++bj) { f32x4 v0 = acc[ai][bj][m][0], v1 = acc[ai][bj][m][1];
;                     if (ACT == 2) {
; #pragma unroll
;                         for (int e = 0; e < 4; ++e) { const float a = fmaxf(v0[e], 0.f), b = fmaxf(v1[e], 0.f); v0[e] = a * a; v1[e] = b * b; } }
;                     u32x4 w; w.x = cvt_pk_bf16(v0[0], v0[1]); w.y = cvt_pk_bf16(v0[2], v0[3]); w.z = cvt_pk_bf16(v1[0], v1[1]); w.w = cvt_pk_bf16(v1[2], v1[3]);
;                     *(u32x4*)(rowp + bj * HALF) = w; } }
.LBB0_882:
	v_max_f32_e32 v124, v124, v124
	v_max_f32_e32 v124, 0, v124
	v_max_f32_e32 v125, v125, v125
	v_max_f32_e32 v126, v126, v126
	v_lshl_or_b32 v132, s43, 8, v138
	v_lshl_add_u32 v142, s44, 8, v137
	v_mul_f32_e32 v141, v124, v124
	v_max_f32_e32 v124, v129, v129
	v_max_f32_e32 v125, 0, v125
	v_max_f32_e32 v126, 0, v126
	v_ashrrev_i32_e32 v133, 31, v132
	v_ashrrev_i32_e32 v143, 31, v142
	v_max_f32_e32 v128, v128, v128
	v_max_f32_e32 v124, 0, v124
	v_mul_f32_e32 v129, v125, v125
	v_max_f32_e32 v125, v130, v130
	v_mul_f32_e32 v130, v126, v126
	v_max_f32_e32 v126, v131, v131
	v_max_f32_e32 v127, v127, v127
	v_lshl_add_u64 v[144:145], v[132:133], 1, s[6:7]
	v_lshlrev_b64 v[132:133], 14, v[142:143]
	v_max_f32_e32 v128, 0, v128
	v_mul_f32_e32 v124, v124, v124
	v_max_f32_e32 v125, 0, v125
	v_max_f32_e32 v126, 0, v126
	v_max_f32_e32 v127, 0, v127
	v_max_f32_e32 v116, v116, v116
	v_max_f32_e32 v117, v117, v117
	v_max_f32_e32 v118, v118, v118
	v_lshl_add_u64 v[132:133], v[144:145], 0, v[132:133]
	v_mul_f32_e32 v128, v128, v128
	v_mul_f32_e32 v125, v125, v125
	v_mul_f32_e32 v126, v126, v126
	v_mul_f32_e32 v127, v127, v127
	v_cvt_pk_bf16_f32 v124, v128, v124
	v_max_f32_e32 v116, 0, v116
	v_max_f32_e32 v117, 0, v117
	v_max_f32_e32 v118, 0, v118
	v_cvt_pk_bf16_f32 v125, v125, v126
	v_cvt_pk_bf16_f32 v126, v141, v129
	v_cvt_pk_bf16_f32 v127, v130, v127
	global_store_dwordx4 v[132:133], v[124:127], off
	v_max_f32_e32 v120, v120, v120
	v_max_f32_e32 v119, v119, v119
	v_mul_f32_e32 v124, v116, v116
	v_max_f32_e32 v116, v121, v121
	v_mul_f32_e32 v121, v117, v117
	v_max_f32_e32 v117, v122, v122
	v_mul_f32_e32 v122, v118, v118
	v_max_f32_e32 v118, v123, v123
	v_max_f32_e32 v116, 0, v116
	v_max_f32_e32 v117, 0, v117
	v_max_f32_e32 v118, 0, v118
	v_max_f32_e32 v120, 0, v120
	v_mul_f32_e32 v116, v116, v116
	v_mul_f32_e32 v117, v117, v117
	v_max_f32_e32 v119, 0, v119
	v_mul_f32_e32 v118, v118, v118
	v_max_f32_e32 v108, v108, v108
	v_mul_f32_e32 v120, v120, v120
	v_mul_f32_e32 v119, v119, v119
	v_cvt_pk_bf16_f32 v116, v120, v116
	v_cvt_pk_bf16_f32 v117, v117, v118
	v_cvt_pk_bf16_f32 v118, v124, v121
	v_max_f32_e32 v108, 0, v108
	v_max_f32_e32 v109, v109, v109
	v_max_f32_e32 v110, v110, v110
	v_cvt_pk_bf16_f32 v119, v122, v119
	global_store_dwordx4 v[132:133], v[116:119], off offset:256
	v_max_f32_e32 v109, 0, v109
	v_max_f32_e32 v110, 0, v110
	v_or_b32_e32 v116, 16, v142
	v_mul_f32_e32 v118, v108, v108
	v_max_f32_e32 v108, v113, v113
	v_ashrrev_i32_e32 v117, 31, v116
	v_max_f32_e32 v112, v112, v112
	v_max_f32_e32 v108, 0, v108
	v_mul_f32_e32 v113, v109, v109
	v_max_f32_e32 v109, v114, v114
	v_mul_f32_e32 v114, v110, v110
	v_max_f32_e32 v110, v115, v115
	v_max_f32_e32 v111, v111, v111
	v_lshlrev_b64 v[116:117], 14, v[116:117]
	v_max_f32_e32 v112, 0, v112
	v_mul_f32_e32 v108, v108, v108
	v_max_f32_e32 v109, 0, v109
	v_max_f32_e32 v110, 0, v110
	v_max_f32_e32 v111, 0, v111
	v_max_f32_e32 v100, v100, v100
	v_max_f32_e32 v101, v101, v101
	v_max_f32_e32 v102, v102, v102
	v_lshl_add_u64 v[116:117], v[144:145], 0, v[116:117]
	v_mul_f32_e32 v112, v112, v112
	v_mul_f32_e32 v109, v109, v109
	v_mul_f32_e32 v110, v110, v110
	v_mul_f32_e32 v111, v111, v111
	v_cvt_pk_bf16_f32 v108, v112, v108
	v_max_f32_e32 v100, 0, v100
	v_max_f32_e32 v101, 0, v101
	v_max_f32_e32 v102, 0, v102
	v_cvt_pk_bf16_f32 v109, v109, v110
	v_cvt_pk_bf16_f32 v110, v118, v113
	v_cvt_pk_bf16_f32 v111, v114, v111
	global_store_dwordx4 v[116:117], v[108:111], off
	v_max_f32_e32 v104, v104, v104
	v_max_f32_e32 v103, v103, v103
	v_mul_f32_e32 v108, v100, v100
	v_max_f32_e32 v100, v105, v105
	v_mul_f32_e32 v105, v101, v101
	v_max_f32_e32 v101, v106, v106
	v_mul_f32_e32 v106, v102, v102
	v_max_f32_e32 v102, v107, v107
	v_max_f32_e32 v100, 0, v100
	v_max_f32_e32 v101, 0, v101
	v_max_f32_e32 v102, 0, v102
	v_max_f32_e32 v104, 0, v104
	v_mul_f32_e32 v100, v100, v100
	v_mul_f32_e32 v101, v101, v101
	v_max_f32_e32 v103, 0, v103
	v_mul_f32_e32 v102, v102, v102
	v_max_f32_e32 v92, v92, v92
	v_mul_f32_e32 v104, v104, v104
	v_mul_f32_e32 v103, v103, v103
	v_cvt_pk_bf16_f32 v100, v104, v100
	v_cvt_pk_bf16_f32 v101, v101, v102
	v_cvt_pk_bf16_f32 v102, v108, v105
	v_max_f32_e32 v92, 0, v92
	v_max_f32_e32 v93, v93, v93
	v_max_f32_e32 v94, v94, v94
	v_cvt_pk_bf16_f32 v103, v106, v103
	global_store_dwordx4 v[116:117], v[100:103], off offset:256
	v_max_f32_e32 v93, 0, v93
	v_max_f32_e32 v94, 0, v94
	v_or_b32_e32 v100, 32, v142
	v_mul_f32_e32 v102, v92, v92
	v_max_f32_e32 v92, v97, v97
	v_ashrrev_i32_e32 v101, 31, v100
	v_max_f32_e32 v96, v96, v96
	v_max_f32_e32 v92, 0, v92
	v_mul_f32_e32 v97, v93, v93
	v_max_f32_e32 v93, v98, v98
	v_mul_f32_e32 v98, v94, v94
	v_max_f32_e32 v94, v99, v99
	v_max_f32_e32 v95, v95, v95
	v_lshlrev_b64 v[100:101], 14, v[100:101]
	v_max_f32_e32 v96, 0, v96
	v_mul_f32_e32 v92, v92, v92
	v_max_f32_e32 v93, 0, v93
	v_max_f32_e32 v94, 0, v94
	v_max_f32_e32 v95, 0, v95
	v_max_f32_e32 v84, v84, v84
	v_max_f32_e32 v85, v85, v85
	v_max_f32_e32 v86, v86, v86
	v_lshl_add_u64 v[100:101], v[144:145], 0, v[100:101]
	v_mul_f32_e32 v96, v96, v96
	v_mul_f32_e32 v93, v93, v93
	v_mul_f32_e32 v94, v94, v94
	v_mul_f32_e32 v95, v95, v95
	v_cvt_pk_bf16_f32 v92, v96, v92
	v_max_f32_e32 v84, 0, v84
	v_max_f32_e32 v85, 0, v85
	v_max_f32_e32 v86, 0, v86
	v_cvt_pk_bf16_f32 v93, v93, v94
	v_cvt_pk_bf16_f32 v94, v102, v97
	v_cvt_pk_bf16_f32 v95, v98, v95
	global_store_dwordx4 v[100:101], v[92:95], off
	v_max_f32_e32 v88, v88, v88
	v_max_f32_e32 v87, v87, v87
	v_mul_f32_e32 v92, v84, v84
	v_max_f32_e32 v84, v89, v89
	v_mul_f32_e32 v89, v85, v85
	v_max_f32_e32 v85, v90, v90
	v_mul_f32_e32 v90, v86, v86
	v_max_f32_e32 v86, v91, v91
; __device__ __forceinline__ unsigned cvt_pk_bf16(float lo, float hi) { unsigned r; asm volatile("v_cvt_pk_bf16_f32 %0, %1, %2" : "=v"(r) : "v"(lo), "v"(hi)); return r; }
;     __device__ __forceinline__ void operator()(const f32x4 (&acc)[2][2][4][2], const Unit& u, int wr, int wc, int fr, int fq) const {
;     ...
;             for (int m = 0; m < 4; ++m) { bf16_t* rowp = base + (size_t)(row0 + ai * HALF + m * 16) * ldc + col0;
; #pragma unroll
;                 for (int bj = 0; bj < 2; ++bj) { f32x4 v0 = acc[ai][bj][m][0], v1 = acc[ai][bj][m][1];
;                     if (ACT == 2) {
; #pragma unroll
;                         for (int e = 0; e < 4; ++e) { const float a = fmaxf(v0[e], 0.f), b = fmaxf(v1[e], 0.f); v0[e] = a * a; v1[e] = b * b; } }
;                     u32x4 w; w.x = cvt_pk_bf16(v0[0], v0[1]); w.y = cvt_pk_bf16(v0[2], v0[3]); w.z = cvt_pk_bf16(v1[0], v1[1]); w.w = cvt_pk_bf16(v1[2], v1[3]);
;                     *(u32x4*)(rowp + bj * HALF) = w; } }
	v_max_f32_e32 v84, 0, v84
	v_max_f32_e32 v85, 0, v85
	v_max_f32_e32 v86, 0, v86
	v_max_f32_e32 v88, 0, v88
	v_mul_f32_e32 v84, v84, v84
	v_mul_f32_e32 v85, v85, v85
	v_max_f32_e32 v87, 0, v87
	v_mul_f32_e32 v86, v86, v86
	v_max_f32_e32 v76, v76, v76
	v_mul_f32_e32 v88, v88, v88
	v_mul_f32_e32 v87, v87, v87
	v_cvt_pk_bf16_f32 v84, v88, v84
	v_cvt_pk_bf16_f32 v85, v85, v86
	v_cvt_pk_bf16_f32 v86, v92, v89
	v_max_f32_e32 v76, 0, v76
	v_max_f32_e32 v77, v77, v77
	v_max_f32_e32 v78, v78, v78
	v_cvt_pk_bf16_f32 v87, v90, v87
	global_store_dwordx4 v[100:101], v[84:87], off offset:256
	v_max_f32_e32 v77, 0, v77
	v_max_f32_e32 v78, 0, v78
	v_or_b32_e32 v84, 48, v142
	v_mul_f32_e32 v86, v76, v76
	v_max_f32_e32 v76, v81, v81
	v_ashrrev_i32_e32 v85, 31, v84
	v_max_f32_e32 v80, v80, v80
	v_max_f32_e32 v76, 0, v76
	v_mul_f32_e32 v81, v77, v77
	v_max_f32_e32 v77, v82, v82
	v_mul_f32_e32 v82, v78, v78
	v_max_f32_e32 v78, v83, v83
	v_max_f32_e32 v79, v79, v79
	v_lshlrev_b64 v[84:85], 14, v[84:85]
	v_max_f32_e32 v80, 0, v80
	v_mul_f32_e32 v76, v76, v76
	v_max_f32_e32 v77, 0, v77
	v_max_f32_e32 v78, 0, v78
	v_max_f32_e32 v79, 0, v79
	v_max_f32_e32 v68, v68, v68
	v_max_f32_e32 v69, v69, v69
	v_max_f32_e32 v70, v70, v70
	v_lshl_add_u64 v[84:85], v[144:145], 0, v[84:85]
	v_mul_f32_e32 v80, v80, v80
	v_mul_f32_e32 v77, v77, v77
	v_mul_f32_e32 v78, v78, v78
	v_mul_f32_e32 v79, v79, v79
	v_cvt_pk_bf16_f32 v76, v80, v76
	v_max_f32_e32 v68, 0, v68
	v_max_f32_e32 v69, 0, v69
	v_max_f32_e32 v70, 0, v70
	v_cvt_pk_bf16_f32 v77, v77, v78
	v_cvt_pk_bf16_f32 v78, v86, v81
	v_cvt_pk_bf16_f32 v79, v82, v79
	global_store_dwordx4 v[84:85], v[76:79], off
	v_max_f32_e32 v72, v72, v72
	v_max_f32_e32 v71, v71, v71
	v_mul_f32_e32 v76, v68, v68
	v_max_f32_e32 v68, v73, v73
	v_mul_f32_e32 v73, v69, v69
	v_max_f32_e32 v69, v74, v74
	v_mul_f32_e32 v74, v70, v70
	v_max_f32_e32 v70, v75, v75
	v_max_f32_e32 v68, 0, v68
	v_max_f32_e32 v69, 0, v69
	v_max_f32_e32 v70, 0, v70
	v_max_f32_e32 v72, 0, v72
	v_mul_f32_e32 v68, v68, v68
	v_mul_f32_e32 v69, v69, v69
	v_max_f32_e32 v71, 0, v71
	v_mul_f32_e32 v70, v70, v70
	v_max_f32_e32 v60, v60, v60
	v_mul_f32_e32 v72, v72, v72
	v_mul_f32_e32 v71, v71, v71
	v_cvt_pk_bf16_f32 v68, v72, v68
	v_cvt_pk_bf16_f32 v69, v69, v70
	v_cvt_pk_bf16_f32 v70, v76, v73
	v_max_f32_e32 v60, 0, v60
	v_max_f32_e32 v61, v61, v61
	v_max_f32_e32 v62, v62, v62
	v_cvt_pk_bf16_f32 v71, v74, v71
	global_store_dwordx4 v[84:85], v[68:71], off offset:256
	v_max_f32_e32 v64, v64, v64
	v_max_f32_e32 v61, 0, v61
	v_mul_f32_e32 v70, v60, v60
	v_max_f32_e32 v60, v65, v65
	v_max_f32_e32 v62, 0, v62
	s_mov_b64 s[0:1], 0x200000
	v_max_f32_e32 v64, 0, v64
	v_max_f32_e32 v60, 0, v60
	v_mul_f32_e32 v65, v61, v61
	v_max_f32_e32 v61, v66, v66
	v_mul_f32_e32 v66, v62, v62
	v_max_f32_e32 v62, v67, v67
	v_lshl_add_u64 v[68:69], v[132:133], 0, s[0:1]
	v_mul_f32_e32 v64, v64, v64
	v_mul_f32_e32 v60, v60, v60
	v_max_f32_e32 v61, 0, v61
	v_max_f32_e32 v62, 0, v62
	v_max_f32_e32 v63, v63, v63
	s_mov_b32 s0, 0x200000
	v_mul_f32_e32 v61, v61, v61
	v_max_f32_e32 v63, 0, v63
	v_mul_f32_e32 v62, v62, v62
	v_cvt_pk_bf16_f32 v60, v64, v60
	v_add_co_u32_e32 v64, vcc, s0, v132
	v_max_f32_e32 v52, v52, v52
	v_max_f32_e32 v53, v53, v53
	v_max_f32_e32 v54, v54, v54
	v_mul_f32_e32 v63, v63, v63
	v_cvt_pk_bf16_f32 v61, v61, v62
	v_cvt_pk_bf16_f32 v62, v70, v65
	v_addc_co_u32_e32 v65, vcc, 0, v133, vcc
	v_max_f32_e32 v52, 0, v52
	v_max_f32_e32 v53, 0, v53
	v_max_f32_e32 v54, 0, v54
	v_cvt_pk_bf16_f32 v63, v66, v63
	global_store_dwordx4 v[64:65], v[60:63], off
	v_max_f32_e32 v56, v56, v56
	v_max_f32_e32 v55, v55, v55
	v_mul_f32_e32 v60, v52, v52
	v_max_f32_e32 v52, v57, v57
	v_mul_f32_e32 v57, v53, v53
	v_max_f32_e32 v53, v58, v58
	v_mul_f32_e32 v58, v54, v54
	v_max_f32_e32 v54, v59, v59
	v_max_f32_e32 v52, 0, v52
	v_max_f32_e32 v53, 0, v53
	v_max_f32_e32 v54, 0, v54
	v_max_f32_e32 v56, 0, v56
	v_mul_f32_e32 v52, v52, v52
	v_mul_f32_e32 v53, v53, v53
	v_max_f32_e32 v55, 0, v55
	v_mul_f32_e32 v54, v54, v54
	v_max_f32_e32 v44, v44, v44
	v_mul_f32_e32 v56, v56, v56
	v_mul_f32_e32 v55, v55, v55
	v_cvt_pk_bf16_f32 v52, v56, v52
	v_cvt_pk_bf16_f32 v53, v53, v54
	v_cvt_pk_bf16_f32 v54, v60, v57
	v_max_f32_e32 v44, 0, v44
	v_max_f32_e32 v45, v45, v45
	v_max_f32_e32 v46, v46, v46
	v_cvt_pk_bf16_f32 v55, v58, v55
	global_store_dwordx4 v[68:69], v[52:55], off offset:256
	v_max_f32_e32 v48, v48, v48
	v_max_f32_e32 v45, 0, v45
	v_mul_f32_e32 v54, v44, v44
	v_max_f32_e32 v44, v49, v49
	v_max_f32_e32 v46, 0, v46
	s_mov_b64 s[0:1], 0x240000
	v_max_f32_e32 v48, 0, v48
	v_max_f32_e32 v44, 0, v44
	v_mul_f32_e32 v49, v45, v45
	v_max_f32_e32 v45, v50, v50
	v_mul_f32_e32 v50, v46, v46
	v_max_f32_e32 v46, v51, v51
	v_lshl_add_u64 v[52:53], v[132:133], 0, s[0:1]
	v_mul_f32_e32 v48, v48, v48
	v_mul_f32_e32 v44, v44, v44
	v_max_f32_e32 v45, 0, v45
	v_max_f32_e32 v46, 0, v46
	v_max_f32_e32 v47, v47, v47
	s_mov_b32 s0, 0x240000
	v_mul_f32_e32 v45, v45, v45
	v_max_f32_e32 v47, 0, v47
	v_mul_f32_e32 v46, v46, v46
	v_cvt_pk_bf16_f32 v44, v48, v44
; __device__ __forceinline__ unsigned cvt_pk_bf16(float lo, float hi) { unsigned r; asm volatile("v_cvt_pk_bf16_f32 %0, %1, %2" : "=v"(r) : "v"(lo), "v"(hi)); return r; }
;     __device__ __forceinline__ void operator()(const f32x4 (&acc)[2][2][4][2], const Unit& u, int wr, int wc, int fr, int fq) const {
;     ...
;             for (int m = 0; m < 4; ++m) { bf16_t* rowp = base + (size_t)(row0 + ai * HALF + m * 16) * ldc + col0;
; #pragma unroll
;                 for (int bj = 0; bj < 2; ++bj) { f32x4 v0 = acc[ai][bj][m][0], v1 = acc[ai][bj][m][1];
;                     if (ACT == 2) {
; #pragma unroll
;                         for (int e = 0; e < 4; ++e) { const float a = fmaxf(v0[e], 0.f), b = fmaxf(v1[e], 0.f); v0[e] = a * a; v1[e] = b * b; } }
;                     u32x4 w; w.x = cvt_pk_bf16(v0[0], v0[1]); w.y = cvt_pk_bf16(v0[2], v0[3]); w.z = cvt_pk_bf16(v1[0], v1[1]); w.w = cvt_pk_bf16(v1[2], v1[3]);
;                     *(u32x4*)(rowp + bj * HALF) = w; } }
; template <class Epi, class Sched, bool ALIGN_EPI = false, bool SP2 = false>
; __device__ __forceinline__ void gemm_phase(PG8_LAS unsigned char* lds, const Gemm g, const Sched& S, const Epi& E) {
;     ...
; #pragma unroll
;         for (int a = 0; a < 2; ++a)
; #pragma unroll
;             for (int b = 0; b < 2; ++b)
; #pragma unroll
;                 for (int m = 0; m < 4; ++m)
; #pragma unroll
;                     for (int n = 0; n < 2; ++n) { typedef double d2_t __attribute__((ext_vector_type(2))); d2_t z; double z0, z1;
;                         asm volatile("v_mov_b64 %0, 0" : "=v"(z0)); asm volatile("v_mov_b64 %0, 0" : "=v"(z1)); z.x = z0; z.y = z1; acc[a][b][m][n] = __builtin_bit_cast(f32x4, z); }
	v_add_co_u32_e32 v48, vcc, s0, v132
	v_max_f32_e32 v36, v36, v36
	v_max_f32_e32 v37, v37, v37
	v_max_f32_e32 v38, v38, v38
	v_mul_f32_e32 v47, v47, v47
	v_cvt_pk_bf16_f32 v45, v45, v46
	v_cvt_pk_bf16_f32 v46, v54, v49
	v_addc_co_u32_e32 v49, vcc, 0, v133, vcc
	v_max_f32_e32 v36, 0, v36
	v_max_f32_e32 v37, 0, v37
	v_max_f32_e32 v38, 0, v38
	v_cvt_pk_bf16_f32 v47, v50, v47
	global_store_dwordx4 v[48:49], v[44:47], off
	v_max_f32_e32 v40, v40, v40
	v_max_f32_e32 v39, v39, v39
	v_mul_f32_e32 v44, v36, v36
	v_max_f32_e32 v36, v41, v41
	v_mul_f32_e32 v41, v37, v37
	v_max_f32_e32 v37, v42, v42
	v_mul_f32_e32 v42, v38, v38
	v_max_f32_e32 v38, v43, v43
	v_max_f32_e32 v36, 0, v36
	v_max_f32_e32 v37, 0, v37
	v_max_f32_e32 v38, 0, v38
	v_max_f32_e32 v40, 0, v40
	v_mul_f32_e32 v36, v36, v36
	v_mul_f32_e32 v37, v37, v37
	v_max_f32_e32 v39, 0, v39
	v_mul_f32_e32 v38, v38, v38
	v_max_f32_e32 v28, v28, v28
	v_mul_f32_e32 v40, v40, v40
	v_mul_f32_e32 v39, v39, v39
	v_cvt_pk_bf16_f32 v36, v40, v36
	v_cvt_pk_bf16_f32 v37, v37, v38
	v_cvt_pk_bf16_f32 v38, v44, v41
	v_max_f32_e32 v28, 0, v28
	v_max_f32_e32 v29, v29, v29
	v_max_f32_e32 v30, v30, v30
	v_cvt_pk_bf16_f32 v39, v42, v39
	global_store_dwordx4 v[52:53], v[36:39], off offset:256
	v_max_f32_e32 v32, v32, v32
	v_max_f32_e32 v29, 0, v29
	v_mul_f32_e32 v38, v28, v28
	v_max_f32_e32 v28, v33, v33
	v_max_f32_e32 v30, 0, v30
	s_mov_b64 s[0:1], 0x280000
	v_max_f32_e32 v32, 0, v32
	v_max_f32_e32 v28, 0, v28
	v_mul_f32_e32 v33, v29, v29
	v_max_f32_e32 v29, v34, v34
	v_mul_f32_e32 v34, v30, v30
	v_max_f32_e32 v30, v35, v35
	v_lshl_add_u64 v[36:37], v[132:133], 0, s[0:1]
	v_mul_f32_e32 v32, v32, v32
	v_mul_f32_e32 v28, v28, v28
	v_max_f32_e32 v29, 0, v29
	v_max_f32_e32 v30, 0, v30
	v_max_f32_e32 v31, v31, v31
	s_mov_b32 s0, 0x280000
	v_mul_f32_e32 v29, v29, v29
	v_max_f32_e32 v31, 0, v31
	v_mul_f32_e32 v30, v30, v30
	v_cvt_pk_bf16_f32 v28, v32, v28
	v_add_co_u32_e32 v32, vcc, s0, v132
	v_max_f32_e32 v20, v20, v20
	v_max_f32_e32 v21, v21, v21
	v_max_f32_e32 v22, v22, v22
	v_mul_f32_e32 v31, v31, v31
	v_cvt_pk_bf16_f32 v29, v29, v30
	v_cvt_pk_bf16_f32 v30, v38, v33
	v_addc_co_u32_e32 v33, vcc, 0, v133, vcc
	v_max_f32_e32 v20, 0, v20
	v_max_f32_e32 v21, 0, v21
	v_max_f32_e32 v22, 0, v22
	v_cvt_pk_bf16_f32 v31, v34, v31
	global_store_dwordx4 v[32:33], v[28:31], off
	v_max_f32_e32 v24, v24, v24
	v_max_f32_e32 v23, v23, v23
	v_mul_f32_e32 v28, v20, v20
	v_max_f32_e32 v20, v25, v25
	v_mul_f32_e32 v25, v21, v21
	v_max_f32_e32 v21, v26, v26
	v_mul_f32_e32 v26, v22, v22
	v_max_f32_e32 v22, v27, v27
	v_max_f32_e32 v20, 0, v20
	v_max_f32_e32 v21, 0, v21
	v_max_f32_e32 v22, 0, v22
	v_max_f32_e32 v24, 0, v24
	v_mul_f32_e32 v20, v20, v20
	v_mul_f32_e32 v21, v21, v21
	v_max_f32_e32 v23, 0, v23
	v_mul_f32_e32 v22, v22, v22
	v_max_f32_e32 v12, v12, v12
	v_mul_f32_e32 v24, v24, v24
	v_mul_f32_e32 v23, v23, v23
	v_cvt_pk_bf16_f32 v20, v24, v20
	v_cvt_pk_bf16_f32 v21, v21, v22
	v_cvt_pk_bf16_f32 v22, v28, v25
	v_max_f32_e32 v12, 0, v12
	v_max_f32_e32 v13, v13, v13
	v_max_f32_e32 v14, v14, v14
	v_cvt_pk_bf16_f32 v23, v26, v23
	global_store_dwordx4 v[36:37], v[20:23], off offset:256
	v_max_f32_e32 v16, v16, v16
	v_max_f32_e32 v13, 0, v13
	v_mul_f32_e32 v22, v12, v12
	v_max_f32_e32 v12, v17, v17
	v_max_f32_e32 v14, 0, v14
	s_mov_b64 s[0:1], 0x2c0000
	v_max_f32_e32 v16, 0, v16
	v_max_f32_e32 v12, 0, v12
	v_mul_f32_e32 v17, v13, v13
	v_max_f32_e32 v13, v18, v18
	v_mul_f32_e32 v18, v14, v14
	v_max_f32_e32 v14, v19, v19
	v_lshl_add_u64 v[20:21], v[132:133], 0, s[0:1]
	v_mul_f32_e32 v16, v16, v16
	v_mul_f32_e32 v12, v12, v12
	v_max_f32_e32 v13, 0, v13
	v_max_f32_e32 v14, 0, v14
	v_max_f32_e32 v15, v15, v15
	s_mov_b32 s0, 0x2c0000
	v_mul_f32_e32 v13, v13, v13
	v_max_f32_e32 v15, 0, v15
	v_mul_f32_e32 v14, v14, v14
	v_cvt_pk_bf16_f32 v12, v16, v12
	v_add_co_u32_e32 v16, vcc, s0, v132
	v_max_f32_e32 v4, v4, v4
	v_max_f32_e32 v5, v5, v5
	v_max_f32_e32 v6, v6, v6
	v_mul_f32_e32 v15, v15, v15
	v_cvt_pk_bf16_f32 v13, v13, v14
	v_cvt_pk_bf16_f32 v14, v22, v17
	v_addc_co_u32_e32 v17, vcc, 0, v133, vcc
	v_max_f32_e32 v4, 0, v4
	v_max_f32_e32 v5, 0, v5
	v_max_f32_e32 v6, 0, v6
	v_cvt_pk_bf16_f32 v15, v18, v15
	global_store_dwordx4 v[16:17], v[12:15], off
	v_max_f32_e32 v7, v7, v7
	v_max_f32_e32 v8, v8, v8
	v_mul_f32_e32 v12, v4, v4
	v_max_f32_e32 v4, v9, v9
	v_mul_f32_e32 v9, v5, v5
	v_max_f32_e32 v5, v10, v10
	v_mul_f32_e32 v10, v6, v6
	v_max_f32_e32 v6, v11, v11
	v_max_f32_e32 v4, 0, v4
	v_max_f32_e32 v5, 0, v5
	v_max_f32_e32 v6, 0, v6
	v_max_f32_e32 v7, 0, v7
	v_max_f32_e32 v8, 0, v8
	v_mul_f32_e32 v4, v4, v4
	v_mul_f32_e32 v5, v5, v5
	v_mul_f32_e32 v6, v6, v6
	v_mul_f32_e32 v7, v7, v7
	v_mul_f32_e32 v8, v8, v8
	v_cvt_pk_bf16_f32 v4, v8, v4
	v_cvt_pk_bf16_f32 v5, v5, v6
	v_cvt_pk_bf16_f32 v6, v12, v9
	v_cvt_pk_bf16_f32 v7, v10, v7
	s_andn2_b64 vcc, exec, s[4:5]
	s_mov_b64 s[0:1], -1
	global_store_dwordx4 v[20:21], v[4:7], off offset:256
	s_cbranch_vccnz .LBB0_871
	s_andn2_b64 vcc, exec, s[2:3]
	s_cbranch_vccnz .LBB0_870
	s_barrier
	s_branch .LBB0_870

; #define PG8_STAGE(bufoff, soff, voff) do { _Pragma("unroll") for (int _i = 0; _i < 2; ++_i) \
;         __builtin_amdgcn_raw_ptr_buffer_load_lds(PG8_RS_##voff, (PG8_LAS void*)(lds + (bufoff) + ldsw + _i * 8192), 16, (voff)[_i], (soff), 0, 0); } while (0)
; #define PG8_LDA(dst, b, h) do { _Pragma("unroll") for (int m = 0; m < 4; ++m) _Pragma("unroll") for (int k = 0; k < 2; ++k) dst[m][k] = *(const PG8_LAS bf16x8*)(lds + PG8_SA(b, h) + aoff + m * 2048 + k * 1024); } while (0)
; #define PG8_LDB(dst, b, h) do { _Pragma("unroll") for (int n = 0; n < 2; ++n) _Pragma("unroll") for (int k = 0; k < 2; ++k) dst[n][k] = *(const PG8_LAS bf16x8*)(lds + PG8_SB(b, h) + boff + n * 2048 + k * 1024); } while (0)
; #define PG8_WAIT_V(n) asm volatile("s_waitcnt vmcnt(" #n ")" ::: "memory")
; #define PG8_WAIT_L(n) asm volatile("s_waitcnt lgkmcnt(" #n ")" ::: "memory")
; #define PG8_BAR __builtin_amdgcn_s_barrier()
; #define PG8_SCHED __builtin_amdgcn_sched_barrier(0)
; template <class Epi, class Sched, bool ALIGN_EPI = false, bool SP2 = false>
; __device__ __forceinline__ void gemm_phase(PG8_LAS unsigned char* lds, const Gemm g, const Sched& S, const Epi& E) {
;     ...
;         const bool has_next = S.next(ui + 1, nxt);
;         const unsigned nA = has_next ? (unsigned)nxt.pm * tstep + (unsigned)nxt.ko * 2u : cA, nB = has_next ? (unsigned)nxt.pn * tstep + (unsigned)nxt.ko * 2u : cB;
;         for (int t = 0; t < nt; t += 2) {
;             const bool last = (t == nt - 2);
;             const unsigned a1 = cA + (unsigned)(t + 1) * kstep;
;             const unsigned a2 = last ? nA : cA + (unsigned)(t + 2) * kstep, b2 = last ? nB : cB + (unsigned)(t + 2) * kstep;
;             const unsigned a3 = a2 + kstep, b3 = b2 + kstep;
;             if (last && has_next) S.a_ready(nxt);
;             if constexpr (SP2) {
;             PG8_LDB(B0, 0, 0); PG8_LDB(B1, 0, 1); PG8_SCHED; PG8_LDA(At, 0, 0); PG8_STAGE(PG8_SA(1, 1), a1 + hstep, voffA);
;             PG8_WAIT_V(8); PG8_WAIT_L(0); PG8_BAR; PG8_MMA(0, 0, At, B0); PG8_MMA(0, 1, At, B1); PG8_BAR; PG8_SCHED;
;             PG8_LDA(At, 0, 1); PG8_STAGE(PG8_SB(0, 0), b2, voffB); PG8_STAGE(PG8_SB(0, 1), b2 + hstep, voffB); PG8_STAGE(PG8_SA(0, 0), a2, voffA);
;             PG8_WAIT_V(8); PG8_WAIT_L(0); PG8_BAR; PG8_MMA(1, 0, At, B0); PG8_MMA(1, 1, At, B1); PG8_BAR; PG8_SCHED;
.LBB0_955:
	s_lshl_b32 s50, s49, 22
	s_and_b64 s[0:1], s[38:39], exec
	s_cselect_b32 s0, s50, s7
	s_lshl_b32 s51, s48, 22
	s_and_b64 s[52:53], s[38:39], exec
	s_cselect_b32 s1, s51, s6
	s_add_i32 s52, s7, 0x200080
	s_add_i32 s53, s6, 0x100
	s_mov_b32 s54, -2
	v_add_u32_e32 v144, 0x10000, v214
	v_add_u32_e32 v168, 0x14000, v214
	ds_read_b128 v[132:135], v144
	ds_read_b128 v[136:139], v144 offset:1024
	ds_read_b128 v[140:143], v144 offset:2048
	ds_read_b128 v[144:147], v144 offset:3072
	ds_read_b128 v[148:151], v168
	ds_read_b128 v[152:155], v168 offset:1024
	ds_read_b128 v[156:159], v168 offset:2048
	ds_read_b128 v[168:171], v168 offset:3072
	s_add_i32 s6, s52, 0xffe00080
	s_cmpk_eq_i32 s54, 0x7c
	s_cselect_b32 s57, s0, s6
	s_cselect_b32 s56, s1, s53
	s_or_b32 s55, s57, 0x80
	s_mov_b32 m0, s46
	ds_read_b128 v[172:175], v215
	ds_read_b128 v[176:179], v215 offset:1024
	ds_read_b128 v[180:183], v215 offset:2048
	ds_read_b128 v[184:187], v215 offset:3072
	ds_read_b128 v[188:191], v215 offset:4096
	ds_read_b128 v[192:195], v215 offset:5120
	ds_read_b128 v[196:199], v215 offset:6144
	ds_read_b128 v[218:221], v215 offset:7168
	buffer_load_dwordx4 v2, s[28:31], s52 offen lds
	s_mov_b32 m0, s47
	s_nop 0
	buffer_load_dwordx4 v208, s[28:31], s52 offen lds
	s_waitcnt vmcnt(8)
	s_waitcnt lgkmcnt(0)
	s_barrier
	s_setprio 1
	s_waitcnt lgkmcnt(7)
	v_mfma_f32_16x16x32_bf16 v[128:131], v[132:135], v[172:175], 0
	v_mfma_f32_16x16x32_bf16 v[124:127], v[140:143], v[172:175], 0
	s_waitcnt lgkmcnt(5)
	v_mfma_f32_16x16x32_bf16 v[112:115], v[132:135], v[180:183], 0
	v_mfma_f32_16x16x32_bf16 v[108:111], v[140:143], v[180:183], 0
	s_waitcnt lgkmcnt(3)
	v_mfma_f32_16x16x32_bf16 v[96:99], v[132:135], v[188:191], 0
	v_mfma_f32_16x16x32_bf16 v[92:95], v[140:143], v[188:191], 0
	s_waitcnt lgkmcnt(1)
	v_mfma_f32_16x16x32_bf16 v[80:83], v[132:135], v[196:199], 0
	v_mfma_f32_16x16x32_bf16 v[76:79], v[140:143], v[196:199], 0
	v_mfma_f32_16x16x32_bf16 v[128:131], v[136:139], v[176:179], v[128:131]
	v_mfma_f32_16x16x32_bf16 v[124:127], v[144:147], v[176:179], v[124:127]
	v_mfma_f32_16x16x32_bf16 v[112:115], v[136:139], v[184:187], v[112:115]
	v_mfma_f32_16x16x32_bf16 v[108:111], v[144:147], v[184:187], v[108:111]
	v_mfma_f32_16x16x32_bf16 v[96:99], v[136:139], v[192:195], v[96:99]
	v_mfma_f32_16x16x32_bf16 v[92:95], v[144:147], v[192:195], v[92:95]
	s_waitcnt lgkmcnt(0)
	v_mfma_f32_16x16x32_bf16 v[80:83], v[136:139], v[218:221], v[80:83]
	v_mfma_f32_16x16x32_bf16 v[76:79], v[144:147], v[218:221], v[76:79]
	s_setprio 0
	s_setprio 1
	v_mfma_f32_16x16x32_bf16 v[120:123], v[148:151], v[172:175], 0
	v_mfma_f32_16x16x32_bf16 v[116:119], v[156:159], v[172:175], 0
	v_mfma_f32_16x16x32_bf16 v[104:107], v[148:151], v[180:183], 0
	v_mfma_f32_16x16x32_bf16 v[100:103], v[156:159], v[180:183], 0
	v_mfma_f32_16x16x32_bf16 v[88:91], v[148:151], v[188:191], 0
	v_mfma_f32_16x16x32_bf16 v[84:87], v[156:159], v[188:191], 0
	v_mfma_f32_16x16x32_bf16 v[72:75], v[148:151], v[196:199], 0
	v_mfma_f32_16x16x32_bf16 v[68:71], v[156:159], v[196:199], 0
	v_mfma_f32_16x16x32_bf16 v[120:123], v[152:155], v[176:179], v[120:123]
	v_mfma_f32_16x16x32_bf16 v[116:119], v[168:171], v[176:179], v[116:119]
	v_mfma_f32_16x16x32_bf16 v[104:107], v[152:155], v[184:187], v[104:107]
	v_mfma_f32_16x16x32_bf16 v[100:103], v[168:171], v[184:187], v[100:103]
	v_mfma_f32_16x16x32_bf16 v[88:91], v[152:155], v[192:195], v[88:91]
	v_mfma_f32_16x16x32_bf16 v[84:87], v[168:171], v[192:195], v[84:87]
	v_mfma_f32_16x16x32_bf16 v[72:75], v[152:155], v[218:221], v[72:75]
	v_mfma_f32_16x16x32_bf16 v[68:71], v[168:171], v[218:221], v[68:71]
	s_setprio 0
	s_barrier
	s_mov_b32 m0, s22
	s_mov_b32 s6, s30
	s_mov_b32 s7, s31
	ds_read_b128 v[172:175], v215 offset:16384
	ds_read_b128 v[176:179], v215 offset:17408
	ds_read_b128 v[180:183], v215 offset:18432
	ds_read_b128 v[184:187], v215 offset:19456
	ds_read_b128 v[188:191], v215 offset:20480
	ds_read_b128 v[192:195], v215 offset:21504
	ds_read_b128 v[196:199], v215 offset:22528
	ds_read_b128 v[218:221], v215 offset:23552
	buffer_load_dwordx4 v207, s[4:7], s56 offen lds
	s_mov_b32 m0, s23
	s_add_i32 s58, s56, 0x200000
	buffer_load_dwordx4 v209, s[4:7], s56 offen lds
	s_mov_b32 m0, s24
	s_nop 0
	buffer_load_dwordx4 v207, s[4:7], s58 offen lds
	s_mov_b32 m0, s25
	s_nop 0
	buffer_load_dwordx4 v209, s[4:7], s58 offen lds
	s_mov_b32 m0, s21
	s_nop 0
	buffer_load_dwordx4 v2, s[28:31], s57 offen lds
	s_mov_b32 m0, s26
	s_nop 0
	buffer_load_dwordx4 v208, s[28:31], s57 offen lds
	s_waitcnt vmcnt(8)
	s_waitcnt lgkmcnt(0)
	s_barrier
; #define PG8_STAGE(bufoff, soff, voff) do { _Pragma("unroll") for (int _i = 0; _i < 2; ++_i) \
;         __builtin_amdgcn_raw_ptr_buffer_load_lds(PG8_RS_##voff, (PG8_LAS void*)(lds + (bufoff) + ldsw + _i * 8192), 16, (voff)[_i], (soff), 0, 0); } while (0)
; #define PG8_LDA(dst, b, h) do { _Pragma("unroll") for (int m = 0; m < 4; ++m) _Pragma("unroll") for (int k = 0; k < 2; ++k) dst[m][k] = *(const PG8_LAS bf16x8*)(lds + PG8_SA(b, h) + aoff + m * 2048 + k * 1024); } while (0)
; #define PG8_LDB(dst, b, h) do { _Pragma("unroll") for (int n = 0; n < 2; ++n) _Pragma("unroll") for (int k = 0; k < 2; ++k) dst[n][k] = *(const PG8_LAS bf16x8*)(lds + PG8_SB(b, h) + boff + n * 2048 + k * 1024); } while (0)
; #define PG8_MMA(ai, bj, At, Bt) do { __builtin_amdgcn_s_setprio(1); _Pragma("unroll") for (int m = 0; m < 4; ++m) _Pragma("unroll") for (int n = 0; n < 2; ++n) _Pragma("unroll") for (int k = 0; k < 2; ++k) \
;         acc[ai][bj][m][n] = __builtin_amdgcn_mfma_f32_16x16x32_bf16(Bt[n][k], At[m][k], acc[ai][bj][m][n], 0, 0, 0); __builtin_amdgcn_s_setprio(0); } while (0)
; #define PG8_WAIT_V(n) asm volatile("s_waitcnt vmcnt(" #n ")" ::: "memory")
; #define PG8_WAIT_L(n) asm volatile("s_waitcnt lgkmcnt(" #n ")" ::: "memory")
; #define PG8_BAR __builtin_amdgcn_s_barrier()
; #define PG8_SCHED __builtin_amdgcn_sched_barrier(0)
; template <class Epi, class Sched, bool ALIGN_EPI = false, bool SP2 = false>
; __device__ __forceinline__ void gemm_phase(PG8_LAS unsigned char* lds, const Gemm g, const Sched& S, const Epi& E) {
;     ...
;             PG8_WAIT_V(8); PG8_WAIT_L(0); PG8_BAR; PG8_MMA(1, 0, At, B0); PG8_MMA(1, 1, At, B1); PG8_BAR; PG8_SCHED;
;             PG8_LDB(B0, 1, 0); PG8_LDB(B1, 1, 1); PG8_SCHED; PG8_LDA(At, 1, 0); PG8_STAGE(PG8_SA(0, 1), a2 + hstep, voffA);
;             PG8_WAIT_V(8); PG8_WAIT_L(0); PG8_BAR; PG8_MMA(0, 0, At, B0); PG8_MMA(0, 1, At, B1); PG8_BAR; PG8_SCHED;
	s_setprio 1
	s_waitcnt lgkmcnt(7)
	v_mfma_f32_16x16x32_bf16 v[64:67], v[132:135], v[172:175], 0
	v_mfma_f32_16x16x32_bf16 v[60:63], v[140:143], v[172:175], 0
	s_waitcnt lgkmcnt(5)
	v_mfma_f32_16x16x32_bf16 v[48:51], v[132:135], v[180:183], 0
	v_mfma_f32_16x16x32_bf16 v[44:47], v[140:143], v[180:183], 0
	s_waitcnt lgkmcnt(3)
	v_mfma_f32_16x16x32_bf16 v[32:35], v[132:135], v[188:191], 0
	v_mfma_f32_16x16x32_bf16 v[28:31], v[140:143], v[188:191], 0
	s_waitcnt lgkmcnt(1)
	v_mfma_f32_16x16x32_bf16 v[16:19], v[132:135], v[196:199], 0
	v_mfma_f32_16x16x32_bf16 v[12:15], v[140:143], v[196:199], 0
	v_mfma_f32_16x16x32_bf16 v[64:67], v[136:139], v[176:179], v[64:67]
	v_mfma_f32_16x16x32_bf16 v[60:63], v[144:147], v[176:179], v[60:63]
	v_mfma_f32_16x16x32_bf16 v[48:51], v[136:139], v[184:187], v[48:51]
	v_mfma_f32_16x16x32_bf16 v[44:47], v[144:147], v[184:187], v[44:47]
	v_mfma_f32_16x16x32_bf16 v[32:35], v[136:139], v[192:195], v[32:35]
	v_mfma_f32_16x16x32_bf16 v[28:31], v[144:147], v[192:195], v[28:31]
	s_waitcnt lgkmcnt(0)
	v_mfma_f32_16x16x32_bf16 v[16:19], v[136:139], v[218:221], v[16:19]
	v_mfma_f32_16x16x32_bf16 v[12:15], v[144:147], v[218:221], v[12:15]
	s_setprio 0
	s_setprio 1
	v_mfma_f32_16x16x32_bf16 v[56:59], v[148:151], v[172:175], 0
	v_mfma_f32_16x16x32_bf16 v[52:55], v[156:159], v[172:175], 0
	v_mfma_f32_16x16x32_bf16 v[40:43], v[148:151], v[180:183], 0
	v_mfma_f32_16x16x32_bf16 v[36:39], v[156:159], v[180:183], 0
	v_mfma_f32_16x16x32_bf16 v[24:27], v[148:151], v[188:191], 0
	v_mfma_f32_16x16x32_bf16 v[20:23], v[156:159], v[188:191], 0
	v_mfma_f32_16x16x32_bf16 v[8:11], v[148:151], v[196:199], 0
	v_mfma_f32_16x16x32_bf16 v[4:7], v[156:159], v[196:199], 0
	v_mfma_f32_16x16x32_bf16 v[56:59], v[152:155], v[176:179], v[56:59]
	v_mfma_f32_16x16x32_bf16 v[52:55], v[168:171], v[176:179], v[52:55]
	v_mfma_f32_16x16x32_bf16 v[40:43], v[152:155], v[184:187], v[40:43]
	v_mfma_f32_16x16x32_bf16 v[36:39], v[168:171], v[184:187], v[36:39]
	v_mfma_f32_16x16x32_bf16 v[24:27], v[152:155], v[192:195], v[24:27]
	v_mfma_f32_16x16x32_bf16 v[20:23], v[168:171], v[192:195], v[20:23]
	v_mfma_f32_16x16x32_bf16 v[8:11], v[152:155], v[218:221], v[8:11]
	v_mfma_f32_16x16x32_bf16 v[4:7], v[168:171], v[218:221], v[4:7]
	s_setprio 0
	s_barrier
	v_add_u32_e32 v144, 0x18000, v214
	v_add_u32_e32 v168, 0x1c000, v214
	ds_read_b128 v[132:135], v144
	ds_read_b128 v[136:139], v144 offset:1024
	ds_read_b128 v[140:143], v144 offset:2048
	ds_read_b128 v[144:147], v144 offset:3072
	ds_read_b128 v[148:151], v168
	ds_read_b128 v[152:155], v168 offset:1024
	ds_read_b128 v[156:159], v168 offset:2048
	ds_read_b128 v[168:171], v168 offset:3072
	s_add_i32 s57, s57, 0x200000
	s_mov_b32 m0, s27
	ds_read_b128 v[172:175], v215 offset:32768
	ds_read_b128 v[176:179], v215 offset:33792
	ds_read_b128 v[180:183], v215 offset:34816
	ds_read_b128 v[184:187], v215 offset:35840
	ds_read_b128 v[188:191], v215 offset:36864
	ds_read_b128 v[192:195], v215 offset:37888
	ds_read_b128 v[196:199], v215 offset:38912
	ds_read_b128 v[218:221], v215 offset:39936
	buffer_load_dwordx4 v2, s[28:31], s57 offen lds
	s_mov_b32 m0, s33
	s_nop 0
	buffer_load_dwordx4 v208, s[28:31], s57 offen lds
	s_waitcnt vmcnt(8)
	s_waitcnt lgkmcnt(0)
	s_barrier
	s_setprio 1
	s_waitcnt lgkmcnt(7)
	v_mfma_f32_16x16x32_bf16 v[128:131], v[132:135], v[172:175], v[128:131]
	v_mfma_f32_16x16x32_bf16 v[124:127], v[140:143], v[172:175], v[124:127]
	s_waitcnt lgkmcnt(5)
	v_mfma_f32_16x16x32_bf16 v[112:115], v[132:135], v[180:183], v[112:115]
	v_mfma_f32_16x16x32_bf16 v[108:111], v[140:143], v[180:183], v[108:111]
	s_waitcnt lgkmcnt(3)
	v_mfma_f32_16x16x32_bf16 v[96:99], v[132:135], v[188:191], v[96:99]
	v_mfma_f32_16x16x32_bf16 v[92:95], v[140:143], v[188:191], v[92:95]
	s_waitcnt lgkmcnt(1)
	v_mfma_f32_16x16x32_bf16 v[80:83], v[132:135], v[196:199], v[80:83]
	v_mfma_f32_16x16x32_bf16 v[76:79], v[140:143], v[196:199], v[76:79]
	v_mfma_f32_16x16x32_bf16 v[128:131], v[136:139], v[176:179], v[128:131]
	v_mfma_f32_16x16x32_bf16 v[124:127], v[144:147], v[176:179], v[124:127]
	v_mfma_f32_16x16x32_bf16 v[112:115], v[136:139], v[184:187], v[112:115]
	v_mfma_f32_16x16x32_bf16 v[108:111], v[144:147], v[184:187], v[108:111]
	v_mfma_f32_16x16x32_bf16 v[96:99], v[136:139], v[192:195], v[96:99]
	v_mfma_f32_16x16x32_bf16 v[92:95], v[144:147], v[192:195], v[92:95]
	s_waitcnt lgkmcnt(0)
	v_mfma_f32_16x16x32_bf16 v[80:83], v[136:139], v[218:221], v[80:83]
	v_mfma_f32_16x16x32_bf16 v[76:79], v[144:147], v[218:221], v[76:79]
	s_setprio 0
	s_setprio 1
	v_mfma_f32_16x16x32_bf16 v[120:123], v[148:151], v[172:175], v[120:123]
	v_mfma_f32_16x16x32_bf16 v[116:119], v[156:159], v[172:175], v[116:119]
	v_mfma_f32_16x16x32_bf16 v[104:107], v[148:151], v[180:183], v[104:107]
	v_mfma_f32_16x16x32_bf16 v[100:103], v[156:159], v[180:183], v[100:103]
	v_mfma_f32_16x16x32_bf16 v[88:91], v[148:151], v[188:191], v[88:91]
	v_mfma_f32_16x16x32_bf16 v[84:87], v[156:159], v[188:191], v[84:87]
	v_mfma_f32_16x16x32_bf16 v[72:75], v[148:151], v[196:199], v[72:75]
	v_mfma_f32_16x16x32_bf16 v[68:71], v[156:159], v[196:199], v[68:71]
	v_mfma_f32_16x16x32_bf16 v[120:123], v[152:155], v[176:179], v[120:123]
	v_mfma_f32_16x16x32_bf16 v[116:119], v[168:171], v[176:179], v[116:119]
	v_mfma_f32_16x16x32_bf16 v[104:107], v[152:155], v[184:187], v[104:107]
	v_mfma_f32_16x16x32_bf16 v[100:103], v[168:171], v[184:187], v[100:103]
	v_mfma_f32_16x16x32_bf16 v[88:91], v[152:155], v[192:195], v[88:91]
	v_mfma_f32_16x16x32_bf16 v[84:87], v[168:171], v[192:195], v[84:87]
	v_mfma_f32_16x16x32_bf16 v[72:75], v[152:155], v[218:221], v[72:75]
	v_mfma_f32_16x16x32_bf16 v[68:71], v[168:171], v[218:221], v[68:71]
	s_setprio 0
	s_barrier
; #define PG8_STAGE(bufoff, soff, voff) do { _Pragma("unroll") for (int _i = 0; _i < 2; ++_i) \
;         __builtin_amdgcn_raw_ptr_buffer_load_lds(PG8_RS_##voff, (PG8_LAS void*)(lds + (bufoff) + ldsw + _i * 8192), 16, (voff)[_i], (soff), 0, 0); } while (0)
; #define PG8_LDA(dst, b, h) do { _Pragma("unroll") for (int m = 0; m < 4; ++m) _Pragma("unroll") for (int k = 0; k < 2; ++k) dst[m][k] = *(const PG8_LAS bf16x8*)(lds + PG8_SA(b, h) + aoff + m * 2048 + k * 1024); } while (0)
; #define PG8_MMA(ai, bj, At, Bt) do { __builtin_amdgcn_s_setprio(1); _Pragma("unroll") for (int m = 0; m < 4; ++m) _Pragma("unroll") for (int n = 0; n < 2; ++n) _Pragma("unroll") for (int k = 0; k < 2; ++k) \
;         acc[ai][bj][m][n] = __builtin_amdgcn_mfma_f32_16x16x32_bf16(Bt[n][k], At[m][k], acc[ai][bj][m][n], 0, 0, 0); __builtin_amdgcn_s_setprio(0); } while (0)
; #define PG8_WAIT_V(n) asm volatile("s_waitcnt vmcnt(" #n ")" ::: "memory")
; #define PG8_WAIT_L(n) asm volatile("s_waitcnt lgkmcnt(" #n ")" ::: "memory")
; #define PG8_BAR __builtin_amdgcn_s_barrier()
; #define PG8_SCHED __builtin_amdgcn_sched_barrier(0)
; template <class Epi, class Sched, bool ALIGN_EPI = false, bool SP2 = false>
; __device__ __forceinline__ void gemm_phase(PG8_LAS unsigned char* lds, const Gemm g, const Sched& S, const Epi& E) {
;     ...
;             PG8_LDA(At, 1, 1); PG8_STAGE(PG8_SB(1, 0), b3, voffB); PG8_STAGE(PG8_SB(1, 1), b3 + hstep, voffB); PG8_STAGE(PG8_SA(1, 0), a3, voffA);
;             PG8_WAIT_V(8); PG8_WAIT_L(0); PG8_BAR; PG8_MMA(1, 0, At, B0); PG8_MMA(1, 1, At, B1); PG8_BAR; PG8_SCHED;
	s_mov_b32 m0, s36
	s_or_b32 s57, s56, 0x80
	ds_read_b128 v[172:175], v215 offset:49152
	ds_read_b128 v[176:179], v215 offset:50176
	ds_read_b128 v[180:183], v215 offset:51200
	ds_read_b128 v[184:187], v215 offset:52224
	ds_read_b128 v[188:191], v215 offset:53248
	ds_read_b128 v[192:195], v215 offset:54272
	ds_read_b128 v[196:199], v215 offset:55296
	ds_read_b128 v[218:221], v215 offset:56320
	buffer_load_dwordx4 v207, s[4:7], s57 offen lds
	s_mov_b32 m0, s37
	s_add_i32 s56, s56, 0x200080
	buffer_load_dwordx4 v209, s[4:7], s57 offen lds
	s_mov_b32 m0, s44
	s_nop 0
	buffer_load_dwordx4 v207, s[4:7], s56 offen lds
	s_mov_b32 m0, s45
	s_nop 0
	buffer_load_dwordx4 v209, s[4:7], s56 offen lds
	s_mov_b32 m0, s42
	s_nop 0
	buffer_load_dwordx4 v2, s[28:31], s55 offen lds
	s_mov_b32 m0, s43
	s_nop 0
	buffer_load_dwordx4 v208, s[28:31], s55 offen lds
	s_waitcnt vmcnt(8)
	s_waitcnt lgkmcnt(0)
	s_barrier
	s_setprio 1
	s_waitcnt lgkmcnt(7)
	v_mfma_f32_16x16x32_bf16 v[64:67], v[132:135], v[172:175], v[64:67]
	v_mfma_f32_16x16x32_bf16 v[60:63], v[140:143], v[172:175], v[60:63]
	s_waitcnt lgkmcnt(5)
	v_mfma_f32_16x16x32_bf16 v[48:51], v[132:135], v[180:183], v[48:51]
	v_mfma_f32_16x16x32_bf16 v[44:47], v[140:143], v[180:183], v[44:47]
	s_waitcnt lgkmcnt(3)
	v_mfma_f32_16x16x32_bf16 v[32:35], v[132:135], v[188:191], v[32:35]
	v_mfma_f32_16x16x32_bf16 v[28:31], v[140:143], v[188:191], v[28:31]
	s_waitcnt lgkmcnt(1)
	v_mfma_f32_16x16x32_bf16 v[16:19], v[132:135], v[196:199], v[16:19]
	v_mfma_f32_16x16x32_bf16 v[12:15], v[140:143], v[196:199], v[12:15]
	v_mfma_f32_16x16x32_bf16 v[64:67], v[136:139], v[176:179], v[64:67]
	v_mfma_f32_16x16x32_bf16 v[60:63], v[144:147], v[176:179], v[60:63]
	v_mfma_f32_16x16x32_bf16 v[48:51], v[136:139], v[184:187], v[48:51]
	v_mfma_f32_16x16x32_bf16 v[44:47], v[144:147], v[184:187], v[44:47]
	v_mfma_f32_16x16x32_bf16 v[32:35], v[136:139], v[192:195], v[32:35]
	v_mfma_f32_16x16x32_bf16 v[28:31], v[144:147], v[192:195], v[28:31]
	s_waitcnt lgkmcnt(0)
	v_mfma_f32_16x16x32_bf16 v[16:19], v[136:139], v[218:221], v[16:19]
	v_mfma_f32_16x16x32_bf16 v[12:15], v[144:147], v[218:221], v[12:15]
	s_setprio 0
	s_setprio 1
	v_mfma_f32_16x16x32_bf16 v[56:59], v[148:151], v[172:175], v[56:59]
	v_mfma_f32_16x16x32_bf16 v[52:55], v[156:159], v[172:175], v[52:55]
	v_mfma_f32_16x16x32_bf16 v[40:43], v[148:151], v[180:183], v[40:43]
	v_mfma_f32_16x16x32_bf16 v[36:39], v[156:159], v[180:183], v[36:39]
	v_mfma_f32_16x16x32_bf16 v[24:27], v[148:151], v[188:191], v[24:27]
	v_mfma_f32_16x16x32_bf16 v[20:23], v[156:159], v[188:191], v[20:23]
	v_mfma_f32_16x16x32_bf16 v[8:11], v[148:151], v[196:199], v[8:11]
	v_mfma_f32_16x16x32_bf16 v[4:7], v[156:159], v[196:199], v[4:7]
	v_mfma_f32_16x16x32_bf16 v[56:59], v[152:155], v[176:179], v[56:59]
	v_mfma_f32_16x16x32_bf16 v[52:55], v[168:171], v[176:179], v[52:55]
	v_mfma_f32_16x16x32_bf16 v[40:43], v[152:155], v[184:187], v[40:43]
	v_mfma_f32_16x16x32_bf16 v[36:39], v[168:171], v[184:187], v[36:39]
	v_mfma_f32_16x16x32_bf16 v[24:27], v[152:155], v[192:195], v[24:27]
	v_mfma_f32_16x16x32_bf16 v[20:23], v[168:171], v[192:195], v[20:23]
	v_mfma_f32_16x16x32_bf16 v[8:11], v[152:155], v[218:221], v[8:11]
	v_mfma_f32_16x16x32_bf16 v[4:7], v[168:171], v[218:221], v[4:7]
	s_setprio 0
	s_barrier
	s_add_i32 s54, s54, 2
	s_addk_i32 s52, 0x100
	s_addk_i32 s53, 0x100
	s_cmpk_gt_u32 s54, 0x7d

;     __device__ __forceinline__ void operator()(const f32x4 (&acc)[2][2][4][2], const Unit& u, int wr, int wc, int fr, int fq) const {
;     ...
;             for (int m = 0; m < 4; ++m) { float q = sq[ai][m]; q = fq_sum(q); sq[ai][m] = q; }
;             const float v = fq == 0 ? sq[ai][0] : (fq == 1 ? sq[ai][1] : (fq == 2 ? sq[ai][2] : sq[ai][3]));
;             atomicAdd(ssout + (u.pm * BM + wr * 64 + ai * HALF + fq * 16 + fr), (unsigned long long)(v * 16777216.f));
; template <class Epi, class Sched, bool ALIGN_EPI = false, bool SP2 = false>
; __device__ __forceinline__ void gemm_phase(PG8_LAS unsigned char* lds, const Gemm g, const Sched& S, const Epi& E) {
;     ...
; #pragma unroll
;         for (int a = 0; a < 2; ++a)
; #pragma unroll
;             for (int b = 0; b < 2; ++b)
; #pragma unroll
;                 for (int m = 0; m < 4; ++m)
; #pragma unroll
;                     for (int n = 0; n < 2; ++n) { typedef double d2_t __attribute__((ext_vector_type(2))); d2_t z; double z0, z1;
;                         asm volatile("v_mov_b64 %0, 0" : "=v"(z0)); asm volatile("v_mov_b64 %0, 0" : "=v"(z1)); z.x = z0; z.y = z1; acc[a][b][m][n] = __builtin_bit_cast(f32x4, z); }
.LBB0_1027:
	s_or_b64 exec, exec, s[0:1]
	v_add_f32_e32 v4, v8, v9
	v_mul_f32_e32 v4, 0x4b800000, v4
	v_trunc_f32_e32 v4, v4
	v_mul_f32_e32 v5, 0x2f800000, v4
	v_floor_f32_e32 v5, v5
	v_fmac_f32_e32 v4, 0xcf800000, v5
	v_cvt_u32_f32_e32 v4, v4
	v_cvt_u32_f32_e32 v5, v5
	v_add_u32_e32 v6, 0x80, v100
	v_ashrrev_i32_e32 v7, 31, v6
	v_lshl_add_u64 v[6:7], v[6:7], 3, s[12:13]
	global_atomic_add_x2 v[6:7], v[4:5], off
	s_andn2_b64 vcc, exec, s[38:39]
	s_mov_b64 s[0:1], -1
	s_cbranch_vccnz .LBB0_948
	s_andn2_b64 vcc, exec, s[2:3]
	s_cbranch_vccnz .LBB0_947
	s_barrier
	s_branch .LBB0_947
